# diff-attn: LDS ops spread over MFMA gaps; K and V tiles staged by LDS-DMA (global_load_lds) into padded images, V^T global token order pre-permuted by the ProjGate epilogue so 16B chunks are LDS-conti
# speedup vs baseline: 1.0932x; 1.0140x over previous
; template <int MODE, bool FROZEN = false>
; __device__ __forceinline__ bool attn_unit(LAS unsigned char* lds, const Params& p, int l, int ua, int ub) {
;     ...
;         const float* lq = p.diff_lambda + (size_t)l * 256;
;         const float s1 = wave_sum(lq[lane] * lq[64 + lane]), s2 = wave_sum(lq[128 + lane] * lq[192 + lane]);
;         lam_init = 0.8f - 0.6f * expf(-0.3f * (float)l);
;         lam = expf(s1) - expf(s2) + lam_init;
;     } else {
;         const int g = ua, qb = ub, hq = g * 4 + (wid >> 1); qtok0 = qb * 64 + (wid & 1) * 32; lut_sel = wid >> 1;
;         qcol = 3072 + hq * 64; kcol = 3584 + g * 64; vcol = 1024 + g * 64; ocol = hq * 64;
;         const int tlo = max(qb - 2, 0), thi = min(qb + 2, S / 64 - 1); kt0 = tlo * 64; NT = thi - tlo + 1; wt_hi = NT;
;         for (int i = tid; i < 4 * 449; i += 512) { const int hh = i / 449, rel = i % 449 - 224; lut[i] = (rel >= -128 && rel <= 128) ? p.rel_bias[t5_bucket(rel) * 12 + 4 + g * 4 + hh] * LOG2E : NEGBIG; }
;         m_run = p.gqa_sink[l * 8 + hq] * LOG2E; l_run = (hi == 0) ? 1.0f : 0.0f;
;     }
;     bf16x8 qf[4];
;     { const bf16_t* qp = proj + (size_t)(qtok0 + r32) * NPROJ + qcol + 8 * hi;
; #pragma unroll
;       for (int d0 = 0; d0 < 4; ++d0) qf[d0] = *(const bf16x8*)(qp + 16 * d0); }
;     f32x16 o[NB];
; #pragma unroll
;     for (int nb = 0; nb < NB; ++nb)
; #pragma unroll
;         for (int r = 0; r < 16; ++r) o[nb][r] = 0.f;
;     u32x4 kr[NKC], vr[NVC];
;     unsigned ksrc[NKC], vsrc[NVC]; int kdst[NKC], vdst[NVC];
;     const bf16_t* kvbase = proj + (size_t)kt0 * NPROJ;
; #pragma unroll
;     for (int i = 0; i < NKC; ++i) { const int cid = tid + 512 * i, row = cid / KCH, ch = cid % KCH; ksrc[i] = (unsigned)(row * NPROJ + kcol + ch * 8); kdst[i] = OFF_K + row * KPB + ch * 16; }
; #pragma unroll
;     for (int i = 0; i < NVC; ++i) { const int cid = tid + 512 * i, row = cid >> 3, ch = cid & 7; vsrc[i] = (unsigned)((vcol + row) * S + ch * 8); vdst[i] = OFF_V + row * VTP + (ch >> 1) * 32 + (ch & 1) * 8; }
;     const bf16_t* vtbase = vtg + kt0;
;     {
;         u32x4 k1[NKC];
; #pragma unroll
;         for (int i = 0; i < NKC; ++i) { kr[i] = *(const u32x4*)(kvbase + ksrc[i]); k1[i] = *(const u32x4*)(kvbase + (size_t)64 * NPROJ + ksrc[i]); }
; #pragma unroll
;         for (int i = 0; i < NVC; ++i) vr[i] = *(const u32x4*)(vtbase + vsrc[i]);
; #pragma unroll
.LBB0_110:
	s_or_b64 exec, exec, s[4:5]
	v_and_b32_e32 v164, 63, v148
	v_lshlrev_b32_e32 v0, 2, v164
	global_load_dword v1, v0, s[46:47]
	global_load_dword v2, v0, s[46:47] offset:256
	v_xor_b32_e32 v4, 1, v233
	v_cmp_lt_i32_e32 vcc, v4, v234
	s_lshl_b32 s0, s52, 6
	s_and_b32 s0, s0, 64
	v_cndmask_b32_e32 v4, v233, v4, vcc
	v_lshlrev_b32_e32 v4, 2, v4
	s_ashr_i32 s57, s52, 3
	s_ashr_i32 s56, s54, 6
	s_add_i32 s0, s0, s57
	s_lshl_b32 s1, s56, 5
	s_lshl_b32 s0, s0, 7
	s_and_b32 s58, s1, 0x60
	v_and_b32_e32 v52, 31, v148
	s_or_b32 s59, s58, s0
	s_lshl_b32 s55, s8, 7
	s_ashr_i32 s8, s54, 2
	v_or_b32_e32 v150, s59, v52
	s_movk_i32 s12, 0x1e00
	s_andn2_b32 s8, s8, 63
	s_or_b32 s11, s55, 0x800
	s_or_b32 s10, s55, 0x200
	v_bfe_u32 v149, v148, 5, 1
	v_lshlrev_b32_e32 v32, 4, v149
	v_mov_b32_e32 v33, v197
	v_ashrrev_i32_e32 v25, 3, v148
	v_mov_b32_e32 v153, v197
	v_mov_b32_e32 v155, v197
	v_mov_b32_e32 v157, v197
	v_readlane_b32 s61, v254, 45
	s_mov_b32 s0, 0xc2ce8ed0
	s_mov_b32 s4, 0x42b17218
	v_ashrrev_i32_e32 v151, 31, v150
	s_mov_b32 s14, s9
	s_mov_b32 s15, s9
	s_mov_b32 s16, s9
	s_mov_b32 s17, s9
	s_mov_b32 s18, s9
	s_mov_b32 s19, s9
	s_mov_b32 s20, s9
	s_mov_b32 s21, s9
	s_mov_b32 s22, s9
	s_mov_b32 s23, s9
	s_waitcnt vmcnt(0)
	v_mul_f32_e32 v3, v1, v2
	ds_bpermute_b32 v3, v4, v3
	s_waitcnt lgkmcnt(0)
	v_fmac_f32_e32 v3, v1, v2
	v_xor_b32_e32 v1, 2, v233
	v_cmp_lt_i32_e32 vcc, v1, v234
	s_nop 1
	v_cndmask_b32_e32 v1, v233, v1, vcc
	v_lshlrev_b32_e32 v1, 2, v1
	ds_bpermute_b32 v2, v1, v3
	s_waitcnt lgkmcnt(0)
	v_add_f32_e32 v2, v3, v2
	v_xor_b32_e32 v3, 4, v233
	v_cmp_lt_i32_e32 vcc, v3, v234
	s_nop 1
	v_cndmask_b32_e32 v3, v233, v3, vcc
	v_lshlrev_b32_e32 v3, 2, v3
	ds_bpermute_b32 v5, v3, v2
	s_waitcnt lgkmcnt(0)
	v_add_f32_e32 v2, v2, v5
	v_xor_b32_e32 v5, 8, v233
	v_cmp_lt_i32_e32 vcc, v5, v234
	s_nop 1
	v_cndmask_b32_e32 v5, v233, v5, vcc
	v_lshlrev_b32_e32 v5, 2, v5
	ds_bpermute_b32 v6, v5, v2
	s_waitcnt lgkmcnt(0)
	v_add_f32_e32 v2, v2, v6
	v_xor_b32_e32 v6, 16, v233
	v_cmp_lt_i32_e32 vcc, v6, v234
	s_nop 1
	v_cndmask_b32_e32 v6, v233, v6, vcc
	v_lshlrev_b32_e32 v6, 2, v6
	ds_bpermute_b32 v7, v6, v2
	s_waitcnt lgkmcnt(0)
	v_add_f32_e32 v2, v2, v7
	v_xor_b32_e32 v7, 32, v233
	v_cmp_lt_i32_e32 vcc, v7, v234
	s_nop 1
	v_cndmask_b32_e32 v7, v233, v7, vcc
	v_lshlrev_b32_e32 v7, 2, v7
	ds_bpermute_b32 v8, v7, v2
	s_waitcnt lgkmcnt(0)
	v_add_f32_e32 v53, v2, v8
	global_load_dword v2, v0, s[46:47] offset:512
	s_nop 0
	global_load_dword v0, v0, s[46:47] offset:768
	v_cmp_ngt_f32_e64 s[40:41], s0, v53
	v_cmp_nlt_f32_e64 s[42:43], s4, v53
	s_waitcnt vmcnt(0)
	v_mul_f32_e32 v8, v2, v0
	ds_bpermute_b32 v4, v4, v8
	s_waitcnt lgkmcnt(0)
	v_fmac_f32_e32 v4, v2, v0
	ds_bpermute_b32 v0, v1, v4
	s_waitcnt lgkmcnt(0)
	v_add_f32_e32 v0, v4, v0
	ds_bpermute_b32 v1, v3, v0
	s_waitcnt lgkmcnt(0)
	v_add_f32_e32 v0, v0, v1
	ds_bpermute_b32 v1, v5, v0
	s_waitcnt lgkmcnt(0)
	v_add_f32_e32 v0, v0, v1
	ds_bpermute_b32 v1, v6, v0
	s_waitcnt lgkmcnt(0)
	v_add_f32_e32 v0, v0, v1
	ds_bpermute_b32 v1, v7, v0
	s_waitcnt lgkmcnt(0)
	v_add_f32_e32 v54, v0, v1
	v_mov_b64_e32 v[0:1], s[34:35]
	v_mad_i64_i32 v[0:1], s[12:13], v150, s12, v[0:1]
	s_ashr_i32 s13, s8, 31
	s_add_u32 s12, s55, s8
	s_addc_u32 s13, 0, s13
	v_lshl_add_u64 v[0:1], s[12:13], 1, v[0:1]
	v_lshl_add_u64 v[0:1], v[0:1], 0, v[32:33]
	global_load_dwordx4 v[116:119], v[0:1], off offset:3072
	global_load_dwordx4 v[120:123], v[0:1], off offset:3104
	global_load_dwordx4 v[124:127], v[0:1], off offset:3136
	global_load_dwordx4 v[128:131], v[0:1], off offset:3168
	v_ashrrev_i32_e32 v0, 31, v148
	v_lshrrev_b32_e32 v0, 28, v0
	v_add_u32_e32 v0, v148, v0
	v_ashrrev_i32_e32 v1, 4, v0
	v_and_b32_e32 v0, -16, v0
	s_movk_i32 s12, 0xf00
	s_movk_i32 s13, 0x110
	v_sub_u32_e32 v0, v148, v0
	v_mul_lo_u32 v2, v1, s12
	v_mul_lo_u32 v1, v1, s13
	v_lshlrev_b32_e32 v3, 3, v0
	v_lshl_add_u32 v33, v0, 4, v1
	v_add_u32_e32 v0, 0x200, v148
	v_ashrrev_i32_e32 v1, 31, v0
	v_lshrrev_b32_e32 v1, 28, v1
	v_add_u32_e32 v1, v0, v1
	v_add3_u32 v196, v2, s11, v3
	v_ashrrev_i32_e32 v2, 4, v1
	v_and_b32_e32 v1, -16, v1
	v_sub_u32_e32 v1, v0, v1
	v_mul_lo_u32 v3, v2, s12
	v_lshlrev_b32_e32 v4, 3, v1
	v_add3_u32 v152, v3, s11, v4
	v_mul_lo_u32 v2, v2, s13
	v_lshlrev_b32_e32 v3, 4, v148
	v_lshl_add_u32 v165, v1, 4, v2
	v_lshlrev_b32_e32 v1, 3, v148
	v_and_b32_e32 v3, 0x60, v3
	v_ashrrev_i32_e32 v38, 3, v0
	v_and_b32_e32 v2, 56, v1
	v_lshlrev_b32_e32 v24, 4, v148
	v_and_b32_e32 v24, 0x70, v24
	v_add_u32_e32 v1, s10, v25
	v_add_u32_e32 v0, s10, v38
	v_lshlrev_b64 v[26:27], 1, v[196:197]
	v_readlane_b32 s10, v252, 27
	v_lshl_or_b32 v154, v1, 14, v2
	v_lshl_or_b32 v156, v0, 14, v2
	v_lshl_add_u64 v[0:1], s[34:35], 0, v[26:27]
	v_readlane_b32 s11, v252, 28
	v_lshlrev_b64 v[28:29], 1, v[152:153]
	global_load_dwordx4 v[0:3], v[0:1], off
	v_lshl_add_u64 v[4:5], s[10:11], 0, v[26:27]
	v_lshl_add_u64 v[8:9], s[34:35], 0, v[28:29]
	global_load_dwordx4 v[4:7], v[4:5], off
	v_lshl_add_u64 v[12:13], s[10:11], 0, v[28:29]
	global_load_dwordx4 v[8:11], v[8:9], off
	v_lshlrev_b64 v[30:31], 1, v[154:155]
	global_load_dwordx4 v[20:23], v[12:13], off
	v_lshl_add_u64 v[12:13], s[6:7], 0, v[30:31]
	global_load_dwordx4 v[12:15], v[12:13], off
	v_lshlrev_b64 v[36:37], 1, v[156:157]
	v_lshl_add_u64 v[16:17], s[6:7], 0, v[36:37]
	global_load_dwordx4 v[16:19], v[16:17], off
	v_add_u32_e32 v39, 0, v33
	s_movk_i32 s12, 0x90
	v_mad_u64_u32 v[158:159], s[10:11], v25, s12, v[24:25]
	v_mad_u64_u32 v[160:161], s[10:11], v38, s12, v[24:25]
	v_readlane_b32 s10, v252, 29
	v_readlane_b32 s11, v252, 30
	s_add_i32 s60, s59, 0xffffff41
	s_cmp_lt_u32 s60, 0xfffffea3
	v_cmp_ngt_f32_e64 s[0:1], s0, v54
	v_cmp_nlt_f32_e64 s[4:5], s4, v54
	s_mov_b32 s12, s9
	s_mov_b32 s13, s9
	s_cselect_b64 s[44:45], -1, 0
	s_cmp_gt_u32 s60, 0xfffffea2
	s_waitcnt vmcnt(5)
	ds_write_b128 v39, v[0:3]
	s_waitcnt vmcnt(4)
	ds_write_b128 v39, v[4:7] offset:17408
	v_add_u32_e32 v0, 0, v165
	s_waitcnt vmcnt(3)
	ds_write_b128 v0, v[8:11]
	s_waitcnt vmcnt(2)
	ds_write_b128 v0, v[20:23] offset:17408
	v_add_u32_e32 v0, 0, v158
	v_add_u32_e32 v0, 0x8800, v0
	s_waitcnt vmcnt(1)
	ds_write_b128 v0, v[12:15]
	v_add_u32_e32 v0, 0, v160
	v_add_u32_e32 v0, 0x8800, v0
	s_waitcnt vmcnt(0)
	ds_write_b128 v0, v[16:19]
	v_lshl_add_u64 v[0:1], s[10:11], 0, v[26:27]
	global_load_dwordx4 v[132:135], v[0:1], off
	v_lshl_add_u64 v[0:1], s[10:11], 0, v[28:29]
	v_readlane_b32 s10, v252, 31
	v_readlane_b32 s11, v252, 32
	global_load_dwordx4 v[140:143], v[0:1], off
	s_nop 0
	v_lshl_add_u64 v[0:1], s[10:11], 0, v[30:31]
	global_load_dwordx4 v[136:139], v[0:1], off
	v_lshl_add_u64 v[0:1], s[10:11], 0, v[36:37]
	global_load_dwordx4 v[144:147], v[0:1], off
	v_lshl_or_b32 v0, s8, 1, v32
	v_readlane_b32 s8, v254, 46
	s_waitcnt lgkmcnt(0)
	s_barrier
; #define ATT_MAX3(dst) do { float tm_ = max3f(sB0[0], sB1[0], sB0[1]), tn_ = max3f(sB1[1], sB0[2], sB1[2]); \
;         _Pragma("unroll") for (int r = 3; r < 15; r += 2) { tm_ = max3f(tm_, sB0[r], sB1[r]); tn_ = max3f(tn_, sB0[r + 1], sB1[r + 1]); } \
;         tm_ = max3f(tm_, sB0[15], sB1[15]); dst = max3f(tm_, tn_, tn_); } while (0)
; template <int MODE, bool FROZEN = false>
; __device__ __forceinline__ bool attn_unit(LAS unsigned char* lds, const Params& p, int l, int ua, int ub) {
;     ...
;     float cb_pos = 0.f, cb_neg = 0.f;
;     if constexpr (MODE == 1) { cb_pos = lut[448]; cb_neg = lut[0]; }
;     ATT_QK(0);
;     if constexpr (FROZEN) m_run = cb_neg;
;     { float tm0 = 0.f; if constexpr (!FROZEN) ATT_MAX3(tm0); ATT_BIAS(0, tm0); ATT_UPD(tm0); }
	v_mov_b32_e32 v1, s8
	ds_read_b32 v159, v1
	v_mov_b32_e32 v1, s61
	ds_read_b32 v161, v1
	v_mul_u32_u24_e32 v1, 0x110, v52
	v_add3_u32 v166, 0, v0, v1
	ds_read_b128 v[0:3], v166 offset:8704
	ds_read_b128 v[4:7], v166
	ds_read_b128 v[36:39], v166 offset:32
	ds_read_b128 v[40:43], v166 offset:8736
	s_waitcnt lgkmcnt(2)
	v_mfma_f32_32x32x16_bf16 v[16:31], v[4:7], v[116:119], 0
	s_mov_b32 s8, s9
	s_mov_b32 s10, s9
	s_mov_b32 s11, s9
	v_mfma_f32_32x32x16_bf16 v[0:15], v[0:3], v[116:119], 0
	s_waitcnt lgkmcnt(1)
	v_mfma_f32_32x32x16_bf16 v[16:31], v[36:39], v[120:123], v[16:31]
	s_waitcnt lgkmcnt(0)
	v_mfma_f32_32x32x16_bf16 v[0:15], v[40:43], v[120:123], v[0:15]
	ds_read_b128 v[36:39], v166 offset:64
	ds_read_b128 v[40:43], v166 offset:8768
	s_waitcnt lgkmcnt(1)
	v_mfma_f32_32x32x16_bf16 v[16:31], v[36:39], v[124:127], v[16:31]
	s_waitcnt lgkmcnt(0)
	v_mfma_f32_32x32x16_bf16 v[0:15], v[40:43], v[124:127], v[0:15]
	ds_read_b128 v[36:39], v166 offset:96
	ds_read_b128 v[40:43], v166 offset:8800
	s_waitcnt lgkmcnt(1)
	v_mfma_f32_32x32x16_bf16 v[16:31], v[36:39], v[128:131], v[16:31]
	s_waitcnt lgkmcnt(0)
	v_mfma_f32_32x32x16_bf16 v[0:15], v[40:43], v[128:131], v[0:15]
	s_cbranch_scc0 .LBB0_112
	v_lshlrev_b32_e32 v36, 2, v149
	v_sub_u32_e32 v36, v36, v150
	v_lshl_add_u32 v55, v36, 2, s61
	ds_read2_b32 v[36:37], v55 offset0:224 offset1:225
	ds_read2_b32 v[38:39], v55 offset0:226 offset1:227
	ds_read2_b32 v[40:41], v55 offset0:232 offset1:233
	ds_read2_b32 v[42:43], v55 offset0:234 offset1:235
	ds_read2_b32 v[44:45], v55 offset0:240 offset1:241
	ds_read2_b32 v[46:47], v55 offset0:242 offset1:243
	ds_read2_b32 v[48:49], v55 offset0:248 offset1:249
	ds_read2_b32 v[50:51], v55 offset0:250 offset1:251
	s_waitcnt lgkmcnt(7)
	v_sub_f32_e32 v37, v37, v161
	s_waitcnt lgkmcnt(3)
	v_sub_f32_e32 v45, v45, v161
	v_sub_f32_e32 v44, v44, v161
	s_waitcnt lgkmcnt(2)
	v_sub_f32_e32 v47, v47, v161
	v_sub_f32_e32 v46, v46, v161
	s_waitcnt lgkmcnt(1)
	v_sub_f32_e32 v49, v49, v161
	v_sub_f32_e32 v48, v48, v161
	s_waitcnt lgkmcnt(0)
	v_sub_f32_e32 v51, v51, v161
	v_sub_f32_e32 v50, v50, v161
	v_sub_f32_e32 v36, v36, v161
	v_sub_f32_e32 v39, v39, v161
	v_sub_f32_e32 v38, v38, v161
	v_sub_f32_e32 v41, v41, v161
	v_sub_f32_e32 v40, v40, v161
	v_sub_f32_e32 v43, v43, v161
	v_sub_f32_e32 v42, v42, v161
	v_pk_add_f32 v[22:23], v[22:23], v[42:43]
	v_pk_add_f32 v[20:21], v[20:21], v[40:41]
	v_pk_add_f32 v[18:19], v[18:19], v[38:39]
	v_pk_add_f32 v[16:17], v[16:17], v[36:37]
	v_pk_add_f32 v[30:31], v[30:31], v[50:51]
	v_pk_add_f32 v[28:29], v[28:29], v[48:49]
	v_pk_add_f32 v[26:27], v[26:27], v[46:47]
	v_pk_add_f32 v[24:25], v[24:25], v[44:45]
	v_add_u32_e32 v36, 0x400, v55
	v_add_u32_e32 v38, 0x408, v55
	v_add_u32_e32 v40, 0x420, v55
	v_add_u32_e32 v42, 0x428, v55
	ds_read2_b32 v[36:37], v36 offset1:1
	ds_read2_b32 v[38:39], v38 offset1:1
	ds_read2_b32 v[40:41], v40 offset1:1
	ds_read2_b32 v[42:43], v42 offset1:1
	v_add_u32_e32 v44, 0x440, v55
	v_add_u32_e32 v46, 0x448, v55
	v_add_u32_e32 v48, 0x460, v55
	v_add_u32_e32 v50, 0x468, v55
	ds_read2_b32 v[44:45], v44 offset1:1
	ds_read2_b32 v[46:47], v46 offset1:1
	ds_read2_b32 v[48:49], v48 offset1:1
	ds_read2_b32 v[50:51], v50 offset1:1
	s_waitcnt lgkmcnt(7)
	v_sub_f32_e32 v37, v37, v161
	v_sub_f32_e32 v36, v36, v161
	s_waitcnt lgkmcnt(2)
	v_sub_f32_e32 v47, v47, v161
	v_sub_f32_e32 v45, v45, v161
	v_sub_f32_e32 v44, v44, v161
	v_sub_f32_e32 v46, v46, v161
	s_waitcnt lgkmcnt(1)
	v_sub_f32_e32 v49, v49, v161
	v_sub_f32_e32 v48, v48, v161
	s_waitcnt lgkmcnt(0)
	v_sub_f32_e32 v51, v51, v161
	v_sub_f32_e32 v50, v50, v161
	v_sub_f32_e32 v39, v39, v161
	v_sub_f32_e32 v38, v38, v161
	v_sub_f32_e32 v41, v41, v161
	v_sub_f32_e32 v40, v40, v161
	v_sub_f32_e32 v43, v43, v161
	v_sub_f32_e32 v42, v42, v161
	v_pk_add_f32 v[6:7], v[6:7], v[42:43]
	v_pk_add_f32 v[4:5], v[4:5], v[40:41]
	v_pk_add_f32 v[2:3], v[2:3], v[38:39]
	v_pk_add_f32 v[0:1], v[0:1], v[36:37]
	v_pk_add_f32 v[14:15], v[14:15], v[50:51]
	v_pk_add_f32 v[12:13], v[12:13], v[48:49]
	v_pk_add_f32 v[10:11], v[10:11], v[46:47]
	v_pk_add_f32 v[8:9], v[8:9], v[44:45]

; template <int MODE, bool FROZEN = false>
; __device__ __forceinline__ bool attn_unit(LAS unsigned char* lds, const Params& p, int l, int ua, int ub) {
;     ...
;         const float s1 = wave_sum(lq[lane] * lq[64 + lane]), s2 = wave_sum(lq[128 + lane] * lq[192 + lane]);
;         lam_init = 0.8f - 0.6f * expf(-0.3f * (float)l);
;         lam = expf(s1) - expf(s2) + lam_init;
;     ...
;     for (int i = 0; i < NKC; ++i) { const int cid = tid + 512 * i, row = cid / KCH, ch = cid % KCH; ksrc[i] = (unsigned)(row * NPROJ + kcol + ch * 8); kdst[i] = OFF_K + row * KPB + ch * 16; }
; #pragma unroll
;     for (int i = 0; i < NVC; ++i) { const int cid = tid + 512 * i, row = cid >> 3, ch = cid & 7; vsrc[i] = (unsigned)((vcol + row) * S + ch * 8); vdst[i] = OFF_V + row * VTP + (ch >> 1) * 32 + (ch & 1) * 8; }
;     const bf16_t* vtbase = vtg + kt0;
.LBB0_116:
	v_mul_f32_e32 v55, 0x3fb8aa3b, v53
	s_mov_b32 s8, 0x3fb8aa3b
	v_fma_f32 v56, v53, s8, -v55
	v_fmac_f32_e32 v56, 0x32a5705f, v53
	v_rndne_f32_e32 v53, v55
	v_sub_f32_e32 v55, v55, v53
	v_add_f32_e32 v55, v55, v56
	v_mul_f32_e32 v56, 0x3fb8aa3b, v54
	v_fma_f32 v57, v54, s8, -v56
	v_fmac_f32_e32 v57, 0x32a5705f, v54
	v_rndne_f32_e32 v54, v56
	v_exp_f32_e32 v55, v55
	v_cvt_i32_f32_e32 v53, v53
	v_sub_f32_e32 v56, v56, v54
	v_add_f32_e32 v56, v56, v57
	v_exp_f32_e32 v56, v56
	v_cvt_i32_f32_e32 v54, v54
	v_ldexp_f32 v53, v55, v53
	v_cndmask_b32_e64 v53, 0, v53, s[40:41]
	v_mov_b32_e32 v55, 0x7f800000
	v_cndmask_b32_e64 v167, v55, v53, s[42:43]
	v_ldexp_f32 v53, v56, v54
	v_cndmask_b32_e64 v53, 0, v53, s[0:1]
	s_lshl_b32 s0, s51, 7
	s_and_b32 s0, s0, 0x2000
	s_lshl_b32 s1, s57, 7
	v_cndmask_b32_e64 v168, v55, v53, s[4:5]
	s_add_i32 s4, s0, s1
	s_or_b32 s4, s4, s58
	v_mul_u32_u24_e32 v53, 0x90, v52
	v_add_lshl_u32 v52, s4, v52, 2
	v_sub_u32_e32 v52, v32, v52
	s_or_b32 s1, s58, s1
	v_add3_u32 v101, 0, v53, v32
	v_add_u32_e32 v102, 0, v52
	s_add_i32 s1, s1, s0
	v_mov_b64_e32 v[98:99], v[50:51]
	v_mov_b64_e32 v[82:83], v[50:51]
	v_mov_b64_e32 v[66:67], v[50:51]
	s_add_i32 s8, s4, 0xffffff81
	s_sub_i32 s12, 33, s1
	s_mov_b32 s13, 0
	v_mov_b64_e32 v[96:97], v[48:49]
	v_mov_b64_e32 v[94:95], v[46:47]
	v_mov_b64_e32 v[92:93], v[44:45]
	v_mov_b64_e32 v[90:91], v[42:43]
	v_mov_b64_e32 v[88:89], v[40:41]
	v_mov_b64_e32 v[86:87], v[38:39]
	v_mov_b64_e32 v[84:85], v[36:37]
	v_mov_b64_e32 v[80:81], v[48:49]
	v_mov_b64_e32 v[78:79], v[46:47]
	v_mov_b64_e32 v[76:77], v[44:45]
	v_mov_b64_e32 v[74:75], v[42:43]
	v_mov_b64_e32 v[72:73], v[40:41]
	v_mov_b64_e32 v[70:71], v[38:39]
	v_mov_b64_e32 v[68:69], v[36:37]
	v_mov_b64_e32 v[64:65], v[48:49]
	v_mov_b64_e32 v[62:63], v[46:47]
	v_mov_b64_e32 v[60:61], v[44:45]
	v_mov_b64_e32 v[58:59], v[42:43]
	v_mov_b64_e32 v[56:57], v[40:41]
	v_mov_b64_e32 v[54:55], v[38:39]
	v_mov_b64_e32 v[52:53], v[36:37]
	v_mov_b64_e32 v[218:219], 0
	v_mov_b64_e32 v[220:221], 0
	v_mov_b64_e32 v[222:223], 0
	v_mov_b64_e32 v[224:225], 0
	v_mov_b64_e32 v[248:249], 0
	v_mov_b64_e32 v[250:251], 0
	v_mov_b64_e32 v[236:237], 0
	v_mov_b64_e32 v[238:239], 0
	v_mov_b64_e32 v[244:245], 0
	v_mov_b64_e32 v[246:247], 0
	s_waitcnt vmcnt(0)
	v_readfirstlane_b32 s98, v228
	s_lshr_b32 s98, s98, 6
	s_lshl_b32 s98, s98, 11
	v_lshrrev_b32_e32 v140, 4, v228
	v_mul_u32_u24_e32 v140, 0xf00, v140
	v_and_b32_e32 v141, 15, v228
	v_lshl_add_u32 v140, v141, 3, v140
	v_sub_u32_e32 v140, v196, v140
	s_nop 0
	v_readfirstlane_b32 s99, v140
	s_lshl_b32 s99, s99, 1
	s_add_i32 s99, s99, 0xf0000
	v_and_b32_e32 v140, 63, v228
	v_lshrrev_b32_e32 v141, 6, v228
	v_lshl_add_u32 v140, v141, 7, v140
	v_add_u32_e32 v141, 64, v140
	v_and_b32_e32 v142, 63, v228
	v_add_u32_e32 v142, 0x400, v142
	v_mul_u32_u24_e32 v132, 0xf10, v140
	v_mul_u32_u24_e32 v133, 0xf10, v141
	v_mul_u32_u24_e32 v134, 0xf10, v142
	v_lshrrev_b32_e32 v132, 16, v132
	v_lshrrev_b32_e32 v133, 16, v133
	v_lshrrev_b32_e32 v134, 16, v134
	v_mul_u32_u24_e32 v135, 17, v132
	v_sub_u32_e32 v140, v140, v135
	v_mul_u32_u24_e32 v135, 17, v133
	v_sub_u32_e32 v141, v141, v135
	v_mul_u32_u24_e32 v135, 17, v134
	v_sub_u32_e32 v142, v142, v135
	v_cmp_eq_u32_e32 vcc, 16, v140
	s_nop 1
	v_cndmask_b32_e64 v140, v140, 0, vcc
	v_cmp_eq_u32_e32 vcc, 16, v141
	s_nop 1
	v_cndmask_b32_e64 v141, v141, 0, vcc
	v_cmp_eq_u32_e32 vcc, 16, v142
	s_nop 1
	v_cndmask_b32_e64 v142, v142, 0, vcc
	v_mul_u32_u24_e32 v132, 0x1e00, v132
	v_mul_u32_u24_e32 v133, 0x1e00, v133
	v_mul_u32_u24_e32 v134, 0x1e00, v134
	v_lshl_add_u32 v132, v140, 4, v132
	v_lshl_add_u32 v133, v141, 4, v133
	v_lshl_add_u32 v134, v142, 4, v134
	v_lshrrev_b32_e32 v140, 3, v228
	v_lshlrev_b32_e32 v140, 14, v140
	v_and_b32_e32 v141, 7, v228
	v_lshl_add_u32 v140, v141, 3, v140
	v_sub_u32_e32 v140, v154, v140
	s_nop 0
	v_readfirstlane_b32 s101, v140
	s_lshl_b32 s101, s101, 1
	v_and_b32_e32 v140, 63, v228
	v_lshrrev_b32_e32 v141, 6, v228
	v_lshl_add_u32 v142, v141, 6, v140
	v_add_u32_e32 v142, 0x400, v142
	v_lshl_add_u32 v140, v141, 7, v140
	v_add_u32_e32 v141, 64, v140
	v_mul_u32_u24_e32 v135, 0x1c72, v140
	v_mul_u32_u24_e32 v136, 0x1c72, v141
	v_mul_u32_u24_e32 v137, 0x1c72, v142
	v_lshrrev_b32_e32 v135, 16, v135
	v_lshrrev_b32_e32 v136, 16, v136
	v_lshrrev_b32_e32 v137, 16, v137
	v_mul_u32_u24_e32 v143, 9, v135
	v_sub_u32_e32 v140, v140, v143
	v_mul_u32_u24_e32 v143, 9, v136
	v_sub_u32_e32 v141, v141, v143
	v_mul_u32_u24_e32 v143, 9, v137
	v_sub_u32_e32 v142, v142, v143
	v_cmp_eq_u32_e32 vcc, 8, v140
	s_nop 1
	v_cndmask_b32_e64 v140, v140, 0, vcc
	v_cmp_eq_u32_e32 vcc, 8, v141
	s_nop 1
	v_cndmask_b32_e64 v141, v141, 0, vcc
	v_cmp_eq_u32_e32 vcc, 8, v142
	s_nop 1
	v_cndmask_b32_e64 v142, v142, 0, vcc
	v_lshlrev_b32_e32 v135, 15, v135
	v_lshlrev_b32_e32 v136, 15, v136
	v_lshlrev_b32_e32 v137, 15, v137
	v_lshl_add_u32 v135, v140, 4, v135
	v_lshl_add_u32 v136, v141, 4, v136
	v_lshl_add_u32 v137, v142, 4, v137
	v_readfirstlane_b32 s100, v228
	s_lshr_b32 s100, s100, 8
	s_cmp_eq_u32 s100, 0
	s_cbranch_scc1 .Lattn_prio_skip
	s_setprio 1

; #define LAS __attribute__((address_space(3)))
; template <int MODE, bool FROZEN = false>
; __device__ __forceinline__ bool attn_unit(LAS unsigned char* lds, const Params& p, int l, int ua, int ub) {
;     ...
;         if (t + 2 < NT) {
; #pragma unroll
;             for (int i = 0; i < NKC; ++i) *(LAS u32x4*)(lds + kdst[i] + (t & 1) * KBUF) = kr[i];
;         }
;         if (t + 1 < NT) {
; #pragma unroll
;             for (int i = 0; i < NVC; ++i) { *(LAS u32x2*)(lds + vdst[i] + ((t + 1) & 1) * VBUF) = (u32x2){vr[i].x, vr[i].y}; *(LAS u32x2*)(lds + vdst[i] + ((t + 1) & 1) * VBUF + 16) = (u32x2){vr[i].z, vr[i].w}; }
;         }
;         {
;             const size_t advk = (size_t)min(t + 3, NT - 1) * 64 * NPROJ, advv = (size_t)min(t + 2, NT - 1) * 64;
; #pragma unroll
;             for (int i = 0; i < NKC; ++i) kr[i] = *(const u32x4*)(kvbase + advk + ksrc[i]);
; #pragma unroll
;             for (int i = 0; i < NVC; ++i) vr[i] = *(const u32x4*)(vtbase + advv + vsrc[i]);
;         }
;         f32x16 sA0 = sB0, sA1 = sB1;
;         const float c2 = cbB - m_run;
;         const LAS unsigned char* Vb = lds + OFF_V + (t & 1) * VBUF + vlane_off;
;         const LAS unsigned char* Kb = lds + OFF_K + ((t + 1) & 1) * KBUF + klane_off;
;     ...
;         bf16x8 kf0[4], kf1[4], va[NB], vb[NB], pf0, pf1; float ps0, ps1, ps2, ps3;
;         VLOAD(0, va);
;         EXPCVT(0, pf0, ps0);
;         SBAR_();
;         VLOAD(1, vb); PVMMA(va, pf0); EXPCVT(1, pf1, ps1); _Pragma("unroll") for (int g_ = 0; g_ < NB; ++g_) { __builtin_amdgcn_sched_group_barrier(0x008, 1, 0); __builtin_amdgcn_sched_group_barrier(0x100, 1, 0); __builtin_amdgcn_sched_group_barrier(0x400, 8 / NB, 0); __builtin_amdgcn_sched_group_barrier(0x002, 12 / NB, 0); } SBAR_();
;         VLOAD(2, va);
; #pragma unroll
;         for (int d0 = 0; d0 < 4; ++d0) { kf0[d0] = *(const LAS bf16x8*)(Kb + d0 * 32); kf1[d0] = *(const LAS bf16x8*)(Kb + 32 * KPB + d0 * 32); }
;         PVMMA(vb, pf1); EXPCVT(2, pf0, ps2); _Pragma("unroll") for (int g_ = 0; g_ < NB; ++g_) { __builtin_amdgcn_sched_group_barrier(0x008, 1, 0); __builtin_amdgcn_sched_group_barrier(0x100, 1, 0); __builtin_amdgcn_sched_group_barrier(0x400, 8 / NB, 0); __builtin_amdgcn_sched_group_barrier(0x002, 12 / NB, 0); } SBAR_();
;         {
;             f32x16 z0, z1;
; #pragma unroll
;             for (int r = 0; r < 16; ++r) { z0[r] = 0.f; z1[r] = 0.f; }
; #pragma unroll
.LBB0_117:
.LBB0_118:
	s_add_i32 s14, s4, 1
	s_bitcmp1_b32 s14, 0
	s_cselect_b32 s15, 0x4400, 0
	s_cselect_b32 s100, 0, 0x4800
	v_add_u32_e32 v194, s100, v101
	s_sub_i32 s5, 0x4400, s15
	s_min_i32 s10, s4, 0xfd
	s_mul_i32 s10, s10, 0x78000
	s_add_u32 s10, s34, s10
	s_addc_u32 s11, s35, 0
	s_add_u32 s10, s10, s99
	s_addc_u32 s11, s11, 0
	s_lshl_b32 s0, s14, 7
	s_add_u32 s0, s6, s0
	s_addc_u32 s1, s7, 0
	s_add_u32 s0, s0, s101
	s_addc_u32 s1, s1, 0
	ds_read_b128 v[112:115], v194 offset:34816
	ds_read_b128 v[170:173], v194 offset:39424
	ds_read_b128 v[174:177], v194 offset:44032
	ds_read_b128 v[178:181], v194 offset:48640
	v_exp_f32_e32 v103, v16
	v_exp_f32_e32 v104, v17
	v_mfma_f32_32x32x16_bf16 v[52:67], v[236:239], v[244:247], v[52:67]
	v_exp_f32_e32 v105, v18
	v_exp_f32_e32 v106, v19
	v_cvt_pk_bf16_f32 v16, v103, v104
	v_mfma_f32_32x32x16_bf16 v[36:51], v[218:221], v[244:247], v[36:51]
	s_add_i32 m0, s5, s98
	s_nop 0
	global_load_lds_dwordx4 v132, s[10:11]
	v_exp_f32_e32 v107, v20
	v_exp_f32_e32 v108, v21
	v_cvt_pk_bf16_f32 v17, v105, v106
	v_mfma_f32_32x32x16_bf16 v[84:99], v[222:225], v[244:247], v[84:99]
	s_add_i32 m0, m0, 0x400
	s_nop 0
	global_load_lds_dwordx4 v133, s[10:11]
	v_exp_f32_e32 v109, v22
	v_exp_f32_e32 v110, v23
	v_cvt_pk_bf16_f32 v18, v107, v108
	v_mfma_f32_32x32x16_bf16 v[68:83], v[248:251], v[244:247], v[68:83]
	s_cmp_lg_u32 s98, 0
	s_cbranch_scc1 .Lkdma_skip
	s_add_i32 m0, s5, 0x4000
	s_nop 0
	global_load_lds_dwordx4 v134, s[10:11]
.Lkdma_skip:
	v_add_u32_e32 v195, s15, v166
	v_cvt_pk_bf16_f32 v19, v109, v110
	s_waitcnt lgkmcnt(3)
	s_nop 0
	v_mfma_f32_32x32x16_bf16 v[36:51], v[112:115], v[16:19], v[36:51]
	ds_read_b128 v[20:23], v194 offset:34848
	ds_read_b128 v[218:221], v195 offset:32
	s_sub_i32 s10, 0xd000, s100
	s_add_i32 m0, s10, s98
	s_nop 0
	global_load_lds_dwordx4 v135, s[0:1]
	v_exp_f32_e32 v111, v24
	v_exp_f32_e32 v112, v25
	s_nop 0
	v_cvt_pk_bf16_f32 v24, v111, v112
	s_waitcnt lgkmcnt(4)
	v_mfma_f32_32x32x16_bf16 v[84:99], v[170:173], v[16:19], v[84:99]
	ds_read_b128 v[182:185], v194 offset:39456
	ds_read_b128 v[222:225], v195 offset:64
	s_add_i32 m0, m0, 0x400
	s_nop 0
	global_load_lds_dwordx4 v136, s[0:1]
	v_exp_f32_e32 v113, v26
	v_exp_f32_e32 v114, v27
	s_nop 0
	v_cvt_pk_bf16_f32 v25, v113, v114
	s_waitcnt lgkmcnt(5)
	v_mfma_f32_32x32x16_bf16 v[68:83], v[174:177], v[16:19], v[68:83]
	ds_read_b128 v[186:189], v194 offset:44064
	ds_read_b128 v[248:251], v195 offset:96
	s_cmp_gt_u32 s98, 0x800
	s_cbranch_scc1 .Lvdma_skip
	s_lshr_b32 s11, s98, 1
	s_add_i32 s11, s11, s10
	s_add_i32 m0, s11, 0x4000
	s_nop 0
	global_load_lds_dwordx4 v137, s[0:1]
.Lvdma_skip:
	v_exp_f32_e32 v115, v28
	v_exp_f32_e32 v170, v29
	s_nop 0
	v_cvt_pk_bf16_f32 v26, v115, v170
	s_waitcnt lgkmcnt(6)
	v_mfma_f32_32x32x16_bf16 v[52:67], v[178:181], v[16:19], v[52:67]
	ds_read_b128 v[16:19], v194 offset:48672
	v_exp_f32_e32 v171, v30
	v_exp_f32_e32 v172, v31
	s_nop 0
	v_cvt_pk_bf16_f32 v27, v171, v172
	s_waitcnt lgkmcnt(6)
	s_nop 0
	v_mfma_f32_32x32x16_bf16 v[36:51], v[20:23], v[24:27], v[36:51]
	ds_read_b128 v[190:193], v194 offset:34880
	ds_read_b128 v[20:23], v195 offset:8736
	v_exp_f32_e32 v173, v0
	v_exp_f32_e32 v174, v1
	s_nop 0
	v_cvt_pk_bf16_f32 v202, v173, v174
	s_waitcnt lgkmcnt(6)
	v_mfma_f32_32x32x16_bf16 v[84:99], v[182:185], v[24:27], v[84:99]
	ds_read_b128 v[206:209], v194 offset:39488
	v_exp_f32_e32 v175, v2
	v_exp_f32_e32 v176, v3
	s_nop 0
	v_cvt_pk_bf16_f32 v203, v175, v176
	s_waitcnt lgkmcnt(5)
	v_mfma_f32_32x32x16_bf16 v[68:83], v[186:189], v[24:27], v[68:83]
	ds_read_b128 v[210:213], v194 offset:44096
	v_exp_f32_e32 v177, v4
	v_exp_f32_e32 v178, v5
	s_nop 0
	v_cvt_pk_bf16_f32 v204, v177, v178
	s_waitcnt lgkmcnt(4)
	v_mfma_f32_32x32x16_bf16 v[52:67], v[16:19], v[24:27], v[52:67]
	ds_read_b128 v[214:217], v194 offset:48704
	ds_read_b128 v[236:239], v194 offset:48736
	ds_read_b128 v[0:3], v195 offset:8704
	v_exp_f32_e32 v179, v6
	v_exp_f32_e32 v180, v7
	s_nop 0
	v_cvt_pk_bf16_f32 v205, v179, v180
	v_exp_f32_e32 v181, v8
	v_exp_f32_e32 v182, v9
	s_waitcnt lgkmcnt(6)
	v_mfma_f32_32x32x16_bf16 v[36:51], v[190:193], v[202:205], v[36:51]
	ds_read_b128 v[24:27], v195 offset:8768
	v_exp_f32_e32 v183, v10
	v_exp_f32_e32 v184, v11
	v_cvt_pk_bf16_f32 v244, v181, v182
	s_waitcnt lgkmcnt(5)
	v_mfma_f32_32x32x16_bf16 v[84:99], v[206:209], v[202:205], v[84:99]
	ds_read_b128 v[28:31], v195 offset:8800
	v_exp_f32_e32 v185, v12
	v_exp_f32_e32 v186, v13
	v_cvt_pk_bf16_f32 v245, v183, v184
	s_waitcnt lgkmcnt(5)
	v_mfma_f32_32x32x16_bf16 v[68:83], v[210:213], v[202:205], v[68:83]
	ds_read_b128 v[16:19], v195
	v_exp_f32_e32 v187, v14
	v_exp_f32_e32 v188, v15
	v_cvt_pk_bf16_f32 v246, v185, v186
	s_waitcnt lgkmcnt(5)
	v_mfma_f32_32x32x16_bf16 v[52:67], v[214:217], v[202:205], v[52:67]
	v_cvt_pk_bf16_f32 v247, v187, v188
	s_waitcnt lgkmcnt(3)
	v_mfma_f32_32x32x16_bf16 v[0:15], v[0:3], v[116:119], 0
	v_add_f32_e32 v105, v105, v106
	v_add_f32_e32 v106, v107, v108
	v_add_f32_e32 v107, v109, v110
	v_add_f32_e32 v103, v103, v104
	v_mfma_f32_32x32x16_bf16 v[0:15], v[20:23], v[120:123], v[0:15]
	v_add_f32_e32 v106, v106, v107
	v_add_f32_e32 v103, v103, v105
	v_add_f32_e32 v105, v115, v170
	v_add_f32_e32 v107, v171, v172
	s_waitcnt lgkmcnt(2)
	v_mfma_f32_32x32x16_bf16 v[0:15], v[24:27], v[124:127], v[0:15]
	v_add_f32_e32 v104, v113, v114
	v_add_f32_e32 v105, v105, v107
	v_add_f32_e32 v107, v111, v112
	v_add_f32_e32 v104, v107, v104
	s_waitcnt lgkmcnt(1)
	v_mfma_f32_32x32x16_bf16 v[0:15], v[28:31], v[128:131], v[0:15]
	v_add_f32_e32 v107, v177, v178
	v_add_f32_e32 v108, v179, v180
	v_add_f32_e32 v104, v104, v105
	v_add_f32_e32 v105, v175, v176
	s_waitcnt lgkmcnt(0)
	v_mfma_f32_32x32x16_bf16 v[16:31], v[16:19], v[116:119], 0
	v_add_f32_e32 v107, v107, v108
	v_add_f32_e32 v108, v173, v174
	v_add_f32_e32 v105, v108, v105
	v_add_f32_e32 v105, v105, v107
	s_cmpk_gt_i32 s12, 0x7f
	s_cselect_b64 s[0:1], -1, 0
	s_cmpk_gt_i32 s8, 0x7f
	s_cselect_b64 s[4:5], -1, 0
	s_or_b64 s[10:11], s[0:1], s[4:5]
	v_mfma_f32_32x32x16_bf16 v[16:31], v[218:221], v[120:123], v[16:31]
	ds_read_b128 v[218:221], v194 offset:34912
	v_add_f32_e32 v107, v185, v186
	v_add_f32_e32 v108, v187, v188
	v_add_f32_e32 v103, v103, v106
	v_add_f32_e32 v106, v183, v184
	s_and_b64 vcc, exec, s[10:11]
	v_mfma_f32_32x32x16_bf16 v[16:31], v[222:225], v[124:127], v[16:31]
	ds_read_b128 v[222:225], v194 offset:39520
	v_add_f32_e32 v107, v107, v108
	v_add_f32_e32 v108, v181, v182
	v_add_f32_e32 v106, v108, v106
	v_add_f32_e32 v106, v106, v107
	v_mfma_f32_32x32x16_bf16 v[16:31], v[248:251], v[128:131], v[16:31]
	ds_read_b128 v[248:251], v194 offset:44128
	v_add_f32_e32 v103, v103, v104
	v_add_f32_e32 v104, v105, v106
	v_add_f32_e32 v103, v103, v104
	v_add_f32_e32 v100, v100, v103
	s_cbranch_vccnz .LBB0_120
	v_add_u32_e32 v189, s13, v102
	v_add_u32_e32 v190, 0x11c80, v189
	v_add_u32_e32 v192, 0x11c88, v189
	v_add_u32_e32 v194, 0x11ca0, v189
	v_add_u32_e32 v202, 0x11ca8, v189
	ds_read2_b32 v[190:191], v190 offset1:1
	ds_read2_b32 v[192:193], v192 offset1:1
	ds_read2_b32 v[194:195], v194 offset1:1
	ds_read2_b32 v[202:203], v202 offset1:1
	v_add_u32_e32 v204, 0x11cc0, v189
	v_add_u32_e32 v206, 0x11cc8, v189
	v_add_u32_e32 v208, 0x11ce0, v189
	v_add_u32_e32 v210, 0x11ce8, v189
	ds_read2_b32 v[204:205], v204 offset1:1
	ds_read2_b32 v[206:207], v206 offset1:1
	ds_read2_b32 v[208:209], v208 offset1:1
	ds_read2_b32 v[210:211], v210 offset1:1
	s_waitcnt lgkmcnt(7)
	v_sub_f32_e32 v191, v191, v169
	v_sub_f32_e32 v190, v190, v169
	s_waitcnt lgkmcnt(2)
	v_sub_f32_e32 v207, v207, v169
	v_sub_f32_e32 v205, v205, v169
	v_sub_f32_e32 v204, v204, v169
	v_sub_f32_e32 v206, v206, v169
	s_waitcnt lgkmcnt(1)
	v_sub_f32_e32 v209, v209, v169
	v_sub_f32_e32 v208, v208, v169
	s_waitcnt lgkmcnt(0)
	v_sub_f32_e32 v211, v211, v169
	v_sub_f32_e32 v210, v210, v169
	v_sub_f32_e32 v193, v193, v169
	v_sub_f32_e32 v192, v192, v169
	v_sub_f32_e32 v195, v195, v169
	v_sub_f32_e32 v194, v194, v169
	v_sub_f32_e32 v203, v203, v169
	v_sub_f32_e32 v202, v202, v169
	v_pk_add_f32 v[22:23], v[22:23], v[202:203]
	v_pk_add_f32 v[20:21], v[20:21], v[194:195]
	v_pk_add_f32 v[18:19], v[18:19], v[192:193]
	v_pk_add_f32 v[16:17], v[16:17], v[190:191]
	v_pk_add_f32 v[30:31], v[30:31], v[210:211]
	v_pk_add_f32 v[28:29], v[28:29], v[208:209]
	v_pk_add_f32 v[26:27], v[26:27], v[206:207]
	v_pk_add_f32 v[24:25], v[24:25], v[204:205]
	v_add_u32_e32 v190, 0x11d00, v189
	v_add_u32_e32 v192, 0x11d08, v189
	v_add_u32_e32 v194, 0x11d20, v189
	v_add_u32_e32 v202, 0x11d28, v189
	ds_read2_b32 v[190:191], v190 offset1:1
	ds_read2_b32 v[192:193], v192 offset1:1
	ds_read2_b32 v[194:195], v194 offset1:1
	ds_read2_b32 v[202:203], v202 offset1:1
	v_add_u32_e32 v204, 0x11d40, v189
	v_add_u32_e32 v206, 0x11d48, v189
	v_add_u32_e32 v208, 0x11d60, v189
	ds_read2_b32 v[204:205], v204 offset1:1
	v_add_u32_e32 v189, 0x11d68, v189
	ds_read2_b32 v[206:207], v206 offset1:1
	ds_read2_b32 v[208:209], v208 offset1:1
	ds_read2_b32 v[210:211], v189 offset1:1
	s_waitcnt lgkmcnt(7)
	v_sub_f32_e32 v191, v191, v169
	v_sub_f32_e32 v190, v190, v169
	s_waitcnt lgkmcnt(3)
	v_sub_f32_e32 v205, v205, v169
	v_sub_f32_e32 v204, v204, v169
	s_waitcnt lgkmcnt(2)
	v_sub_f32_e32 v207, v207, v169
	v_sub_f32_e32 v206, v206, v169
	s_waitcnt lgkmcnt(1)
	v_sub_f32_e32 v209, v209, v169
	v_sub_f32_e32 v208, v208, v169
	s_waitcnt lgkmcnt(0)
	v_sub_f32_e32 v211, v211, v169
	v_sub_f32_e32 v210, v210, v169
	v_sub_f32_e32 v193, v193, v169
	v_sub_f32_e32 v192, v192, v169
	v_sub_f32_e32 v195, v195, v169
	v_sub_f32_e32 v194, v194, v169
	v_sub_f32_e32 v203, v203, v169
	v_sub_f32_e32 v202, v202, v169
	v_pk_add_f32 v[6:7], v[6:7], v[202:203]
	v_pk_add_f32 v[4:5], v[4:5], v[194:195]
	v_pk_add_f32 v[2:3], v[2:3], v[192:193]
	v_pk_add_f32 v[0:1], v[0:1], v[190:191]
	v_pk_add_f32 v[14:15], v[14:15], v[210:211]
	v_pk_add_f32 v[12:13], v[12:13], v[208:209]
	v_pk_add_f32 v[10:11], v[10:11], v[206:207]
	v_pk_add_f32 v[8:9], v[8:9], v[204:205]

; template <int MODE, bool FROZEN = false>
; __device__ __forceinline__ bool attn_unit(LAS unsigned char* lds, const Params& p, int l, int ua, int ub) {
;     ...
;         if (t + 1 < NT) { ATT_BIAS(t + 1, tmr); ATT_UPD(tmr); }
;         asm volatile("s_waitcnt lgkmcnt(0)" ::: "memory"); __builtin_amdgcn_s_barrier(); asm volatile("" ::: "memory");
.LBB0_123:
	s_waitcnt vmcnt(0) lgkmcnt(0)
	s_barrier
	s_addk_i32 s13, 0x100
	s_sub_i32 s8, s8, 64
	s_add_i32 s12, s12, 64
	s_cmpk_eq_u32 s13, 0xff00
	s_cbranch_scc1 .LBB0_125
	s_mov_b32 s4, s14
	s_branch .LBB0_118

; template <int MODE, bool FROZEN = false>
; __device__ __forceinline__ bool attn_unit(LAS unsigned char* lds, const Params& p, int l, int ua, int ub) {
;     ...
;         const float* lq = p.diff_lambda + (size_t)l * 256;
;         const float s1 = wave_sum(lq[lane] * lq[64 + lane]), s2 = wave_sum(lq[128 + lane] * lq[192 + lane]);
;         lam_init = 0.8f - 0.6f * expf(-0.3f * (float)l);
;         lam = expf(s1) - expf(s2) + lam_init;
;     } else {
;         const int g = ua, qb = ub, hq = g * 4 + (wid >> 1); qtok0 = qb * 64 + (wid & 1) * 32; lut_sel = wid >> 1;
;         qcol = 3072 + hq * 64; kcol = 3584 + g * 64; vcol = 1024 + g * 64; ocol = hq * 64;
;         const int tlo = max(qb - 2, 0), thi = min(qb + 2, S / 64 - 1); kt0 = tlo * 64; NT = thi - tlo + 1; wt_hi = NT;
;         for (int i = tid; i < 4 * 449; i += 512) { const int hh = i / 449, rel = i % 449 - 224; lut[i] = (rel >= -128 && rel <= 128) ? p.rel_bias[t5_bucket(rel) * 12 + 4 + g * 4 + hh] * LOG2E : NEGBIG; }
;         m_run = p.gqa_sink[l * 8 + hq] * LOG2E; l_run = (hi == 0) ? 1.0f : 0.0f;
;     }
;     bf16x8 qf[4];
;     { const bf16_t* qp = proj + (size_t)(qtok0 + r32) * NPROJ + qcol + 8 * hi;
; #pragma unroll
;       for (int d0 = 0; d0 < 4; ++d0) qf[d0] = *(const bf16x8*)(qp + 16 * d0); }
;     f32x16 o[NB];
; #pragma unroll
;     for (int nb = 0; nb < NB; ++nb)
; #pragma unroll
;         for (int r = 0; r < 16; ++r) o[nb][r] = 0.f;
;     u32x4 kr[NKC], vr[NVC];
;     unsigned ksrc[NKC], vsrc[NVC]; int kdst[NKC], vdst[NVC];
;     const bf16_t* kvbase = proj + (size_t)kt0 * NPROJ;
; #pragma unroll
;     for (int i = 0; i < NKC; ++i) { const int cid = tid + 512 * i, row = cid / KCH, ch = cid % KCH; ksrc[i] = (unsigned)(row * NPROJ + kcol + ch * 8); kdst[i] = OFF_K + row * KPB + ch * 16; }
; #pragma unroll
;     for (int i = 0; i < NVC; ++i) { const int cid = tid + 512 * i, row = cid >> 3, ch = cid & 7; vsrc[i] = (unsigned)((vcol + row) * S + ch * 8); vdst[i] = OFF_V + row * VTP + (ch >> 1) * 32 + (ch & 1) * 8; }
;     const bf16_t* vtbase = vtg + kt0;
;     {
;         u32x4 k1[NKC];
; #pragma unroll
;         for (int i = 0; i < NKC; ++i) { kr[i] = *(const u32x4*)(kvbase + ksrc[i]); k1[i] = *(const u32x4*)(kvbase + (size_t)64 * NPROJ + ksrc[i]); }
; #pragma unroll
;         for (int i = 0; i < NVC; ++i) vr[i] = *(const u32x4*)(vtbase + vsrc[i]);
; #pragma unroll
.LBB0_155:
	s_or_b64 exec, exec, s[4:5]
	v_ashrrev_i32_e32 v2, 31, v0
	v_lshrrev_b32_e32 v2, 28, v2
	v_add_u32_e32 v2, v0, v2
	v_ashrrev_i32_e32 v44, 4, v2
	v_and_b32_e32 v2, -16, v2
	v_and_b32_e32 v174, 63, v0
	s_lshl_b32 s14, s40, 7
	v_sub_u32_e32 v45, v0, v2
	s_movk_i32 s5, 0xf00
	s_add_i32 s1, s14, 0x800
	v_lshlrev_b32_e32 v1, 2, v174
	v_mul_lo_u32 v2, v44, s5
	v_lshlrev_b32_e32 v3, 3, v45
	global_load_dword v42, v1, s[10:11]
	global_load_dword v43, v1, s[10:11] offset:256
	v_add3_u32 v196, v2, s1, v3
	v_add_u32_e32 v2, 0x200, v0
	v_ashrrev_i32_e32 v3, 31, v2
	v_lshrrev_b32_e32 v3, 28, v3
	v_add_u32_e32 v3, v2, v3
	v_ashrrev_i32_e32 v46, 4, v3
	v_and_b32_e32 v3, -16, v3
	v_sub_u32_e32 v47, v2, v3
	s_add_i32 s4, s14, 0x200
	v_mul_lo_u32 v3, v46, s5
	v_lshlrev_b32_e32 v4, 3, v47
	v_lshlrev_b32_e32 v48, 3, v0
	v_ashrrev_i32_e32 v49, 3, v0
	v_readlane_b32 s16, v252, 27
	v_add3_u32 v162, v3, s1, v4
	v_and_b32_e32 v26, 56, v48
	v_add_u32_e32 v3, s4, v49
	v_lshlrev_b64 v[14:15], 1, v[196:197]
	v_readlane_b32 s17, v252, 28
	v_lshl_or_b32 v164, v3, 14, v26
	v_ashrrev_i32_e32 v50, 3, v2
	v_lshl_add_u64 v[2:3], s[34:35], 0, v[14:15]
	v_lshl_add_u64 v[6:7], s[16:17], 0, v[14:15]
	v_mov_b32_e32 v163, v197
	global_load_dwordx4 v[2:5], v[2:3], off
	s_nop 0
	global_load_dwordx4 v[6:9], v[6:7], off
	v_lshlrev_b64 v[30:31], 1, v[162:163]
	v_lshl_add_u64 v[10:11], s[34:35], 0, v[30:31]
	v_lshl_add_u64 v[16:17], s[16:17], 0, v[30:31]
	global_load_dwordx4 v[10:13], v[10:11], off
	s_nop 0
	global_load_dwordx4 v[18:21], v[16:17], off
	v_add_u32_e32 v27, s4, v50
	v_mov_b32_e32 v165, v197
	v_lshlrev_b64 v[36:37], 1, v[164:165]
	v_lshl_or_b32 v166, v27, 14, v26
	v_mov_b32_e32 v167, v197
	v_lshl_add_u64 v[16:17], s[6:7], 0, v[36:37]
	v_lshlrev_b64 v[38:39], 1, v[166:167]
	global_load_dwordx4 v[22:25], v[16:17], off
	v_lshl_add_u64 v[16:17], s[6:7], 0, v[38:39]
	global_load_dwordx4 v[26:29], v[16:17], off
	s_lshl_b32 s0, s43, 6
	s_and_b32 s0, s0, 64
	s_ashr_i32 s16, s23, 6
	s_add_i32 s0, s0, s42
	s_lshl_b32 s1, s16, 5
	s_lshl_b32 s0, s0, 7
	s_and_b32 s18, s1, 0x60
	v_and_b32_e32 v16, 31, v0
	s_or_b32 s17, s18, s0
	s_ashr_i32 s0, s23, 2
	s_and_b32 s4, s0, 0xffffffc0
	v_or_b32_e32 v160, s17, v16
	v_mov_b64_e32 v[32:33], s[34:35]
	s_movk_i32 s0, 0x1e00
	v_mad_i64_i32 v[32:33], s[0:1], v160, s0, v[32:33]
	s_ashr_i32 s1, s4, 31
	s_ashr_i32 s15, s14, 31
	s_add_u32 s0, s14, s4
	v_bfe_u32 v173, v0, 5, 1
	s_addc_u32 s1, s15, s1
	v_lshl_add_u64 v[40:41], s[0:1], 1, v[32:33]
	v_lshlrev_b32_e32 v32, 4, v173
	v_mov_b32_e32 v33, v197
	v_lshl_add_u64 v[40:41], v[40:41], 0, v[32:33]
	global_load_dwordx4 v[100:103], v[40:41], off offset:3072
	global_load_dword v17, v1, s[10:11] offset:512
	global_load_dword v33, v1, s[10:11] offset:768
	global_load_dwordx4 v[104:107], v[40:41], off offset:3104
	v_xor_b32_e32 v51, 1, v233
	v_cmp_lt_i32_e32 vcc, v51, v234
	global_load_dwordx4 v[108:111], v[40:41], off offset:3136
	global_load_dwordx4 v[112:115], v[40:41], off offset:3168
	v_cndmask_b32_e32 v51, v233, v51, vcc
	v_lshlrev_b32_e32 v51, 2, v51
	s_movk_i32 s0, 0x110
	v_lshlrev_b32_e32 v0, 4, v0
	v_and_b32_e32 v0, 0x70, v0
	s_movk_i32 s5, 0x90
	v_readlane_b32 s19, v254, 46
	v_readlane_b32 s20, v254, 45
	v_ashrrev_i32_e32 v161, 31, v160
	s_waitcnt vmcnt(0)
	v_mul_f32_e32 v1, v42, v43
	ds_bpermute_b32 v52, v51, v1
	v_xor_b32_e32 v1, 2, v233
	v_cmp_lt_i32_e32 vcc, v1, v234
	s_waitcnt lgkmcnt(0)
	v_fmac_f32_e32 v52, v42, v43
	v_cndmask_b32_e32 v1, v233, v1, vcc
	v_lshlrev_b32_e32 v42, 2, v1
	v_mul_lo_u32 v1, v44, s0
	v_lshl_add_u32 v175, v45, 4, v1
	v_mul_lo_u32 v1, v46, s0
	v_lshl_add_u32 v176, v47, 4, v1
	v_add_u32_e32 v1, 0, v175
	s_waitcnt vmcnt(11)
	ds_write_b128 v1, v[2:5]
	s_waitcnt vmcnt(10)
	ds_write_b128 v1, v[6:9] offset:17408
	v_add_u32_e32 v1, 0, v176
	v_mad_u64_u32 v[168:169], s[0:1], v49, s5, v[0:1]
	s_waitcnt vmcnt(9)
	ds_write_b128 v1, v[10:13]
	s_waitcnt vmcnt(8)
	ds_write_b128 v1, v[18:21] offset:17408
	v_add_u32_e32 v1, 0, v168
	v_add_u32_e32 v1, 0x8800, v1
	v_mad_u64_u32 v[170:171], s[0:1], v50, s5, v[0:1]
	v_add_u32_e32 v0, 0, v170
	v_readlane_b32 s0, v252, 29
	v_add_u32_e32 v0, 0x8800, v0
	v_readlane_b32 s1, v252, 30
	s_waitcnt vmcnt(7)
	ds_write_b128 v1, v[22:25]
	s_waitcnt vmcnt(6)
	ds_write_b128 v0, v[26:29]
	v_lshl_add_u64 v[0:1], s[0:1], 0, v[14:15]
	v_lshl_add_u64 v[2:3], s[0:1], 0, v[30:31]
	v_readlane_b32 s0, v252, 31
	v_readlane_b32 s1, v252, 32
	global_load_dwordx4 v[124:127], v[0:1], off
	global_load_dwordx4 v[128:131], v[2:3], off
	v_lshl_add_u64 v[0:1], s[0:1], 0, v[36:37]
	v_lshl_add_u64 v[2:3], s[0:1], 0, v[38:39]
	global_load_dwordx4 v[116:119], v[0:1], off
	global_load_dwordx4 v[120:123], v[2:3], off
	ds_bpermute_b32 v43, v42, v52
	v_xor_b32_e32 v5, 4, v233
	v_cmp_lt_i32_e32 vcc, v5, v234
	v_lshl_or_b32 v0, s4, 1, v32
	v_mul_u32_u24_e32 v1, 0x110, v16
	v_cndmask_b32_e32 v5, v233, v5, vcc
	s_waitcnt lgkmcnt(0)
	v_add_f32_e32 v4, v52, v43
	v_lshlrev_b32_e32 v26, 2, v5
	v_add3_u32 v171, 0, v0, v1
	ds_bpermute_b32 v5, v26, v4
	s_waitcnt lgkmcnt(0)
	s_barrier
; #define ATT_MAX3(dst) do { float tm_ = max3f(sB0[0], sB1[0], sB0[1]), tn_ = max3f(sB1[1], sB0[2], sB1[2]); \
;         _Pragma("unroll") for (int r = 3; r < 15; r += 2) { tm_ = max3f(tm_, sB0[r], sB1[r]); tn_ = max3f(tn_, sB0[r + 1], sB1[r + 1]); } \
;         tm_ = max3f(tm_, sB0[15], sB1[15]); dst = max3f(tm_, tn_, tn_); } while (0)
; template <int MODE, bool FROZEN = false>
; __device__ __forceinline__ bool attn_unit(LAS unsigned char* lds, const Params& p, int l, int ua, int ub) {
;     ...
;         const float s1 = wave_sum(lq[lane] * lq[64 + lane]), s2 = wave_sum(lq[128 + lane] * lq[192 + lane]);
;     ...
;     float cb_pos = 0.f, cb_neg = 0.f;
;     if constexpr (MODE == 1) { cb_pos = lut[448]; cb_neg = lut[0]; }
;     ATT_QK(0);
;     if constexpr (FROZEN) m_run = cb_neg;
;     { float tm0 = 0.f; if constexpr (!FROZEN) ATT_MAX3(tm0); ATT_BIAS(0, tm0); ATT_UPD(tm0); }
	ds_read_b128 v[0:3], v171
	v_add_f32_e32 v27, v4, v5
	s_waitcnt vmcnt(9) lgkmcnt(0)
	v_mfma_f32_32x32x16_bf16 v[84:99], v[0:3], v[100:103], 0
	s_waitcnt vmcnt(7)
	v_mul_f32_e32 v4, v17, v33
	ds_bpermute_b32 v28, v51, v4
	ds_read_b128 v[0:3], v171 offset:8704
	ds_read_b128 v[18:21], v171 offset:32
	v_xor_b32_e32 v5, 8, v233
	v_cmp_lt_i32_e32 vcc, v5, v234
	s_mov_b32 s0, 0xc2ce8ed0
	s_waitcnt lgkmcnt(2)
	v_fmac_f32_e32 v28, v17, v33
	ds_bpermute_b32 v17, v42, v28
	v_cndmask_b32_e32 v22, v233, v5, vcc
	v_lshlrev_b32_e32 v29, 2, v22
	ds_read_b128 v[22:25], v171 offset:8736
	s_waitcnt lgkmcnt(3)
	v_mfma_f32_32x32x16_bf16 v[0:15], v[0:3], v[100:103], 0
	s_waitcnt lgkmcnt(1)
	v_add_f32_e32 v17, v28, v17
	ds_bpermute_b32 v30, v29, v27
	s_mov_b32 s1, 0x42b17218
	s_waitcnt lgkmcnt(0)
	v_add_f32_e32 v27, v27, v30
	s_waitcnt vmcnt(6)
	v_mfma_f32_32x32x16_bf16 v[84:99], v[18:21], v[104:107], v[84:99]
	ds_bpermute_b32 v18, v26, v17
	v_xor_b32_e32 v19, 16, v233
	v_cmp_lt_i32_e32 vcc, v19, v234
	s_waitcnt lgkmcnt(0)
	v_add_f32_e32 v17, v17, v18
	v_cndmask_b32_e32 v19, v233, v19, vcc
	v_lshlrev_b32_e32 v26, 2, v19
	ds_read_b128 v[18:21], v171 offset:64
	v_mfma_f32_32x32x16_bf16 v[0:15], v[22:25], v[104:107], v[0:15]
	ds_bpermute_b32 v22, v29, v17
	ds_bpermute_b32 v28, v26, v27
	s_waitcnt lgkmcnt(1)
	v_add_f32_e32 v17, v17, v22
	ds_read_b128 v[22:25], v171 offset:8768
	s_waitcnt lgkmcnt(1)
	v_add_f32_e32 v30, v27, v28
	s_waitcnt vmcnt(5)
	v_mfma_f32_32x32x16_bf16 v[84:99], v[18:21], v[108:111], v[84:99]
	ds_bpermute_b32 v18, v26, v17
	ds_read_b128 v[26:29], v171 offset:96
	v_xor_b32_e32 v19, 32, v233
	v_cmp_lt_i32_e32 vcc, v19, v234
	s_waitcnt lgkmcnt(1)
	v_add_f32_e32 v17, v17, v18
	v_cndmask_b32_e32 v19, v233, v19, vcc
	v_mfma_f32_32x32x16_bf16 v[0:15], v[22:25], v[108:111], v[0:15]
	ds_read_b128 v[20:23], v171 offset:8800
	v_lshlrev_b32_e32 v19, 2, v19
	ds_bpermute_b32 v31, v19, v30
	ds_bpermute_b32 v19, v19, v17
	v_mov_b32_e32 v24, s20
	s_waitcnt lgkmcnt(1)
	v_add_f32_e32 v18, v30, v31
	s_waitcnt vmcnt(4)
	v_mfma_f32_32x32x16_bf16 v[84:99], v[26:29], v[112:115], v[84:99]
	s_waitcnt lgkmcnt(0)
	v_add_f32_e32 v17, v17, v19
	v_mov_b32_e32 v19, s19
	ds_read_b32 v177, v19
	ds_read_b32 v178, v24
	s_add_i32 s19, s17, 0xffffff41
	v_cmp_ngt_f32_e64 s[40:41], s0, v18
	v_cmp_nlt_f32_e64 s[4:5], s1, v18
	v_cmp_ngt_f32_e32 vcc, s0, v17
	v_mfma_f32_32x32x16_bf16 v[0:15], v[20:23], v[112:115], v[0:15]
	v_cmp_nlt_f32_e64 s[0:1], s1, v17
	s_cmp_gt_u32 s19, 0xfffffea2
	s_cbranch_scc0 .LBB0_157
	v_lshlrev_b32_e32 v19, 2, v173
	v_sub_u32_e32 v19, v19, v160
	v_lshl_add_u32 v19, v19, 2, s20
	ds_read2_b32 v[20:21], v19 offset0:224 offset1:225
	s_waitcnt lgkmcnt(0)
	v_pk_add_f32 v[20:21], v[20:21], 0 op_sel_hi:[1,0]
	s_nop 0
	v_pk_add_f32 v[84:85], v[84:85], v[20:21]
	ds_read2_b32 v[20:21], v19 offset0:226 offset1:227
	s_waitcnt lgkmcnt(0)
	v_pk_add_f32 v[20:21], v[20:21], 0 op_sel_hi:[1,0]
	s_nop 0
	v_pk_add_f32 v[86:87], v[86:87], v[20:21]
	ds_read2_b32 v[20:21], v19 offset0:232 offset1:233
	s_waitcnt lgkmcnt(0)
	v_pk_add_f32 v[20:21], v[20:21], 0 op_sel_hi:[1,0]
	s_nop 0
	v_pk_add_f32 v[88:89], v[88:89], v[20:21]
	ds_read2_b32 v[20:21], v19 offset0:234 offset1:235
	s_waitcnt lgkmcnt(0)
	v_pk_add_f32 v[20:21], v[20:21], 0 op_sel_hi:[1,0]
	s_nop 0
	v_pk_add_f32 v[90:91], v[90:91], v[20:21]
	ds_read2_b32 v[20:21], v19 offset0:240 offset1:241
	s_waitcnt lgkmcnt(0)
	v_pk_add_f32 v[20:21], v[20:21], 0 op_sel_hi:[1,0]
	s_nop 0
	v_pk_add_f32 v[92:93], v[92:93], v[20:21]
	ds_read2_b32 v[20:21], v19 offset0:242 offset1:243
	s_waitcnt lgkmcnt(0)
	v_pk_add_f32 v[20:21], v[20:21], 0 op_sel_hi:[1,0]
	s_nop 0
	v_pk_add_f32 v[94:95], v[94:95], v[20:21]
	ds_read2_b32 v[20:21], v19 offset0:248 offset1:249
	s_waitcnt lgkmcnt(0)
	v_pk_add_f32 v[20:21], v[20:21], 0 op_sel_hi:[1,0]
	s_nop 0
	v_pk_add_f32 v[96:97], v[96:97], v[20:21]
	ds_read2_b32 v[20:21], v19 offset0:250 offset1:251
	s_waitcnt lgkmcnt(0)
	v_pk_add_f32 v[20:21], v[20:21], 0 op_sel_hi:[1,0]
	s_nop 0
	v_pk_add_f32 v[98:99], v[98:99], v[20:21]
	v_add_u32_e32 v20, 0x400, v19
	ds_read2_b32 v[20:21], v20 offset1:1
	s_waitcnt lgkmcnt(0)
	v_pk_add_f32 v[20:21], v[20:21], 0 op_sel_hi:[1,0]
	s_nop 0
	v_pk_add_f32 v[0:1], v[0:1], v[20:21]
	v_add_u32_e32 v20, 0x408, v19
	ds_read2_b32 v[20:21], v20 offset1:1
	s_waitcnt lgkmcnt(0)
	v_pk_add_f32 v[20:21], v[20:21], 0 op_sel_hi:[1,0]
	s_nop 0
	v_pk_add_f32 v[2:3], v[2:3], v[20:21]
	v_add_u32_e32 v20, 0x420, v19
	ds_read2_b32 v[20:21], v20 offset1:1
	s_waitcnt lgkmcnt(0)
	v_pk_add_f32 v[20:21], v[20:21], 0 op_sel_hi:[1,0]
	s_nop 0
	v_pk_add_f32 v[4:5], v[4:5], v[20:21]
	v_add_u32_e32 v20, 0x428, v19
	ds_read2_b32 v[20:21], v20 offset1:1
	s_waitcnt lgkmcnt(0)
	v_pk_add_f32 v[20:21], v[20:21], 0 op_sel_hi:[1,0]
	s_nop 0
	v_pk_add_f32 v[6:7], v[6:7], v[20:21]
	v_add_u32_e32 v20, 0x440, v19
	ds_read2_b32 v[20:21], v20 offset1:1
	s_waitcnt lgkmcnt(0)
	v_pk_add_f32 v[20:21], v[20:21], 0 op_sel_hi:[1,0]
	s_nop 0
	v_pk_add_f32 v[8:9], v[8:9], v[20:21]
	v_add_u32_e32 v20, 0x448, v19
	ds_read2_b32 v[20:21], v20 offset1:1
	s_waitcnt lgkmcnt(0)
	v_pk_add_f32 v[20:21], v[20:21], 0 op_sel_hi:[1,0]
	s_nop 0
	v_pk_add_f32 v[10:11], v[10:11], v[20:21]
	v_add_u32_e32 v20, 0x460, v19
	ds_read2_b32 v[20:21], v20 offset1:1
	v_add_u32_e32 v19, 0x468, v19
	s_waitcnt lgkmcnt(0)
	v_pk_add_f32 v[20:21], v[20:21], 0 op_sel_hi:[1,0]
	s_nop 0
	v_pk_add_f32 v[12:13], v[12:13], v[20:21]
	ds_read2_b32 v[20:21], v19 offset1:1
	s_waitcnt lgkmcnt(0)
	v_pk_add_f32 v[20:21], v[20:21], 0 op_sel_hi:[1,0]
	s_nop 0
	v_pk_add_f32 v[14:15], v[14:15], v[20:21]
	v_max_f32_e32 v19, v84, v0
	s_branch .LBB0_158

; template <int MODE, bool FROZEN = false>
; __device__ __forceinline__ bool attn_unit(LAS unsigned char* lds, const Params& p, int l, int ua, int ub) {
;     ...
;     for (int t = 0; t < NT; ++t) {
;         if (t + 2 < NT) {
; #pragma unroll
;             for (int i = 0; i < NKC; ++i) *(LAS u32x4*)(lds + kdst[i] + (t & 1) * KBUF) = kr[i];
;         }
;         if (t + 1 < NT) {
; #pragma unroll
;             for (int i = 0; i < NVC; ++i) { *(LAS u32x2*)(lds + vdst[i] + ((t + 1) & 1) * VBUF) = (u32x2){vr[i].x, vr[i].y}; *(LAS u32x2*)(lds + vdst[i] + ((t + 1) & 1) * VBUF + 16) = (u32x2){vr[i].z, vr[i].w}; }
;         }
;         {
;             const size_t advk = (size_t)min(t + 3, NT - 1) * 64 * NPROJ, advv = (size_t)min(t + 2, NT - 1) * 64;
; #pragma unroll
;             for (int i = 0; i < NKC; ++i) kr[i] = *(const u32x4*)(kvbase + advk + ksrc[i]);
; #pragma unroll
;             for (int i = 0; i < NVC; ++i) vr[i] = *(const u32x4*)(vtbase + advv + vsrc[i]);
;         }
;         f32x16 sA0 = sB0, sA1 = sB1;
;         const float c2 = cbB - m_run;
;         const LAS unsigned char* Vb = lds + OFF_V + (t & 1) * VBUF + vlane_off;
;         const LAS unsigned char* Kb = lds + OFF_K + ((t + 1) & 1) * KBUF + klane_off;
;     ...
;         bf16x8 kf0[4], kf1[4], va[NB], vb[NB], pf0, pf1; float ps0, ps1, ps2, ps3;
;         VLOAD(0, va);
;         EXPCVT(0, pf0, ps0);
;         SBAR_();
;         VLOAD(1, vb); PVMMA(va, pf0); EXPCVT(1, pf1, ps1); _Pragma("unroll") for (int g_ = 0; g_ < NB; ++g_) { __builtin_amdgcn_sched_group_barrier(0x008, 1, 0); __builtin_amdgcn_sched_group_barrier(0x100, 1, 0); __builtin_amdgcn_sched_group_barrier(0x400, 8 / NB, 0); __builtin_amdgcn_sched_group_barrier(0x002, 12 / NB, 0); } SBAR_();
;         VLOAD(2, va);
; #pragma unroll
;         for (int d0 = 0; d0 < 4; ++d0) { kf0[d0] = *(const LAS bf16x8*)(Kb + d0 * 32); kf1[d0] = *(const LAS bf16x8*)(Kb + 32 * KPB + d0 * 32); }
;         PVMMA(vb, pf1); EXPCVT(2, pf0, ps2); _Pragma("unroll") for (int g_ = 0; g_ < NB; ++g_) { __builtin_amdgcn_sched_group_barrier(0x008, 1, 0); __builtin_amdgcn_sched_group_barrier(0x100, 1, 0); __builtin_amdgcn_sched_group_barrier(0x400, 8 / NB, 0); __builtin_amdgcn_sched_group_barrier(0x002, 12 / NB, 0); } SBAR_();
;         {
;             f32x16 z0, z1;
; #pragma unroll
;             for (int r = 0; r < 16; ++r) { z0[r] = 0.f; z1[r] = 0.f; }
; #pragma unroll
.LBB0_160:
	s_add_i32 s20, s4, 1
	s_bitcmp1_b32 s20, 0
	s_cselect_b32 s5, 0x4800, 0
	s_cselect_b32 s21, 0x4400, 0
	s_add_i32 s5, s5, 0
	s_waitcnt vmcnt(3)
	v_add_u32_e32 v124, s5, v170
	v_add_u32_e32 v125, s5, v168
	s_min_i32 s5, s4, 0xfc
	s_mul_i32 s5, s5, 0x78000
	s_add_u32 s5, s34, s5
	s_addc_u32 s41, s35, 0
	s_add_u32 s40, s5, 0x168000
	s_addc_u32 s41, s41, 0
	s_min_i32 s4, s4, 0xfd
	v_add_u32_e32 v125, 0x8800, v125
	s_lshl_b32 s4, s4, 7
	s_waitcnt vmcnt(1)
	ds_write_b128 v125, v[116:119]
	v_add_u32_e32 v116, 0x8800, v124
	s_add_u32 s4, s6, s4
	s_waitcnt vmcnt(0)
	ds_write_b128 v116, v[120:123]
	v_lshl_add_u64 v[116:117], v[196:197], 1, s[40:41]
	s_addc_u32 s5, s7, 0
	v_lshl_add_u64 v[118:119], v[162:163], 1, s[40:41]
	global_load_dwordx4 v[124:127], v[116:117], off
	v_lshl_add_u64 v[116:117], v[164:165], 1, s[4:5]
	v_lshl_add_u64 v[120:121], v[166:167], 1, s[4:5]
	global_load_dwordx4 v[128:131], v[118:119], off
	v_sub_f32_e32 v156, v132, v182
	global_load_dwordx4 v[116:119], v[116:117], off offset:256
	v_add_f32_e32 v84, v84, v156
	global_load_dwordx4 v[120:123], v[120:121], off offset:256
	v_exp_f32_e32 v183, v84
	v_add_f32_e32 v84, v85, v156
	v_exp_f32_e32 v184, v84
	v_add_f32_e32 v84, v86, v156
	v_exp_f32_e32 v185, v84
	v_add_f32_e32 v84, v87, v156
	v_exp_f32_e32 v186, v84
	v_add_f32_e32 v84, v88, v156
	v_exp_f32_e32 v187, v84
	v_add_f32_e32 v84, v89, v156
	s_and_b64 s[0:1], s[0:1], exec
	v_exp_f32_e32 v188, v84
	v_add_f32_e32 v84, v90, v156
	s_cselect_b32 s0, 0x4800, 0
	v_exp_f32_e32 v189, v84
	v_add_f32_e32 v84, v91, v156
	v_add_u32_e32 v221, s0, v180
	v_exp_f32_e32 v190, v84
	ds_read_b128 v[134:137], v221 offset:34816
	ds_read_b128 v[138:141], v221 offset:39424
	ds_read_b128 v[142:145], v221 offset:44032
	ds_read_b128 v[146:149], v221 offset:48640
	v_cvt_pk_bf16_f32 v84, v183, v184
	v_cvt_pk_bf16_f32 v85, v185, v186
	v_cvt_pk_bf16_f32 v86, v187, v188
	v_cvt_pk_bf16_f32 v87, v189, v190
	s_waitcnt lgkmcnt(3)
	s_nop 0
	v_mfma_f32_32x32x16_bf16 v[52:67], v[134:137], v[84:87], v[52:67]
	ds_read_b128 v[88:91], v221 offset:34848
	v_add_f32_e32 v94, v94, v156
	v_exp_f32_e32 v203, v94
	v_add_f32_e32 v92, v92, v156
	v_exp_f32_e32 v195, v92
	v_add_f32_e32 v92, v95, v156
	v_exp_f32_e32 v204, v92
	v_add_f32_e32 v97, v97, v156
	v_add_f32_e32 v96, v96, v156
	v_add_f32_e32 v132, v99, v156
	s_waitcnt lgkmcnt(3)
	v_mfma_f32_32x32x16_bf16 v[68:83], v[138:141], v[84:87], v[68:83]
	s_waitcnt lgkmcnt(2)
	v_mfma_f32_32x32x16_bf16 v[36:51], v[142:145], v[84:87], v[36:51]
	s_waitcnt lgkmcnt(1)
	v_mfma_f32_32x32x16_bf16 v[16:31], v[146:149], v[84:87], v[16:31]
	ds_read_b128 v[84:87], v221 offset:48672
	v_exp_f32_e32 v191, v97
	v_exp_f32_e32 v192, v96
	v_add_f32_e32 v133, v98, v156
	v_add_u32_e32 v157, s21, v171
	ds_read_b128 v[96:99], v221 offset:39456
	v_exp_f32_e32 v193, v132
	v_exp_f32_e32 v194, v133
	v_add_f32_e32 v93, v93, v156
	v_cvt_pk_bf16_f32 v94, v192, v191
	ds_read_b128 v[140:143], v221 offset:44064
	v_exp_f32_e32 v202, v93
	v_cvt_pk_bf16_f32 v93, v203, v204
	v_cvt_pk_bf16_f32 v95, v194, v193
	v_cvt_pk_bf16_f32 v92, v195, v202
	s_waitcnt lgkmcnt(3)
	s_nop 0
	v_mfma_f32_32x32x16_bf16 v[52:67], v[88:91], v[92:95], v[52:67]
	ds_read_b128 v[132:135], v221 offset:34880
	v_add_f32_e32 v3, v3, v156
	v_exp_f32_e32 v212, v3
	v_add_f32_e32 v2, v2, v156
	v_exp_f32_e32 v211, v2
	v_add_f32_e32 v5, v5, v156
	v_add_f32_e32 v4, v4, v156
	v_add_f32_e32 v0, v0, v156
	s_waitcnt lgkmcnt(2)
	v_mfma_f32_32x32x16_bf16 v[68:83], v[96:99], v[92:95], v[68:83]
	ds_read_b128 v[136:139], v221 offset:39488
	v_exp_f32_e32 v205, v5
	v_exp_f32_e32 v206, v4
	v_add_f32_e32 v4, v7, v156
	v_add_f32_e32 v5, v6, v156
	v_add_f32_e32 v1, v1, v156
	ds_read_b128 v[88:91], v157 offset:8736
	s_waitcnt lgkmcnt(3)
	v_mfma_f32_32x32x16_bf16 v[36:51], v[140:143], v[92:95], v[36:51]
	ds_read_b128 v[140:143], v221 offset:44096
	v_exp_f32_e32 v207, v4
	v_exp_f32_e32 v208, v5
	v_cvt_pk_bf16_f32 v145, v211, v212
	ds_read_b128 v[96:99], v157 offset:8800
	ds_read_b128 v[222:225], v157 offset:32
	ds_read_b128 v[236:239], v157 offset:64
	v_mfma_f32_32x32x16_bf16 v[16:31], v[84:87], v[92:95], v[16:31]
	ds_read_b128 v[148:151], v221 offset:48704
	v_exp_f32_e32 v209, v0
	v_exp_f32_e32 v210, v1
	ds_read_b128 v[0:3], v157 offset:8704
	ds_read_b128 v[84:87], v157
	ds_read_b128 v[92:95], v157 offset:8768
	ds_read_b128 v[152:155], v157 offset:96
	v_cvt_pk_bf16_f32 v144, v209, v210
	v_cvt_pk_bf16_f32 v146, v206, v205
	v_cvt_pk_bf16_f32 v147, v208, v207
	v_add_f32_e32 v220, v14, v156
	v_exp_f32_e32 v220, v220
	v_add_f32_e32 v4, v15, v156
	v_add_f32_e32 v5, v9, v156
	v_exp_f32_e32 v213, v4
	v_add_f32_e32 v4, v8, v156
	v_add_f32_e32 v157, v11, v156
	v_exp_f32_e32 v214, v4
	v_add_f32_e32 v4, v10, v156
	v_add_f32_e32 v158, v12, v156
	v_exp_f32_e32 v215, v5
	v_add_f32_e32 v159, v13, v156
	v_exp_f32_e32 v216, v4
	s_waitcnt lgkmcnt(3)
	v_mfma_f32_32x32x16_bf16 v[0:15], v[0:3], v[100:103], 0
	v_mfma_f32_32x32x16_bf16 v[0:15], v[88:91], v[104:107], v[0:15]
	s_waitcnt lgkmcnt(1)
	v_mfma_f32_32x32x16_bf16 v[0:15], v[92:95], v[108:111], v[0:15]
	v_mfma_f32_32x32x16_bf16 v[0:15], v[96:99], v[112:115], v[0:15]
	v_mfma_f32_32x32x16_bf16 v[84:99], v[84:87], v[100:103], 0
	v_mfma_f32_32x32x16_bf16 v[84:99], v[222:225], v[104:107], v[84:99]
	v_mfma_f32_32x32x16_bf16 v[84:99], v[236:239], v[108:111], v[84:99]
	v_cvt_pk_bf16_f32 v156, v214, v215
	v_exp_f32_e32 v217, v157
	s_nop 0
	v_cvt_pk_bf16_f32 v157, v216, v217
	v_exp_f32_e32 v218, v158
	s_waitcnt lgkmcnt(0)
	v_mfma_f32_32x32x16_bf16 v[84:99], v[152:155], v[112:115], v[84:99]
	v_exp_f32_e32 v219, v159
	v_cvt_pk_bf16_f32 v159, v220, v213
	v_cvt_pk_bf16_f32 v158, v218, v219
	ds_read_b128 v[152:155], v221 offset:34912
	ds_read_b128 v[222:225], v221 offset:39520
	ds_read_b128 v[236:239], v221 offset:44128
	ds_read_b128 v[244:247], v221 offset:48736
	v_mfma_f32_32x32x16_bf16 v[52:67], v[132:135], v[144:147], v[52:67]
	s_cmpk_gt_i32 s18, 0x7f
	s_cselect_b64 s[0:1], -1, 0
	s_cmpk_gt_i32 s17, 0x7f
	s_cselect_b64 s[4:5], -1, 0
	s_or_b64 s[40:41], s[0:1], s[4:5]
	s_and_b64 vcc, exec, s[40:41]
	v_mfma_f32_32x32x16_bf16 v[68:83], v[136:139], v[144:147], v[68:83]
	v_mfma_f32_32x32x16_bf16 v[36:51], v[140:143], v[144:147], v[36:51]
	v_mfma_f32_32x32x16_bf16 v[16:31], v[148:151], v[144:147], v[16:31]
	s_waitcnt lgkmcnt(3)
	v_mfma_f32_32x32x16_bf16 v[52:67], v[152:155], v[156:159], v[52:67]
	s_waitcnt lgkmcnt(2)
	v_mfma_f32_32x32x16_bf16 v[68:83], v[222:225], v[156:159], v[68:83]
	s_waitcnt lgkmcnt(1)
	v_mfma_f32_32x32x16_bf16 v[36:51], v[236:239], v[156:159], v[36:51]
	s_waitcnt lgkmcnt(0)
	v_mfma_f32_32x32x16_bf16 v[16:31], v[244:247], v[156:159], v[16:31]
	s_cbranch_vccnz .LBB0_162
	v_add_u32_e32 v134, s19, v181
	v_add_u32_e32 v132, 0x11c80, v134
	ds_read2_b32 v[132:133], v132 offset1:1
	s_waitcnt lgkmcnt(0)
	v_pk_add_f32 v[132:133], v[132:133], 0 op_sel_hi:[1,0]
	s_nop 0
	v_pk_add_f32 v[84:85], v[84:85], v[132:133]
	v_add_u32_e32 v132, 0x11c88, v134
	ds_read2_b32 v[132:133], v132 offset1:1
	s_waitcnt lgkmcnt(0)
	v_pk_add_f32 v[132:133], v[132:133], 0 op_sel_hi:[1,0]
	s_nop 0
	v_pk_add_f32 v[86:87], v[86:87], v[132:133]
	v_add_u32_e32 v132, 0x11ca0, v134
	ds_read2_b32 v[132:133], v132 offset1:1
	s_waitcnt lgkmcnt(0)
	v_pk_add_f32 v[132:133], v[132:133], 0 op_sel_hi:[1,0]
	s_nop 0
	v_pk_add_f32 v[88:89], v[88:89], v[132:133]
	v_add_u32_e32 v132, 0x11ca8, v134
	ds_read2_b32 v[132:133], v132 offset1:1
	s_waitcnt lgkmcnt(0)
	v_pk_add_f32 v[132:133], v[132:133], 0 op_sel_hi:[1,0]
	s_nop 0
	v_pk_add_f32 v[90:91], v[90:91], v[132:133]
	v_add_u32_e32 v132, 0x11cc0, v134
	ds_read2_b32 v[132:133], v132 offset1:1
	s_waitcnt lgkmcnt(0)
	v_pk_add_f32 v[132:133], v[132:133], 0 op_sel_hi:[1,0]
	s_nop 0
	v_pk_add_f32 v[92:93], v[92:93], v[132:133]
	v_add_u32_e32 v132, 0x11cc8, v134
	ds_read2_b32 v[132:133], v132 offset1:1
	s_waitcnt lgkmcnt(0)
	v_pk_add_f32 v[132:133], v[132:133], 0 op_sel_hi:[1,0]
	s_nop 0
	v_pk_add_f32 v[94:95], v[94:95], v[132:133]
	v_add_u32_e32 v132, 0x11ce0, v134
	ds_read2_b32 v[132:133], v132 offset1:1
	s_waitcnt lgkmcnt(0)
	v_pk_add_f32 v[132:133], v[132:133], 0 op_sel_hi:[1,0]
	s_nop 0
	v_pk_add_f32 v[96:97], v[96:97], v[132:133]
	v_add_u32_e32 v132, 0x11ce8, v134
	ds_read2_b32 v[132:133], v132 offset1:1
	s_waitcnt lgkmcnt(0)
	v_pk_add_f32 v[132:133], v[132:133], 0 op_sel_hi:[1,0]
	s_nop 0
	v_pk_add_f32 v[98:99], v[98:99], v[132:133]
	v_add_u32_e32 v132, 0x11d00, v134
	ds_read2_b32 v[132:133], v132 offset1:1
	s_waitcnt lgkmcnt(0)
	v_pk_add_f32 v[132:133], v[132:133], 0 op_sel_hi:[1,0]
	s_nop 0
	v_pk_add_f32 v[0:1], v[0:1], v[132:133]
	v_add_u32_e32 v132, 0x11d08, v134
	ds_read2_b32 v[132:133], v132 offset1:1
	s_waitcnt lgkmcnt(0)
	v_pk_add_f32 v[132:133], v[132:133], 0 op_sel_hi:[1,0]
	s_nop 0
	v_pk_add_f32 v[2:3], v[2:3], v[132:133]
	v_add_u32_e32 v132, 0x11d20, v134
	ds_read2_b32 v[132:133], v132 offset1:1
	s_waitcnt lgkmcnt(0)
	v_pk_add_f32 v[132:133], v[132:133], 0 op_sel_hi:[1,0]
	s_nop 0
	v_pk_add_f32 v[4:5], v[4:5], v[132:133]
	v_add_u32_e32 v132, 0x11d28, v134
	ds_read2_b32 v[132:133], v132 offset1:1
	s_waitcnt lgkmcnt(0)
	v_pk_add_f32 v[132:133], v[132:133], 0 op_sel_hi:[1,0]
	s_nop 0
	v_pk_add_f32 v[6:7], v[6:7], v[132:133]
	v_add_u32_e32 v132, 0x11d40, v134
	ds_read2_b32 v[132:133], v132 offset1:1
	s_waitcnt lgkmcnt(0)
	v_pk_add_f32 v[132:133], v[132:133], 0 op_sel_hi:[1,0]
	s_nop 0
	v_pk_add_f32 v[8:9], v[8:9], v[132:133]
	v_add_u32_e32 v132, 0x11d48, v134
	ds_read2_b32 v[132:133], v132 offset1:1
	s_waitcnt lgkmcnt(0)
	v_pk_add_f32 v[132:133], v[132:133], 0 op_sel_hi:[1,0]
	s_nop 0
	v_pk_add_f32 v[10:11], v[10:11], v[132:133]
	v_add_u32_e32 v132, 0x11d60, v134
	ds_read2_b32 v[132:133], v132 offset1:1
	s_waitcnt lgkmcnt(0)
	v_pk_add_f32 v[132:133], v[132:133], 0 op_sel_hi:[1,0]
	s_nop 0
	v_pk_add_f32 v[12:13], v[12:13], v[132:133]
	v_add_u32_e32 v132, 0x11d68, v134
	ds_read2_b32 v[132:133], v132 offset1:1
	s_waitcnt lgkmcnt(0)
	v_pk_add_f32 v[132:133], v[132:133], 0 op_sel_hi:[1,0]
	s_nop 0
	v_pk_add_f32 v[14:15], v[14:15], v[132:133]
	v_max_f32_e32 v132, v84, v0
	v_max3_f32 v133, v1, v86, v2
	v_max3_f32 v132, v132, v85, v87
	v_max3_f32 v133, v133, v88, v4
	v_max3_f32 v132, v132, v3, v89
	v_max3_f32 v133, v133, v90, v6
	v_max3_f32 v132, v132, v5, v91
	v_max3_f32 v133, v133, v92, v8
	v_max3_f32 v132, v132, v7, v93
	v_max3_f32 v133, v133, v94, v10
	v_max3_f32 v132, v132, v9, v95
	v_max3_f32 v133, v133, v96, v12
	v_max3_f32 v132, v132, v11, v97
	v_max3_f32 v133, v133, v98, v14
	v_max3_f32 v132, v132, v13, v99
	s_branch .LBB0_163

; #define LAS __attribute__((address_space(3)))
; template <int MODE, bool FROZEN = false>
; __device__ __forceinline__ bool attn_unit(LAS unsigned char* lds, const Params& p, int l, int ua, int ub) {
;     ...
;     bf16x8 qf[4];
;     { const bf16_t* qp = proj + (size_t)(qtok0 + r32) * NPROJ + qcol + 8 * hi;
; #pragma unroll
;       for (int d0 = 0; d0 < 4; ++d0) qf[d0] = *(const bf16x8*)(qp + 16 * d0); }
;     f32x16 o[NB];
; #pragma unroll
;     for (int nb = 0; nb < NB; ++nb)
; #pragma unroll
;         for (int r = 0; r < 16; ++r) o[nb][r] = 0.f;
;     u32x4 kr[NKC], vr[NVC];
;     unsigned ksrc[NKC], vsrc[NVC]; int kdst[NKC], vdst[NVC];
;     const bf16_t* kvbase = proj + (size_t)kt0 * NPROJ;
; #pragma unroll
;     for (int i = 0; i < NKC; ++i) { const int cid = tid + 512 * i, row = cid / KCH, ch = cid % KCH; ksrc[i] = (unsigned)(row * NPROJ + kcol + ch * 8); kdst[i] = OFF_K + row * KPB + ch * 16; }
; #pragma unroll
;     for (int i = 0; i < NVC; ++i) { const int cid = tid + 512 * i, row = cid >> 3, ch = cid & 7; vsrc[i] = (unsigned)((vcol + row) * S + ch * 8); vdst[i] = OFF_V + row * VTP + (ch >> 1) * 32 + (ch & 1) * 8; }
;     const bf16_t* vtbase = vtg + kt0;
;     {
;         u32x4 k1[NKC];
; #pragma unroll
;         for (int i = 0; i < NKC; ++i) { kr[i] = *(const u32x4*)(kvbase + ksrc[i]); k1[i] = *(const u32x4*)(kvbase + (size_t)64 * NPROJ + ksrc[i]); }
; #pragma unroll
;         for (int i = 0; i < NVC; ++i) vr[i] = *(const u32x4*)(vtbase + vsrc[i]);
; #pragma unroll
;         for (int i = 0; i < NKC; ++i) { *(LAS u32x4*)(lds + kdst[i]) = kr[i]; *(LAS u32x4*)(lds + kdst[i] + KBUF) = k1[i]; }
; #pragma unroll
;         for (int i = 0; i < NVC; ++i) { *(LAS u32x2*)(lds + vdst[i]) = (u32x2){vr[i].x, vr[i].y}; *(LAS u32x2*)(lds + vdst[i] + 16) = (u32x2){vr[i].z, vr[i].w}; }
; #pragma unroll
;         for (int i = 0; i < NKC; ++i) kr[i] = *(const u32x4*)(kvbase + (size_t)2 * 64 * NPROJ + ksrc[i]);
; #pragma unroll
;         for (int i = 0; i < NVC; ++i) vr[i] = *(const u32x4*)(vtbase + 64 + vsrc[i]);
;     }
;     __syncthreads();
.LBB0_188:
	s_or_b64 exec, exec, s[0:1]
	s_ashr_i32 s0, s14, 1
	s_and_b32 s10, s0, -4
	s_ashr_i32 s11, s15, 7
	s_add_i32 s0, s11, s10
	s_lshr_b32 s4, s15, 1
	s_lshl_b32 s1, s0, 6
	s_and_b32 s4, s4, 32
	v_and_b32_e32 v35, 31, v0
	s_or_b32 s5, s1, s4
	s_max_i32 s13, s0, 4
	v_or_b32_e32 v124, s5, v35
	v_mov_b64_e32 v[2:3], s[34:35]
	s_movk_i32 s5, 0x1e00
	v_bfe_u32 v32, v0, 5, 1
	s_lshl_b32 s15, s8, 6
	s_max_i32 s12, s10, 4
	s_add_i32 s13, s13, -4
	v_mad_i64_i32 v[2:3], s[18:19], v124, s5, v[2:3]
	s_lshl_b32 s8, s8, 7
	v_ashrrev_i32_e32 v1, 31, v0
	s_add_i32 s1, s12, -4
	s_min_u32 s13, s13, 0xf8
	v_lshl_add_u64 v[2:3], v[2:3], 0, s[8:9]
	v_lshlrev_b32_e32 v196, 4, v32
	v_lshrrev_b32_e32 v1, 29, v1
	s_lshl_b32 s17, s1, 6
	s_sub_i32 s16, s13, s1
	v_lshl_add_u64 v[2:3], v[2:3], 0, v[196:197]
	s_mul_i32 s5, s1, 0x78000
	v_add_u32_e32 v1, v0, v1
	global_load_dwordx4 v[100:103], v[2:3], off
	global_load_dwordx4 v[104:107], v[2:3], off offset:32
	global_load_dwordx4 v[108:111], v[2:3], off offset:64
	global_load_dwordx4 v[112:115], v[2:3], off offset:96
	s_add_u32 s18, s34, s5
	v_ashrrev_i32_e32 v3, 3, v1
	v_and_b32_e32 v1, -8, v1
	s_movk_i32 s5, 0xf00
	v_sub_u32_e32 v1, v0, v1
	v_mul_lo_u32 v2, v3, s5
	v_add_u32_e32 v2, s15, v2
	v_lshlrev_b32_e32 v4, 3, v1
	s_movk_i32 s5, 0x200
	v_add3_u32 v2, v2, v4, s5
	s_movk_i32 s5, 0x90
	v_mul_lo_u32 v12, v3, s5
	v_lshlrev_b32_e32 v13, 4, v1
	v_ashrrev_i32_e32 v1, 3, v0
	v_and_b32_e32 v3, 7, v0
	s_mul_hi_u32 s8, s17, 0x1e00
	v_add_u32_e32 v4, s15, v1
	v_lshlrev_b32_e32 v3, 3, v3
	s_addc_u32 s19, s35, s8
	v_lshl_or_b32 v8, v4, 14, v3
	v_mul_lo_u32 v14, v1, s5
	s_lshl_b32 s5, s1, 7
	v_mov_b32_e32 v3, v197
	s_add_u32 s20, s6, s5
	v_lshl_add_u64 v[126:127], v[2:3], 1, s[18:19]
	s_mov_b32 s5, 0x78000
	v_lshlrev_b32_e32 v1, 4, v0
	v_lshlrev_b32_e32 v0, 3, v0
	v_add_co_u32_e32 v4, vcc, s5, v126
	v_and_b32_e32 v15, 0x60, v1
	v_and_b32_e32 v16, 16, v1
	global_load_dwordx4 v[0:3], v[126:127], off
	v_addc_co_u32_e32 v5, vcc, 0, v127, vcc
	s_addc_u32 s21, s7, 0
	global_load_dwordx4 v[4:7], v[4:5], off
	v_mov_b32_e32 v9, v197
	v_lshl_add_u64 v[128:129], v[8:9], 1, s[20:21]
	global_load_dwordx4 v[8:11], v[128:129], off
	v_add3_u32 v131, 0, v12, v13
	s_mov_b32 s5, 0xf0000
	v_mul_u32_u24_e32 v33, 0x90, v35
	v_add3_u32 v149, 0, v196, v33
	s_add_i32 s8, s16, 7
	s_cmp_lt_u32 s8, 8
	v_bitop3_b32 v68, s4, 63, v35 bitop3:0x36
	v_lshlrev_b32_e32 v130, 2, v32
	s_waitcnt vmcnt(0)
	ds_write_b128 v131, v[0:3]
	s_waitcnt vmcnt(1)
	ds_write_b128 v131, v[4:7] offset:9216
	v_add_u32_e32 v0, 0, v14
	v_add3_u32 v148, v0, v16, v15
	v_add_u32_e32 v0, 0x4800, v148
	s_waitcnt vmcnt(0)
	ds_write_b128 v0, v[8:11]
	v_add_co_u32_e32 v0, vcc, s5, v126
	s_nop 1
	v_addc_co_u32_e32 v1, vcc, 0, v127, vcc
	global_load_dwordx4 v[120:123], v[0:1], off
	global_load_dwordx4 v[116:119], v[128:129], off offset:128
	s_waitcnt lgkmcnt(0)
	s_barrier
	ds_read_b128 v[0:3], v149 offset:4608
	ds_read_b128 v[4:7], v149
	ds_read_b128 v[36:39], v149 offset:32
	ds_read_b128 v[40:43], v149 offset:4640
	s_waitcnt lgkmcnt(2)
	v_mfma_f32_32x32x16_bf16 v[16:31], v[4:7], v[100:103], 0
	v_mfma_f32_32x32x16_bf16 v[0:15], v[0:3], v[100:103], 0
	s_waitcnt lgkmcnt(1)
	v_mfma_f32_32x32x16_bf16 v[16:31], v[36:39], v[104:107], v[16:31]
	s_waitcnt lgkmcnt(0)
	v_mfma_f32_32x32x16_bf16 v[0:15], v[40:43], v[104:107], v[0:15]
	ds_read_b128 v[36:39], v149 offset:64
	ds_read_b128 v[40:43], v149 offset:4672
	s_waitcnt lgkmcnt(1)
	v_mfma_f32_32x32x16_bf16 v[16:31], v[36:39], v[108:111], v[16:31]
	s_waitcnt lgkmcnt(0)
	v_mfma_f32_32x32x16_bf16 v[0:15], v[40:43], v[108:111], v[0:15]
	ds_read_b128 v[36:39], v149 offset:96
	ds_read_b128 v[40:43], v149 offset:4704
	s_waitcnt lgkmcnt(1)
	v_mfma_f32_32x32x16_bf16 v[16:31], v[36:39], v[112:115], v[16:31]
	v_or_b32_e32 v36, s4, v35
	v_sub_u32_e64 v69, v36, 8 clamp
	s_waitcnt lgkmcnt(0)
	v_mfma_f32_32x32x16_bf16 v[0:15], v[40:43], v[112:115], v[0:15]
	s_cbranch_scc0 .LBB0_254
	s_sub_i32 s0, s1, s0
	s_max_i32 s0, s0, -7
	s_add_i32 s0, s0, 7
	s_min_u32 s0, s0, 14
	v_min_u32_e32 v36, 48, v69
	v_lshlrev_b32_e32 v37, 2, v32
	s_mulk_i32 s0, 0x1fc
	v_lshlrev_b32_e32 v35, 2, v68
	s_add_i32 s0, s0, 0
	v_sub_u32_e32 v51, v37, v36
	v_add3_u32 v35, s0, v35, v196
	v_cmp_gt_u32_e32 vcc, 16, v51
	v_mov_b32_e32 v36, 0xf149f2ca
	v_mov_b32_e32 v52, 0xf149f2ca
	s_and_saveexec_b64 s[0:1], vcc
	s_cbranch_execz .LBB0_191
	ds_read_b32 v37, v35 offset:36864
	s_waitcnt lgkmcnt(0)
	v_add_f32_e32 v52, v16, v37

; #define LAS __attribute__((address_space(3)))
; template <int MODE, bool FROZEN = false>
; __device__ __forceinline__ bool attn_unit(LAS unsigned char* lds, const Params& p, int l, int ua, int ub) {
;     ...
;         if (t + 1 < NT) {
; #pragma unroll
;             for (int i = 0; i < NVC; ++i) { *(LAS u32x2*)(lds + vdst[i] + ((t + 1) & 1) * VBUF) = (u32x2){vr[i].x, vr[i].y}; *(LAS u32x2*)(lds + vdst[i] + ((t + 1) & 1) * VBUF + 16) = (u32x2){vr[i].z, vr[i].w}; }
;         }
.LBB0_262:
	s_andn2_b64 vcc, exec, s[12:13]
	s_cbranch_vccnz .LBB0_264
	s_bitcmp1_b32 s20, 0
	s_cselect_b32 s22, 0x2400, 0
	v_add_u32_e32 v1, s22, v148
	v_add_u32_e32 v1, 0x4800, v1
	s_waitcnt vmcnt(0)
	ds_write_b128 v1, v[116:119]

; __device__ __forceinline__ float rstd_of(const float* ssq, int row) {
;     const f32x4* q = (const f32x4*)(ssq + (size_t)row * 16); const f32x4 a = q[0], b = q[1], c = q[2], d = q[3];
;     const float t = (((a.x + a.y) + (a.z + a.w)) + ((b.x + b.y) + (b.z + b.w))) + (((c.x + c.y) + (c.z + c.w)) + ((d.x + d.y) + (d.z + d.w)));
;     return 1.0f / sqrtf(t * (1.0f / DM) + 1e-6f); }
;     __device__ __forceinline__ void operator()(const pg8::f32x4 (&acc)[2][2][4][2], const pg8::Unit& u, int wr, int wc, int fr, int fq) const {
;         const int row0 = u.pm * 256 + wr * 64 + fr;
;         if (u.pn < 15) {
;             const float sc = ((u.pn % 6) < 2) ? QSCALE : 1.0f;
;             const int col0 = u.pn * 256 + wc * 32 + 8 * fq;
;             const bool vt_all = (u.pn == 4) | (u.pn == 5) | (u.pn == 10) | (u.pn == 11), vt_half = (u.pn == 14);
;             const int vrow0 = (u.pn <= 5 ? (u.pn - 4) * 256 : (u.pn <= 11 ? 512 + (u.pn - 10) * 256 : 1024 - 128)) + wc * 32 + 8 * fq;
; #pragma unroll
;             for (int ai = 0; ai < 2; ++ai)
; #pragma unroll
;                 for (int m = 0; m < 4; ++m) {
;                     const int row = row0 + ai * 128 + m * 16; const float rs = rstd_of(ssq, row) * sc;
.LBB0_345:
	v_lshl_add_u32 v158, s44, 8, v35
	v_lshrrev_b32_e32 v220, 2, v158
	v_lshrrev_b32_e32 v221, 3, v158
	v_xor_b32_e32 v220, v220, v221
	v_and_b32_e32 v220, 1, v220
	v_mul_u32_u24_e32 v220, 12, v220
	v_xor_b32_e32 v220, v158, v220
	v_mov_b32_e32 v221, 0
	v_mbcnt_lo_u32_b32 v210, -1, 0
	v_mbcnt_hi_u32_b32 v210, -1, v210
	v_lshrrev_b32_e32 v211, 4, v210
	v_and_b32_e32 v212, 1, v211
	v_lshrrev_b32_e32 v211, 1, v211
	v_lshlrev_b32_e32 v212, 5, v212
	v_lshl_add_u32 v212, v211, 7, v212
	v_add_u32_e32 v212, v212, v158
	v_mov_b32_e32 v213, 0
	v_lshlrev_b64 v[212:213], 6, v[212:213]
	v_lshl_add_u64 v[212:213], s[14:15], 0, v[212:213]
	global_load_dwordx4 v[132:135], v[212:213], off
	global_load_dwordx4 v[136:139], v[212:213], off offset:16
	global_load_dwordx4 v[140:143], v[212:213], off offset:32
	global_load_dwordx4 v[144:147], v[212:213], off offset:48
	global_load_dwordx4 v[174:177], v[212:213], off offset:1024
	global_load_dwordx4 v[178:181], v[212:213], off offset:1040
	global_load_dwordx4 v[182:185], v[212:213], off offset:1056
	global_load_dwordx4 v[186:189], v[212:213], off offset:1072
	v_and_b32_e32 v214, 15, v210
	v_lshlrev_b32_e32 v214, 2, v214
	v_add_u32_e32 v215, 64, v214
	v_add_u32_e32 v216, 0x80, v214
	v_add_u32_e32 v217, 0xc0, v214
	s_waitcnt vmcnt(4)
	v_add_f32_e32 v132, v132, v133
	v_add_f32_e32 v134, v134, v135
	v_add_f32_e32 v132, v132, v134
	v_add_f32_e32 v136, v136, v137
	v_add_f32_e32 v138, v138, v139
	v_add_f32_e32 v136, v136, v138
	v_add_f32_e32 v140, v140, v141
	v_add_f32_e32 v142, v142, v143
	v_add_f32_e32 v140, v140, v142
	v_add_f32_e32 v144, v144, v145
	v_add_f32_e32 v146, v146, v147
	v_add_f32_e32 v144, v144, v146
	v_add_f32_e32 v132, v132, v136
	v_add_f32_e32 v140, v140, v144
	v_add_f32_e32 v132, v132, v140
	v_fmamk_f32 v132, v132, 0x3a800000, v229
	v_cmp_gt_f32_e32 vcc, 0xf800000, v132
	v_mul_f32_e32 v137, 0x4f800000, v132
	s_nop 0
	v_cndmask_b32_e32 v132, v132, v137, vcc
	v_sqrt_f32_e32 v137, v132
	s_nop 0
	v_add_u32_e32 v138, -1, v137
	v_fma_f32 v139, -v138, v137, v132
	v_cmp_ge_f32_e64 s[100:101], 0, v139
	v_add_u32_e32 v139, 1, v137
	s_nop 0
	v_cndmask_b32_e64 v138, v137, v138, s[100:101]
	v_fma_f32 v137, -v139, v137, v132
	v_cmp_lt_f32_e64 s[100:101], 0, v137
	s_nop 1
	v_cndmask_b32_e64 v137, v138, v139, s[100:101]
	v_mul_f32_e32 v138, 0x37800000, v137
	v_cndmask_b32_e32 v137, v137, v138, vcc
	v_cmp_class_f32_e32 vcc, v132, v230
	s_nop 1
	v_cndmask_b32_e32 v132, v137, v132, vcc
	v_div_scale_f32 v137, s[100:101], v132, v132, 1.0
	v_rcp_f32_e32 v138, v137
	s_nop 0
	v_fma_f32 v139, -v137, v138, 1.0
	v_fmac_f32_e32 v138, v139, v138
	v_div_scale_f32 v139, vcc, 1.0, v132, 1.0
	v_mul_f32_e32 v141, v139, v138
	v_fma_f32 v142, -v137, v141, v139
	v_fmac_f32_e32 v141, v142, v138
	v_fma_f32 v137, -v137, v141, v139
	v_div_fmas_f32 v137, v137, v138, v141
	v_div_fixup_f32 v218, v137, v132, 1.0
	s_waitcnt vmcnt(0)
	v_add_f32_e32 v174, v174, v175
	v_add_f32_e32 v176, v176, v177
	v_add_f32_e32 v174, v174, v176
	v_add_f32_e32 v178, v178, v179
	v_add_f32_e32 v180, v180, v181
	v_add_f32_e32 v178, v178, v180
	v_add_f32_e32 v182, v182, v183
	v_add_f32_e32 v184, v184, v185
	v_add_f32_e32 v182, v182, v184
	v_add_f32_e32 v186, v186, v187
	v_add_f32_e32 v188, v188, v189
	v_add_f32_e32 v186, v186, v188
	v_add_f32_e32 v174, v174, v178
	v_add_f32_e32 v182, v182, v186
	v_add_f32_e32 v174, v174, v182
	v_fmamk_f32 v174, v174, 0x3a800000, v229
	v_cmp_gt_f32_e32 vcc, 0xf800000, v174
	v_mul_f32_e32 v179, 0x4f800000, v174
	s_nop 0
	v_cndmask_b32_e32 v174, v174, v179, vcc
	v_sqrt_f32_e32 v179, v174
	s_nop 0
	v_add_u32_e32 v180, -1, v179
	v_fma_f32 v181, -v180, v179, v174
	v_cmp_ge_f32_e64 s[100:101], 0, v181
	v_add_u32_e32 v181, 1, v179
	s_nop 0
	v_cndmask_b32_e64 v180, v179, v180, s[100:101]
	v_fma_f32 v179, -v181, v179, v174
	v_cmp_lt_f32_e64 s[100:101], 0, v179
	s_nop 1
	v_cndmask_b32_e64 v179, v180, v181, s[100:101]
	v_mul_f32_e32 v180, 0x37800000, v179
	v_cndmask_b32_e32 v179, v179, v180, vcc
	v_cmp_class_f32_e32 vcc, v174, v230
	s_nop 1
	v_cndmask_b32_e32 v174, v179, v174, vcc
	v_div_scale_f32 v179, s[100:101], v174, v174, 1.0
	v_rcp_f32_e32 v180, v179
	s_nop 0
	v_fma_f32 v181, -v179, v180, 1.0
	v_fmac_f32_e32 v180, v181, v180
	v_div_scale_f32 v181, vcc, 1.0, v174, 1.0
	v_mul_f32_e32 v183, v181, v180
	v_fma_f32 v184, -v179, v183, v181
	v_fmac_f32_e32 v183, v184, v180
	v_fma_f32 v179, -v179, v183, v181
	v_div_fmas_f32 v179, v179, v180, v183
	v_div_fixup_f32 v219, v179, v174, 1.0
	ds_bpermute_b32 v202, v214, v218
	ds_bpermute_b32 v203, v214, v219
	ds_bpermute_b32 v204, v215, v218
	ds_bpermute_b32 v205, v215, v219
	ds_bpermute_b32 v206, v216, v218
	ds_bpermute_b32 v207, v216, v219
	ds_bpermute_b32 v208, v217, v218
	ds_bpermute_b32 v209, v217, v219
	s_waitcnt lgkmcnt(0)
	v_or_b32_e32 v164, 16, v158
	v_or_b32_e32 v162, 32, v158
	s_mov_b64 s[0:1], -1
	s_cmp_gt_i32 s57, 14
	v_ashrrev_i32_e32 v159, 31, v158
	v_ashrrev_i32_e32 v165, 31, v164
	v_ashrrev_i32_e32 v163, 31, v162
	v_or_b32_e32 v160, 48, v158
	s_cbranch_scc0 .LBB0_347
; __device__ __forceinline__ unsigned pk2(float lo, float hi) { return pg8::cvt_pk_bf16(lo, hi); }
; __device__ __forceinline__ float fast_exp2(float x) { return __builtin_amdgcn_exp2f(x); }
; __device__ __forceinline__ float fast_rcp(float x) { return __builtin_amdgcn_rcpf(x); }
;     __device__ __forceinline__ void operator()(const pg8::f32x4 (&acc)[2][2][4][2], const pg8::Unit& u, int wr, int wc, int fr, int fq) const {
;     ...
;             const int col0 = (u.pn - 15) * 256 + wc * 32 + 8 * fq;
;             f32x4 bb[2][2];
; #pragma unroll
;             for (int bj = 0; bj < 2; ++bj) { bb[bj][0] = *(const f32x4*)(bg + col0 + bj * 128); bb[bj][1] = *(const f32x4*)(bg + col0 + bj * 128 + 4); }
; #pragma unroll
;             for (int ai = 0; ai < 2; ++ai)
; #pragma unroll
;                 for (int m = 0; m < 4; ++m) {
;                     const int row = row0 + ai * 128 + m * 16; const float rs = rstd_of(ssq, row);
; #pragma unroll
;                     for (int bj = 0; bj < 2; ++bj) {
;                         float v[8];
; #pragma unroll
;                         for (int j = 0; j < 4; ++j) { v[j] = fast_rcp(1.0f + fast_exp2(-(acc[ai][bj][m][0][j] * rs + bb[bj][0][j]) * LOG2E)); v[4 + j] = fast_rcp(1.0f + fast_exp2(-(acc[ai][bj][m][1][j] * rs + bb[bj][1][j]) * LOG2E)); }
;                         u32x4 w; w.x = pk2(v[0], v[1]); w.y = pk2(v[2], v[3]); w.z = pk2(v[4], v[5]); w.w = pk2(v[6], v[7]);
;                         *(u32x4*)(G + (size_t)row * NGATE + col0 + bj * 128) = w;
;                     }
	v_lshl_add_u32 v196, s57, 8, v172
	v_lshl_add_u64 v[132:133], v[196:197], 2, s[12:13]
	global_load_dwordx4 v[144:147], v[132:133], off
	global_load_dwordx4 v[140:143], v[132:133], off offset:16
	global_load_dwordx4 v[136:139], v[132:133], off offset:512
	s_nop 0
	global_load_dwordx4 v[132:135], v[132:133], off offset:528
	s_mov_b32 s4, 0xf800000
	v_readlane_b32 s0, v252, 4
	v_readlane_b32 s1, v252, 5
	s_waitcnt vmcnt(0)
	s_nop 0
	v_mov_b64_e32 v[166:167], s[0:1]
	v_mad_i64_i32 v[174:175], s[0:1], v158, s31, v[166:167]
	s_nop 1
	v_lshlrev_b64 v[168:169], 1, v[196:197]
	s_nop 1
	v_lshl_add_u64 v[178:179], v[174:175], 0, v[168:169]
	s_nop 0
	v_mov_b32_e32 v161, v202
	v_fma_f32 v174, v128, v161, v144
	v_fma_f32 v175, v124, v161, v140
	v_fma_f32 v176, v129, v161, v145
	v_fma_f32 v177, v125, v161, v141
	v_fma_f32 v180, v130, v161, v146
	v_fma_f32 v181, v126, v161, v142
	v_fma_f32 v182, v131, v161, v147
	v_fma_f32 v183, v127, v161, v143
	v_mul_f32_e32 v174, 0xbfb8aa3b, v174
	v_mul_f32_e32 v175, 0xbfb8aa3b, v175
	v_mul_f32_e32 v176, 0xbfb8aa3b, v176
	v_mul_f32_e32 v177, 0xbfb8aa3b, v177
	v_mul_f32_e32 v180, 0xbfb8aa3b, v180
	v_mul_f32_e32 v181, 0xbfb8aa3b, v181
	v_mul_f32_e32 v182, 0xbfb8aa3b, v182
	v_mul_f32_e32 v183, 0xbfb8aa3b, v183
	v_exp_f32_e32 v174, v174
	v_exp_f32_e32 v175, v175
	v_exp_f32_e32 v176, v176
	v_exp_f32_e32 v177, v177
	v_exp_f32_e32 v180, v180
	v_exp_f32_e32 v181, v181
	v_exp_f32_e32 v182, v182
	v_exp_f32_e32 v183, v183
	v_add_f32_e32 v174, 1.0, v174
	v_add_f32_e32 v175, 1.0, v175
	v_add_f32_e32 v176, 1.0, v176
	v_add_f32_e32 v177, 1.0, v177
	v_add_f32_e32 v180, 1.0, v180
	v_add_f32_e32 v181, 1.0, v181
	v_add_f32_e32 v182, 1.0, v182
	v_add_f32_e32 v183, 1.0, v183
	v_rcp_f32_e32 v174, v174
	v_rcp_f32_e32 v188, v175
	v_rcp_f32_e32 v175, v176
	v_rcp_f32_e32 v176, v177
	v_rcp_f32_e32 v177, v180
	v_rcp_f32_e32 v180, v181
	v_rcp_f32_e32 v181, v182
	v_rcp_f32_e32 v182, v183
	v_fma_f32 v187, v117, v161, v133
	v_cvt_pk_bf16_f32 v174, v174, v175
	v_cvt_pk_bf16_f32 v175, v177, v181
	v_cvt_pk_bf16_f32 v176, v188, v176
	v_cvt_pk_bf16_f32 v177, v180, v182
	v_mul_f32_e32 v187, 0xbfb8aa3b, v187
	global_store_dwordx4 v[178:179], v[174:177], off
	v_fma_f32 v180, v118, v161, v134
	v_mul_f32_e32 v180, 0xbfb8aa3b, v180
	v_fma_f32 v177, v122, v161, v138
	v_exp_f32_e32 v174, v187
	v_mul_f32_e32 v177, 0xbfb8aa3b, v177
	v_exp_f32_e32 v177, v177
	v_exp_f32_e32 v180, v180
	v_add_f32_e32 v174, 1.0, v174
	v_rcp_f32_e32 v181, v174
	v_add_f32_e32 v174, 1.0, v177
	v_fma_f32 v184, v120, v161, v136
	v_fma_f32 v185, v116, v161, v132
	v_fma_f32 v186, v121, v161, v137
	v_rcp_f32_e32 v177, v174
	v_add_f32_e32 v174, 1.0, v180
	v_fma_f32 v180, v123, v161, v139
	v_fma_f32 v161, v119, v161, v135
	v_mul_f32_e32 v184, 0xbfb8aa3b, v184
	v_mul_f32_e32 v185, 0xbfb8aa3b, v185
	v_mul_f32_e32 v186, 0xbfb8aa3b, v186
	v_mul_f32_e32 v180, 0xbfb8aa3b, v180
	v_mul_f32_e32 v161, 0xbfb8aa3b, v161
	v_exp_f32_e32 v184, v184
	v_exp_f32_e32 v185, v185
	v_exp_f32_e32 v186, v186
	v_exp_f32_e32 v180, v180
	v_exp_f32_e32 v161, v161
	v_add_f32_e32 v184, 1.0, v184
	v_add_f32_e32 v185, 1.0, v185
	v_add_f32_e32 v175, 1.0, v186
	v_rcp_f32_e32 v182, v174
	v_add_f32_e32 v174, 1.0, v180
	v_add_f32_e32 v161, 1.0, v161
	v_rcp_f32_e32 v183, v184
	v_rcp_f32_e32 v176, v185
	v_rcp_f32_e32 v175, v175
	v_rcp_f32_e32 v180, v174
	v_rcp_f32_e32 v161, v161
	v_cvt_pk_bf16_f32 v176, v176, v181
	v_cvt_pk_bf16_f32 v174, v183, v175
	v_cvt_pk_bf16_f32 v175, v177, v180
	v_cvt_pk_bf16_f32 v177, v182, v161
	global_store_dwordx4 v[178:179], v[174:177], off offset:256
	s_nop 1
	v_mov_b32_e32 v161, v203
	v_fma_f32 v175, v108, v161, v140
	v_fma_f32 v176, v113, v161, v145
	v_fma_f32 v177, v109, v161, v141
	v_fma_f32 v178, v114, v161, v146
	v_mul_f32_e32 v175, 0xbfb8aa3b, v175
	v_mul_f32_e32 v176, 0xbfb8aa3b, v176
	v_mul_f32_e32 v177, 0xbfb8aa3b, v177
	v_mul_f32_e32 v178, 0xbfb8aa3b, v178
	v_exp_f32_e32 v175, v175
	v_exp_f32_e32 v176, v176
	v_exp_f32_e32 v177, v177
	v_exp_f32_e32 v178, v178
	v_add_f32_e32 v175, 1.0, v175
	v_add_f32_e32 v176, 1.0, v176
	v_add_f32_e32 v177, 1.0, v177
	v_add_f32_e32 v178, 1.0, v178
	v_fma_f32 v174, v112, v161, v144
	v_fma_f32 v179, v110, v161, v142
	v_fma_f32 v180, v115, v161, v147
	v_rcp_f32_e32 v181, v175
	v_rcp_f32_e32 v175, v176
	v_rcp_f32_e32 v176, v177
	v_rcp_f32_e32 v177, v178
	v_fma_f32 v178, v111, v161, v143
	v_mul_f32_e32 v174, 0xbfb8aa3b, v174
	v_mul_f32_e32 v179, 0xbfb8aa3b, v179
	v_mul_f32_e32 v180, 0xbfb8aa3b, v180
	v_mul_f32_e32 v178, 0xbfb8aa3b, v178
	v_exp_f32_e32 v174, v174
	v_exp_f32_e32 v179, v179
	v_exp_f32_e32 v180, v180
	v_exp_f32_e32 v178, v178
	v_add_f32_e32 v174, 1.0, v174
	v_add_f32_e32 v179, 1.0, v179
	v_add_f32_e32 v180, 1.0, v180
	v_add_f32_e32 v178, 1.0, v178
	v_rcp_f32_e32 v174, v174
	v_rcp_f32_e32 v179, v179
	v_rcp_f32_e32 v180, v180
	v_rcp_f32_e32 v178, v178
	v_cvt_pk_bf16_f32 v174, v174, v175
	v_cvt_pk_bf16_f32 v176, v181, v176
	v_cvt_pk_bf16_f32 v175, v177, v180
	v_cvt_pk_bf16_f32 v177, v179, v178
	v_mad_i64_i32 v[178:179], s[0:1], v164, s31, v[166:167]
	v_lshl_add_u64 v[178:179], v[178:179], 0, v[168:169]
	v_fma_f32 v181, v100, v161, v132
	v_fma_f32 v180, v104, v161, v136
	v_mul_f32_e32 v181, 0xbfb8aa3b, v181
	global_store_dwordx4 v[178:179], v[174:177], off
	v_mul_f32_e32 v180, 0xbfb8aa3b, v180
	v_exp_f32_e32 v181, v181
	v_fma_f32 v176, v105, v161, v137
	v_fma_f32 v177, v101, v161, v133
	v_mul_f32_e32 v176, 0xbfb8aa3b, v176
	v_mul_f32_e32 v177, 0xbfb8aa3b, v177
	v_exp_f32_e32 v180, v180
	v_exp_f32_e32 v176, v176
	v_exp_f32_e32 v177, v177
	v_add_f32_e32 v175, 1.0, v181
	v_add_f32_e32 v174, 1.0, v180
	v_rcp_f32_e32 v180, v175
	v_add_f32_e32 v175, 1.0, v176
; __device__ __forceinline__ unsigned pk2(float lo, float hi) { return pg8::cvt_pk_bf16(lo, hi); }
; __device__ __forceinline__ float fast_exp2(float x) { return __builtin_amdgcn_exp2f(x); }
; __device__ __forceinline__ float fast_rcp(float x) { return __builtin_amdgcn_rcpf(x); }
;     __device__ __forceinline__ void operator()(const pg8::f32x4 (&acc)[2][2][4][2], const pg8::Unit& u, int wr, int wc, int fr, int fq) const {
;     ...
; #pragma unroll
;             for (int ai = 0; ai < 2; ++ai)
; #pragma unroll
;                 for (int m = 0; m < 4; ++m) {
;                     const int row = row0 + ai * 128 + m * 16; const float rs = rstd_of(ssq, row);
; #pragma unroll
;                     for (int bj = 0; bj < 2; ++bj) {
;                         float v[8];
; #pragma unroll
;                         for (int j = 0; j < 4; ++j) { v[j] = fast_rcp(1.0f + fast_exp2(-(acc[ai][bj][m][0][j] * rs + bb[bj][0][j]) * LOG2E)); v[4 + j] = fast_rcp(1.0f + fast_exp2(-(acc[ai][bj][m][1][j] * rs + bb[bj][1][j]) * LOG2E)); }
;                         u32x4 w; w.x = pk2(v[0], v[1]); w.y = pk2(v[2], v[3]); w.z = pk2(v[4], v[5]); w.w = pk2(v[6], v[7]);
;                         *(u32x4*)(G + (size_t)row * NGATE + col0 + bj * 128) = w;
;                     }
	v_add_f32_e32 v176, 1.0, v177
	v_fma_f32 v177, v106, v161, v138
	v_fma_f32 v181, v102, v161, v134
	v_fma_f32 v182, v107, v161, v139
	v_fma_f32 v161, v103, v161, v135
	v_mul_f32_e32 v177, 0xbfb8aa3b, v177
	v_mul_f32_e32 v181, 0xbfb8aa3b, v181
	v_mul_f32_e32 v182, 0xbfb8aa3b, v182
	v_mul_f32_e32 v161, 0xbfb8aa3b, v161
	v_exp_f32_e32 v177, v177
	v_exp_f32_e32 v181, v181
	v_exp_f32_e32 v182, v182
	v_exp_f32_e32 v161, v161
	v_add_f32_e32 v177, 1.0, v177
	v_add_f32_e32 v181, 1.0, v181
	v_add_f32_e32 v182, 1.0, v182
	v_add_f32_e32 v161, 1.0, v161
	v_rcp_f32_e32 v174, v174
	v_rcp_f32_e32 v175, v175
	v_rcp_f32_e32 v176, v176
	v_rcp_f32_e32 v177, v177
	v_rcp_f32_e32 v181, v181
	v_rcp_f32_e32 v182, v182
	v_rcp_f32_e32 v161, v161
	v_cvt_pk_bf16_f32 v174, v174, v175
	v_cvt_pk_bf16_f32 v176, v180, v176
	v_cvt_pk_bf16_f32 v175, v177, v182
	v_cvt_pk_bf16_f32 v177, v181, v161
	global_store_dwordx4 v[178:179], v[174:177], off offset:256
	s_nop 1
	v_mov_b32_e32 v161, v204
	v_fma_f32 v175, v92, v161, v140
	v_mul_f32_e32 v175, 0xbfb8aa3b, v175
	v_fma_f32 v176, v97, v161, v145
	v_fma_f32 v177, v93, v161, v141
	v_exp_f32_e32 v175, v175
	v_mul_f32_e32 v176, 0xbfb8aa3b, v176
	v_mul_f32_e32 v177, 0xbfb8aa3b, v177
	v_exp_f32_e32 v176, v176
	v_exp_f32_e32 v177, v177
	v_add_f32_e32 v175, 1.0, v175
	v_fma_f32 v174, v96, v161, v144
	v_rcp_f32_e32 v178, v175
	v_add_f32_e32 v175, 1.0, v176
	v_add_f32_e32 v176, 1.0, v177
	v_fma_f32 v177, v98, v161, v146
	v_fma_f32 v179, v94, v161, v142
	v_fma_f32 v180, v99, v161, v147
	v_fma_f32 v181, v95, v161, v143
	v_mul_f32_e32 v174, 0xbfb8aa3b, v174
	v_mul_f32_e32 v177, 0xbfb8aa3b, v177
	v_mul_f32_e32 v179, 0xbfb8aa3b, v179
	v_mul_f32_e32 v180, 0xbfb8aa3b, v180
	v_mul_f32_e32 v181, 0xbfb8aa3b, v181
	v_exp_f32_e32 v174, v174
	v_exp_f32_e32 v177, v177
	v_exp_f32_e32 v179, v179
	v_exp_f32_e32 v180, v180
	v_exp_f32_e32 v181, v181
	v_add_f32_e32 v174, 1.0, v174
	v_add_f32_e32 v177, 1.0, v177
	v_add_f32_e32 v179, 1.0, v179
	v_add_f32_e32 v180, 1.0, v180
	v_add_f32_e32 v181, 1.0, v181
	v_rcp_f32_e32 v174, v174
	v_rcp_f32_e32 v175, v175
	v_rcp_f32_e32 v176, v176
	v_rcp_f32_e32 v177, v177
	v_rcp_f32_e32 v179, v179
	v_rcp_f32_e32 v180, v180
	v_rcp_f32_e32 v181, v181
	v_cvt_pk_bf16_f32 v174, v174, v175
	v_cvt_pk_bf16_f32 v176, v178, v176
	v_cvt_pk_bf16_f32 v175, v177, v180
	v_cvt_pk_bf16_f32 v177, v179, v181
	v_mad_i64_i32 v[178:179], s[0:1], v162, s31, v[166:167]
	v_lshl_add_u64 v[178:179], v[178:179], 0, v[168:169]
	v_fma_f32 v181, v84, v161, v132
	v_fma_f32 v180, v88, v161, v136
	v_mul_f32_e32 v181, 0xbfb8aa3b, v181
	global_store_dwordx4 v[178:179], v[174:177], off
	v_mul_f32_e32 v180, 0xbfb8aa3b, v180
	v_exp_f32_e32 v181, v181
	v_fma_f32 v176, v89, v161, v137
	v_fma_f32 v177, v85, v161, v133
	v_mul_f32_e32 v176, 0xbfb8aa3b, v176
	v_mul_f32_e32 v177, 0xbfb8aa3b, v177
	v_exp_f32_e32 v180, v180
	v_exp_f32_e32 v176, v176
	v_exp_f32_e32 v177, v177
	v_add_f32_e32 v175, 1.0, v181
	v_add_f32_e32 v174, 1.0, v180
	v_rcp_f32_e32 v180, v175
	v_add_f32_e32 v175, 1.0, v176
	v_add_f32_e32 v176, 1.0, v177
	v_fma_f32 v177, v90, v161, v138
	v_fma_f32 v181, v86, v161, v134
	v_fma_f32 v182, v91, v161, v139
	v_fma_f32 v161, v87, v161, v135
	v_mul_f32_e32 v177, 0xbfb8aa3b, v177
	v_mul_f32_e32 v181, 0xbfb8aa3b, v181
	v_mul_f32_e32 v182, 0xbfb8aa3b, v182
	v_mul_f32_e32 v161, 0xbfb8aa3b, v161
	v_exp_f32_e32 v177, v177
	v_exp_f32_e32 v181, v181
	v_exp_f32_e32 v182, v182
	v_exp_f32_e32 v161, v161
	v_add_f32_e32 v177, 1.0, v177
	v_add_f32_e32 v181, 1.0, v181
	v_add_f32_e32 v182, 1.0, v182
	v_add_f32_e32 v161, 1.0, v161
	v_rcp_f32_e32 v174, v174
	v_rcp_f32_e32 v175, v175
	v_rcp_f32_e32 v176, v176
	v_rcp_f32_e32 v177, v177
	v_rcp_f32_e32 v181, v181
	v_rcp_f32_e32 v182, v182
	v_rcp_f32_e32 v161, v161
	v_cvt_pk_bf16_f32 v174, v174, v175
	v_cvt_pk_bf16_f32 v176, v180, v176
	v_cvt_pk_bf16_f32 v175, v177, v182
	v_cvt_pk_bf16_f32 v177, v181, v161
	global_store_dwordx4 v[178:179], v[174:177], off offset:256
	s_nop 1
	v_add_u32_e32 v190, 0x80, v158
	v_ashrrev_i32_e32 v191, 31, v190
	s_nop 1
	v_mov_b32_e32 v161, v205
	v_fma_f32 v175, v76, v161, v140
	v_mul_f32_e32 v175, 0xbfb8aa3b, v175
	v_fma_f32 v176, v81, v161, v145
	v_fma_f32 v177, v77, v161, v141
	v_exp_f32_e32 v175, v175
	v_mul_f32_e32 v176, 0xbfb8aa3b, v176
	v_mul_f32_e32 v177, 0xbfb8aa3b, v177
	v_exp_f32_e32 v176, v176
	v_exp_f32_e32 v177, v177
	v_add_f32_e32 v175, 1.0, v175
	v_fma_f32 v174, v80, v161, v144
	v_rcp_f32_e32 v178, v175
	v_add_f32_e32 v175, 1.0, v176
	v_add_f32_e32 v176, 1.0, v177
	v_fma_f32 v177, v82, v161, v146
	v_fma_f32 v179, v78, v161, v142
	v_fma_f32 v180, v83, v161, v147
	v_fma_f32 v181, v79, v161, v143
	v_mul_f32_e32 v174, 0xbfb8aa3b, v174
	v_mul_f32_e32 v177, 0xbfb8aa3b, v177
	v_mul_f32_e32 v179, 0xbfb8aa3b, v179
	v_mul_f32_e32 v180, 0xbfb8aa3b, v180
	v_mul_f32_e32 v181, 0xbfb8aa3b, v181
	v_exp_f32_e32 v174, v174
	v_exp_f32_e32 v177, v177
	v_exp_f32_e32 v179, v179
	v_exp_f32_e32 v180, v180
	v_exp_f32_e32 v181, v181
	v_add_f32_e32 v174, 1.0, v174
	v_add_f32_e32 v177, 1.0, v177
	v_add_f32_e32 v179, 1.0, v179
	v_add_f32_e32 v180, 1.0, v180
	v_add_f32_e32 v181, 1.0, v181
	v_rcp_f32_e32 v174, v174
	v_rcp_f32_e32 v175, v175
	v_rcp_f32_e32 v176, v176
	v_rcp_f32_e32 v177, v177
	v_rcp_f32_e32 v179, v179
	v_rcp_f32_e32 v180, v180
	v_rcp_f32_e32 v181, v181
	v_cvt_pk_bf16_f32 v174, v174, v175
	v_cvt_pk_bf16_f32 v176, v178, v176
	v_cvt_pk_bf16_f32 v175, v177, v180
	v_cvt_pk_bf16_f32 v177, v179, v181
	v_mad_i64_i32 v[178:179], s[0:1], v160, s31, v[166:167]
	v_lshl_add_u64 v[178:179], v[178:179], 0, v[168:169]
	v_fma_f32 v181, v68, v161, v132
	v_fma_f32 v180, v72, v161, v136
	v_mul_f32_e32 v181, 0xbfb8aa3b, v181
; __device__ __forceinline__ unsigned pk2(float lo, float hi) { return pg8::cvt_pk_bf16(lo, hi); }
; __device__ __forceinline__ float fast_exp2(float x) { return __builtin_amdgcn_exp2f(x); }
; __device__ __forceinline__ float fast_rcp(float x) { return __builtin_amdgcn_rcpf(x); }
;     __device__ __forceinline__ void operator()(const pg8::f32x4 (&acc)[2][2][4][2], const pg8::Unit& u, int wr, int wc, int fr, int fq) const {
;     ...
; #pragma unroll
;             for (int ai = 0; ai < 2; ++ai)
; #pragma unroll
;                 for (int m = 0; m < 4; ++m) {
;                     const int row = row0 + ai * 128 + m * 16; const float rs = rstd_of(ssq, row);
; #pragma unroll
;                     for (int bj = 0; bj < 2; ++bj) {
;                         float v[8];
; #pragma unroll
;                         for (int j = 0; j < 4; ++j) { v[j] = fast_rcp(1.0f + fast_exp2(-(acc[ai][bj][m][0][j] * rs + bb[bj][0][j]) * LOG2E)); v[4 + j] = fast_rcp(1.0f + fast_exp2(-(acc[ai][bj][m][1][j] * rs + bb[bj][1][j]) * LOG2E)); }
;                         u32x4 w; w.x = pk2(v[0], v[1]); w.y = pk2(v[2], v[3]); w.z = pk2(v[4], v[5]); w.w = pk2(v[6], v[7]);
;                         *(u32x4*)(G + (size_t)row * NGATE + col0 + bj * 128) = w;
;                     }
	global_store_dwordx4 v[178:179], v[174:177], off
	v_mul_f32_e32 v180, 0xbfb8aa3b, v180
	v_exp_f32_e32 v181, v181
	v_fma_f32 v176, v73, v161, v137
	v_fma_f32 v177, v69, v161, v133
	v_mul_f32_e32 v176, 0xbfb8aa3b, v176
	v_mul_f32_e32 v177, 0xbfb8aa3b, v177
	v_exp_f32_e32 v180, v180
	v_exp_f32_e32 v176, v176
	v_exp_f32_e32 v177, v177
	v_add_f32_e32 v175, 1.0, v181
	v_add_f32_e32 v174, 1.0, v180
	v_rcp_f32_e32 v180, v175
	v_add_f32_e32 v175, 1.0, v176
	v_add_f32_e32 v176, 1.0, v177
	v_fma_f32 v177, v74, v161, v138
	v_fma_f32 v181, v70, v161, v134
	v_fma_f32 v182, v75, v161, v139
	v_fma_f32 v161, v71, v161, v135
	v_mul_f32_e32 v177, 0xbfb8aa3b, v177
	v_mul_f32_e32 v181, 0xbfb8aa3b, v181
	v_mul_f32_e32 v182, 0xbfb8aa3b, v182
	v_mul_f32_e32 v161, 0xbfb8aa3b, v161
	v_exp_f32_e32 v177, v177
	v_exp_f32_e32 v181, v181
	v_exp_f32_e32 v182, v182
	v_exp_f32_e32 v161, v161
	v_add_f32_e32 v177, 1.0, v177
	v_add_f32_e32 v181, 1.0, v181
	v_add_f32_e32 v182, 1.0, v182
	v_add_f32_e32 v161, 1.0, v161
	v_rcp_f32_e32 v174, v174
	v_rcp_f32_e32 v175, v175
	v_rcp_f32_e32 v176, v176
	v_rcp_f32_e32 v177, v177
	v_rcp_f32_e32 v181, v181
	v_rcp_f32_e32 v182, v182
	v_rcp_f32_e32 v161, v161
	v_cvt_pk_bf16_f32 v174, v174, v175
	v_cvt_pk_bf16_f32 v176, v180, v176
	v_cvt_pk_bf16_f32 v175, v177, v182
	v_cvt_pk_bf16_f32 v177, v181, v161
	global_store_dwordx4 v[178:179], v[174:177], off offset:256
	s_nop 1
	v_mov_b32_e32 v161, v206
	v_fma_f32 v175, v60, v161, v140
	v_mul_f32_e32 v175, 0xbfb8aa3b, v175
	v_fma_f32 v176, v65, v161, v145
	v_fma_f32 v177, v61, v161, v141
	v_exp_f32_e32 v175, v175
	v_mul_f32_e32 v176, 0xbfb8aa3b, v176
	v_mul_f32_e32 v177, 0xbfb8aa3b, v177
	v_exp_f32_e32 v176, v176
	v_exp_f32_e32 v177, v177
	v_add_f32_e32 v175, 1.0, v175
	v_fma_f32 v174, v64, v161, v144
	v_rcp_f32_e32 v178, v175
	v_add_f32_e32 v175, 1.0, v176
	v_add_f32_e32 v176, 1.0, v177
	v_fma_f32 v177, v66, v161, v146
	v_fma_f32 v179, v62, v161, v142
	v_fma_f32 v180, v67, v161, v147
	v_fma_f32 v181, v63, v161, v143
	v_mul_f32_e32 v174, 0xbfb8aa3b, v174
	v_mul_f32_e32 v177, 0xbfb8aa3b, v177
	v_mul_f32_e32 v179, 0xbfb8aa3b, v179
	v_mul_f32_e32 v180, 0xbfb8aa3b, v180
	v_mul_f32_e32 v181, 0xbfb8aa3b, v181
	v_exp_f32_e32 v174, v174
	v_exp_f32_e32 v177, v177
	v_exp_f32_e32 v179, v179
	v_exp_f32_e32 v180, v180
	v_exp_f32_e32 v181, v181
	v_add_f32_e32 v174, 1.0, v174
	v_add_f32_e32 v177, 1.0, v177
	v_add_f32_e32 v179, 1.0, v179
	v_add_f32_e32 v180, 1.0, v180
	v_add_f32_e32 v181, 1.0, v181
	v_rcp_f32_e32 v174, v174
	v_rcp_f32_e32 v175, v175
	v_rcp_f32_e32 v176, v176
	v_rcp_f32_e32 v177, v177
	v_rcp_f32_e32 v179, v179
	v_rcp_f32_e32 v180, v180
	v_rcp_f32_e32 v181, v181
	v_cvt_pk_bf16_f32 v174, v174, v175
	v_cvt_pk_bf16_f32 v176, v178, v176
	v_cvt_pk_bf16_f32 v175, v177, v180
	v_cvt_pk_bf16_f32 v177, v179, v181
	v_mad_i64_i32 v[178:179], s[0:1], v190, s31, v[166:167]
	v_lshl_add_u64 v[178:179], v[178:179], 0, v[168:169]
	v_fma_f32 v181, v52, v161, v132
	v_fma_f32 v180, v56, v161, v136
	v_mul_f32_e32 v181, 0xbfb8aa3b, v181
	global_store_dwordx4 v[178:179], v[174:177], off
	v_mul_f32_e32 v180, 0xbfb8aa3b, v180
	v_exp_f32_e32 v181, v181
	v_fma_f32 v176, v57, v161, v137
	v_fma_f32 v177, v53, v161, v133
	v_mul_f32_e32 v176, 0xbfb8aa3b, v176
	v_mul_f32_e32 v177, 0xbfb8aa3b, v177
	v_exp_f32_e32 v180, v180
	v_exp_f32_e32 v176, v176
	v_exp_f32_e32 v177, v177
	v_add_f32_e32 v175, 1.0, v181
	v_add_f32_e32 v174, 1.0, v180
	v_rcp_f32_e32 v180, v175
	v_add_f32_e32 v175, 1.0, v176
	v_add_f32_e32 v176, 1.0, v177
	v_fma_f32 v177, v58, v161, v138
	v_fma_f32 v181, v54, v161, v134
	v_fma_f32 v182, v59, v161, v139
	v_fma_f32 v161, v55, v161, v135
	v_mul_f32_e32 v177, 0xbfb8aa3b, v177
	v_mul_f32_e32 v181, 0xbfb8aa3b, v181
	v_mul_f32_e32 v182, 0xbfb8aa3b, v182
	v_mul_f32_e32 v161, 0xbfb8aa3b, v161
	v_exp_f32_e32 v177, v177
	v_exp_f32_e32 v181, v181
	v_exp_f32_e32 v182, v182
	v_exp_f32_e32 v161, v161
	v_add_f32_e32 v177, 1.0, v177
	v_add_f32_e32 v181, 1.0, v181
	v_add_f32_e32 v182, 1.0, v182
	v_add_f32_e32 v161, 1.0, v161
	v_rcp_f32_e32 v174, v174
	v_rcp_f32_e32 v175, v175
	v_rcp_f32_e32 v176, v176
	v_rcp_f32_e32 v177, v177
	v_rcp_f32_e32 v181, v181
	v_rcp_f32_e32 v182, v182
	v_rcp_f32_e32 v161, v161
	v_add_u32_e32 v190, 0x90, v158
	v_cvt_pk_bf16_f32 v174, v174, v175
	v_cvt_pk_bf16_f32 v175, v177, v182
	v_cvt_pk_bf16_f32 v176, v180, v176
	v_cvt_pk_bf16_f32 v177, v181, v161
	global_store_dwordx4 v[178:179], v[174:177], off offset:256
	s_nop 1
	v_mov_b32_e32 v161, v207
	v_fma_f32 v175, v44, v161, v140
	v_mul_f32_e32 v175, 0xbfb8aa3b, v175
	v_fma_f32 v176, v49, v161, v145
	v_fma_f32 v177, v45, v161, v141
	v_exp_f32_e32 v175, v175
	v_mul_f32_e32 v176, 0xbfb8aa3b, v176
	v_mul_f32_e32 v177, 0xbfb8aa3b, v177
	v_exp_f32_e32 v176, v176
	v_exp_f32_e32 v177, v177
	v_add_f32_e32 v175, 1.0, v175
	v_fma_f32 v174, v48, v161, v144
	v_rcp_f32_e32 v178, v175
	v_add_f32_e32 v175, 1.0, v176
	v_add_f32_e32 v176, 1.0, v177
	v_fma_f32 v177, v50, v161, v146
	v_fma_f32 v179, v46, v161, v142
	v_fma_f32 v180, v51, v161, v147
	v_fma_f32 v181, v47, v161, v143
	v_mul_f32_e32 v174, 0xbfb8aa3b, v174
	v_mul_f32_e32 v177, 0xbfb8aa3b, v177
	v_mul_f32_e32 v179, 0xbfb8aa3b, v179
	v_mul_f32_e32 v180, 0xbfb8aa3b, v180
	v_mul_f32_e32 v181, 0xbfb8aa3b, v181
	v_exp_f32_e32 v174, v174
	v_exp_f32_e32 v177, v177
	v_exp_f32_e32 v179, v179
	v_exp_f32_e32 v180, v180
	v_exp_f32_e32 v181, v181
	v_add_f32_e32 v174, 1.0, v174
	v_add_f32_e32 v177, 1.0, v177
	v_add_f32_e32 v179, 1.0, v179
	v_add_f32_e32 v180, 1.0, v180
	v_add_f32_e32 v181, 1.0, v181
	v_rcp_f32_e32 v174, v174
	v_rcp_f32_e32 v175, v175
	v_rcp_f32_e32 v176, v176
	v_rcp_f32_e32 v177, v177
	v_rcp_f32_e32 v179, v179
; __device__ __forceinline__ unsigned pk2(float lo, float hi) { return pg8::cvt_pk_bf16(lo, hi); }
; __device__ __forceinline__ float fast_exp2(float x) { return __builtin_amdgcn_exp2f(x); }
; __device__ __forceinline__ float fast_rcp(float x) { return __builtin_amdgcn_rcpf(x); }
;     __device__ __forceinline__ void operator()(const pg8::f32x4 (&acc)[2][2][4][2], const pg8::Unit& u, int wr, int wc, int fr, int fq) const {
;     ...
; #pragma unroll
;             for (int ai = 0; ai < 2; ++ai)
; #pragma unroll
;                 for (int m = 0; m < 4; ++m) {
;                     const int row = row0 + ai * 128 + m * 16; const float rs = rstd_of(ssq, row);
; #pragma unroll
;                     for (int bj = 0; bj < 2; ++bj) {
;                         float v[8];
; #pragma unroll
;                         for (int j = 0; j < 4; ++j) { v[j] = fast_rcp(1.0f + fast_exp2(-(acc[ai][bj][m][0][j] * rs + bb[bj][0][j]) * LOG2E)); v[4 + j] = fast_rcp(1.0f + fast_exp2(-(acc[ai][bj][m][1][j] * rs + bb[bj][1][j]) * LOG2E)); }
;                         u32x4 w; w.x = pk2(v[0], v[1]); w.y = pk2(v[2], v[3]); w.z = pk2(v[4], v[5]); w.w = pk2(v[6], v[7]);
;                         *(u32x4*)(G + (size_t)row * NGATE + col0 + bj * 128) = w;
;                     }
	v_rcp_f32_e32 v180, v180
	v_rcp_f32_e32 v181, v181
	v_cvt_pk_bf16_f32 v174, v174, v175
	v_cvt_pk_bf16_f32 v176, v178, v176
	v_cvt_pk_bf16_f32 v175, v177, v180
	v_cvt_pk_bf16_f32 v177, v179, v181
	v_mad_i64_i32 v[178:179], s[0:1], v190, s31, v[166:167]
	v_lshl_add_u64 v[178:179], v[178:179], 0, v[168:169]
	v_fma_f32 v181, v36, v161, v132
	v_fma_f32 v180, v40, v161, v136
	v_mul_f32_e32 v181, 0xbfb8aa3b, v181
	global_store_dwordx4 v[178:179], v[174:177], off
	v_mul_f32_e32 v180, 0xbfb8aa3b, v180
	v_exp_f32_e32 v181, v181
	v_fma_f32 v176, v41, v161, v137
	v_fma_f32 v177, v37, v161, v133
	v_mul_f32_e32 v176, 0xbfb8aa3b, v176
	v_mul_f32_e32 v177, 0xbfb8aa3b, v177
	v_exp_f32_e32 v180, v180
	v_exp_f32_e32 v176, v176
	v_exp_f32_e32 v177, v177
	v_add_f32_e32 v175, 1.0, v181
	v_add_f32_e32 v174, 1.0, v180
	v_rcp_f32_e32 v180, v175
	v_add_f32_e32 v175, 1.0, v176
	v_add_f32_e32 v176, 1.0, v177
	v_fma_f32 v177, v42, v161, v138
	v_fma_f32 v181, v38, v161, v134
	v_fma_f32 v182, v43, v161, v139
	v_fma_f32 v161, v39, v161, v135
	v_mul_f32_e32 v177, 0xbfb8aa3b, v177
	v_mul_f32_e32 v181, 0xbfb8aa3b, v181
	v_mul_f32_e32 v182, 0xbfb8aa3b, v182
	v_mul_f32_e32 v161, 0xbfb8aa3b, v161
	v_exp_f32_e32 v177, v177
	v_exp_f32_e32 v181, v181
	v_exp_f32_e32 v182, v182
	v_exp_f32_e32 v161, v161
	v_add_f32_e32 v177, 1.0, v177
	v_add_f32_e32 v181, 1.0, v181
	v_add_f32_e32 v182, 1.0, v182
	v_add_f32_e32 v161, 1.0, v161
	v_rcp_f32_e32 v174, v174
	v_rcp_f32_e32 v175, v175
	v_rcp_f32_e32 v176, v176
	v_rcp_f32_e32 v177, v177
	v_rcp_f32_e32 v181, v181
	v_rcp_f32_e32 v182, v182
	v_rcp_f32_e32 v161, v161
	v_add_u32_e32 v190, 0xa0, v158
	v_cvt_pk_bf16_f32 v174, v174, v175
	v_cvt_pk_bf16_f32 v175, v177, v182
	v_cvt_pk_bf16_f32 v176, v180, v176
	v_cvt_pk_bf16_f32 v177, v181, v161
	global_store_dwordx4 v[178:179], v[174:177], off offset:256
	s_nop 1
	v_mov_b32_e32 v161, v208
	v_fma_f32 v175, v24, v161, v140
	v_mul_f32_e32 v175, 0xbfb8aa3b, v175
	v_fma_f32 v176, v29, v161, v145
	v_fma_f32 v177, v25, v161, v141
	v_exp_f32_e32 v175, v175
	v_mul_f32_e32 v176, 0xbfb8aa3b, v176
	v_mul_f32_e32 v177, 0xbfb8aa3b, v177
	v_exp_f32_e32 v176, v176
	v_exp_f32_e32 v177, v177
	v_add_f32_e32 v175, 1.0, v175
	v_fma_f32 v174, v28, v161, v144
	v_rcp_f32_e32 v178, v175
	v_add_f32_e32 v175, 1.0, v176
	v_add_f32_e32 v176, 1.0, v177
	v_fma_f32 v177, v30, v161, v146
	v_fma_f32 v179, v26, v161, v142
	v_fma_f32 v180, v31, v161, v147
	v_fma_f32 v181, v27, v161, v143
	v_mul_f32_e32 v174, 0xbfb8aa3b, v174
	v_mul_f32_e32 v177, 0xbfb8aa3b, v177
	v_mul_f32_e32 v179, 0xbfb8aa3b, v179
	v_mul_f32_e32 v180, 0xbfb8aa3b, v180
	v_mul_f32_e32 v181, 0xbfb8aa3b, v181
	v_exp_f32_e32 v174, v174
	v_exp_f32_e32 v177, v177
	v_exp_f32_e32 v179, v179
	v_exp_f32_e32 v180, v180
	v_exp_f32_e32 v181, v181
	v_add_f32_e32 v174, 1.0, v174
	v_add_f32_e32 v177, 1.0, v177
	v_add_f32_e32 v179, 1.0, v179
	v_add_f32_e32 v180, 1.0, v180
	v_add_f32_e32 v181, 1.0, v181
	v_rcp_f32_e32 v174, v174
	v_rcp_f32_e32 v175, v175
	v_rcp_f32_e32 v176, v176
	v_rcp_f32_e32 v177, v177
	v_rcp_f32_e32 v179, v179
	v_rcp_f32_e32 v180, v180
	v_rcp_f32_e32 v181, v181
	v_cvt_pk_bf16_f32 v174, v174, v175
	v_cvt_pk_bf16_f32 v176, v178, v176
	v_cvt_pk_bf16_f32 v175, v177, v180
	v_cvt_pk_bf16_f32 v177, v179, v181
	v_mad_i64_i32 v[178:179], s[0:1], v190, s31, v[166:167]
	v_lshl_add_u64 v[178:179], v[178:179], 0, v[168:169]
	v_fma_f32 v181, v16, v161, v132
	v_fma_f32 v180, v20, v161, v136
	v_mul_f32_e32 v181, 0xbfb8aa3b, v181
	global_store_dwordx4 v[178:179], v[174:177], off
	v_mul_f32_e32 v180, 0xbfb8aa3b, v180
	v_exp_f32_e32 v181, v181
	v_fma_f32 v176, v21, v161, v137
	v_fma_f32 v177, v17, v161, v133
	v_mul_f32_e32 v176, 0xbfb8aa3b, v176
	v_mul_f32_e32 v177, 0xbfb8aa3b, v177
	v_exp_f32_e32 v180, v180
	v_exp_f32_e32 v176, v176
	v_exp_f32_e32 v177, v177
	v_add_f32_e32 v175, 1.0, v181
	v_add_f32_e32 v174, 1.0, v180
	v_rcp_f32_e32 v180, v175
	v_add_f32_e32 v175, 1.0, v176
	v_add_f32_e32 v176, 1.0, v177
; __device__ __forceinline__ unsigned pk2(float lo, float hi) { return pg8::cvt_pk_bf16(lo, hi); }
; __device__ __forceinline__ float fast_exp2(float x) { return __builtin_amdgcn_exp2f(x); }
; __device__ __forceinline__ float fast_rcp(float x) { return __builtin_amdgcn_rcpf(x); }
;     __device__ __forceinline__ void operator()(const pg8::f32x4 (&acc)[2][2][4][2], const pg8::Unit& u, int wr, int wc, int fr, int fq) const {
;     ...
; #pragma unroll
;             for (int ai = 0; ai < 2; ++ai)
; #pragma unroll
;                 for (int m = 0; m < 4; ++m) {
;                     const int row = row0 + ai * 128 + m * 16; const float rs = rstd_of(ssq, row);
; #pragma unroll
;                     for (int bj = 0; bj < 2; ++bj) {
;                         float v[8];
; #pragma unroll
;                         for (int j = 0; j < 4; ++j) { v[j] = fast_rcp(1.0f + fast_exp2(-(acc[ai][bj][m][0][j] * rs + bb[bj][0][j]) * LOG2E)); v[4 + j] = fast_rcp(1.0f + fast_exp2(-(acc[ai][bj][m][1][j] * rs + bb[bj][1][j]) * LOG2E)); }
;                         u32x4 w; w.x = pk2(v[0], v[1]); w.y = pk2(v[2], v[3]); w.z = pk2(v[4], v[5]); w.w = pk2(v[6], v[7]);
;                         *(u32x4*)(G + (size_t)row * NGATE + col0 + bj * 128) = w;
;                     }
	v_fma_f32 v177, v22, v161, v138
	v_fma_f32 v181, v18, v161, v134
	v_fma_f32 v182, v23, v161, v139
	v_fma_f32 v161, v19, v161, v135
	v_mul_f32_e32 v177, 0xbfb8aa3b, v177
	v_mul_f32_e32 v181, 0xbfb8aa3b, v181
	v_mul_f32_e32 v182, 0xbfb8aa3b, v182
	v_mul_f32_e32 v161, 0xbfb8aa3b, v161
	v_exp_f32_e32 v177, v177
	v_exp_f32_e32 v181, v181
	v_exp_f32_e32 v182, v182
	v_exp_f32_e32 v161, v161
	v_add_f32_e32 v177, 1.0, v177
	v_add_f32_e32 v181, 1.0, v181
	v_add_f32_e32 v182, 1.0, v182
	v_add_f32_e32 v161, 1.0, v161
	v_rcp_f32_e32 v174, v174
	v_rcp_f32_e32 v175, v175
	v_rcp_f32_e32 v176, v176
	v_rcp_f32_e32 v177, v177
	v_rcp_f32_e32 v181, v181
	v_rcp_f32_e32 v182, v182
	v_rcp_f32_e32 v161, v161
	v_add_u32_e32 v190, 0xb0, v158
	v_cvt_pk_bf16_f32 v174, v174, v175
	v_cvt_pk_bf16_f32 v175, v177, v182
	v_cvt_pk_bf16_f32 v176, v180, v176
	v_cvt_pk_bf16_f32 v177, v181, v161
	global_store_dwordx4 v[178:179], v[174:177], off offset:256
	s_nop 1
	v_mov_b32_e32 v161, v209
	v_fma_f32 v140, v8, v161, v140
	v_mul_f32_e32 v140, 0xbfb8aa3b, v140
	v_fma_f32 v145, v13, v161, v145
	v_exp_f32_e32 v140, v140
	v_mul_f32_e32 v145, 0xbfb8aa3b, v145
	v_exp_f32_e32 v145, v145
	v_fma_f32 v141, v9, v161, v141
	v_add_f32_e32 v140, 1.0, v140
	v_mul_f32_e32 v141, 0xbfb8aa3b, v141
	v_rcp_f32_e32 v174, v140
	v_add_f32_e32 v140, 1.0, v145
	v_fma_f32 v145, v14, v161, v146
	v_exp_f32_e32 v141, v141
	v_mul_f32_e32 v145, 0xbfb8aa3b, v145
	v_exp_f32_e32 v145, v145
	v_fma_f32 v144, v12, v161, v144
	v_fma_f32 v142, v10, v161, v142
	v_mul_f32_e32 v144, 0xbfb8aa3b, v144
	v_add_f32_e32 v141, 1.0, v141
	v_mul_f32_e32 v142, 0xbfb8aa3b, v142
	v_fmac_f32_e32 v147, v15, v161
	v_fmac_f32_e32 v143, v11, v161
	v_exp_f32_e32 v144, v144
	v_exp_f32_e32 v142, v142
	v_rcp_f32_e32 v146, v141
	v_add_f32_e32 v141, 1.0, v145
	v_mul_f32_e32 v145, 0xbfb8aa3b, v147
	v_mul_f32_e32 v143, 0xbfb8aa3b, v143
	v_exp_f32_e32 v145, v145
	v_exp_f32_e32 v143, v143
	v_add_f32_e32 v144, 1.0, v144
	v_add_f32_e32 v142, 1.0, v142
	v_fma_f32 v132, v0, v161, v132
	v_rcp_f32_e32 v144, v144
	v_rcp_f32_e32 v140, v140
	v_rcp_f32_e32 v147, v142
	v_add_f32_e32 v142, 1.0, v145
	v_add_f32_e32 v143, 1.0, v143
	v_mul_f32_e32 v132, 0xbfb8aa3b, v132
	v_fma_f32 v137, v5, v161, v137
	v_rcp_f32_e32 v141, v141
	v_rcp_f32_e32 v142, v142
	v_rcp_f32_e32 v143, v143
	v_exp_f32_e32 v132, v132
	v_mul_f32_e32 v137, 0xbfb8aa3b, v137
	v_exp_f32_e32 v137, v137
	v_cvt_pk_bf16_f32 v140, v144, v140
	v_mad_i64_i32 v[144:145], s[0:1], v190, s31, v[166:167]
	v_cvt_pk_bf16_f32 v141, v141, v142
	v_cvt_pk_bf16_f32 v142, v174, v146
	v_cvt_pk_bf16_f32 v143, v147, v143
	v_lshl_add_u64 v[144:145], v[144:145], 0, v[168:169]
	v_add_f32_e32 v132, 1.0, v132
	v_fma_f32 v133, v1, v161, v133
	global_store_dwordx4 v[144:145], v[140:143], off
	v_mul_f32_e32 v133, 0xbfb8aa3b, v133
	v_exp_f32_e32 v133, v133
	v_rcp_f32_e32 v140, v132
	v_add_f32_e32 v132, 1.0, v137
	v_fma_f32 v137, v6, v161, v138
	v_mul_f32_e32 v137, 0xbfb8aa3b, v137
	v_exp_f32_e32 v137, v137
	v_fma_f32 v134, v2, v161, v134
	v_fma_f32 v136, v4, v161, v136
	v_add_f32_e32 v133, 1.0, v133
	v_mul_f32_e32 v134, 0xbfb8aa3b, v134
	v_fmac_f32_e32 v139, v7, v161
	v_fmac_f32_e32 v135, v3, v161
	v_mul_f32_e32 v136, 0xbfb8aa3b, v136
	v_exp_f32_e32 v134, v134
	v_rcp_f32_e32 v138, v133
	v_add_f32_e32 v133, 1.0, v137
	v_mul_f32_e32 v137, 0xbfb8aa3b, v139
	v_mul_f32_e32 v135, 0xbfb8aa3b, v135
	v_exp_f32_e32 v136, v136
	v_exp_f32_e32 v137, v137
	v_exp_f32_e32 v135, v135
	v_add_f32_e32 v134, 1.0, v134
	v_add_f32_e32 v136, 1.0, v136
	v_rcp_f32_e32 v139, v134
	v_add_f32_e32 v134, 1.0, v137
	v_add_f32_e32 v135, 1.0, v135
	v_rcp_f32_e32 v136, v136
	v_rcp_f32_e32 v132, v132
	v_rcp_f32_e32 v133, v133
	v_rcp_f32_e32 v134, v134
	v_rcp_f32_e32 v135, v135
	v_cvt_pk_bf16_f32 v132, v136, v132
	s_mov_b64 s[0:1], 0
	v_cvt_pk_bf16_f32 v133, v133, v134
	v_cvt_pk_bf16_f32 v134, v140, v138
	v_cvt_pk_bf16_f32 v135, v139, v135
	global_store_dwordx4 v[144:145], v[132:135], off offset:256

;     __device__ __forceinline__ void operator()(const pg8::f32x4 (&acc)[2][2][4][2], const pg8::Unit& u, int wr, int wc, int fr, int fq) const {
;     ...
;                         if (vt_all || (vt_half && bj == 1)) {
;                             bf16_t* vp = vt + (size_t)(vrow0 + bj * 128) * S + row;
;                             vp[0 * (size_t)S] = (bf16_t)(w.x & 0xffffu); vp[1 * (size_t)S] = (bf16_t)(w.x >> 16); vp[2 * (size_t)S] = (bf16_t)(w.y & 0xffffu); vp[3 * (size_t)S] = (bf16_t)(w.y >> 16);
;                             vp[4 * (size_t)S] = (bf16_t)(w.z & 0xffffu); vp[5 * (size_t)S] = (bf16_t)(w.z >> 16); vp[6 * (size_t)S] = (bf16_t)(w.w & 0xffffu); vp[7 * (size_t)S] = (bf16_t)(w.w >> 16);
.LBB0_354:
	v_or_b32_e32 v128, s21, v171
	s_andn2_b64 vcc, exec, s[4:5]
	v_ashrrev_i32_e32 v129, 31, v128
	s_cbranch_vccnz .LBB0_356
	v_lshlrev_b64 v[130:131], 15, v[128:129]
	v_lshl_add_u64 v[130:131], s[6:7], 0, v[130:131]
	v_lshl_add_u64 v[130:131], v[220:221], 1, v[130:131]
	v_add_co_u32_e32 v140, vcc, 0x8000, v130
	global_store_short v[130:131], v124, off
	s_nop 0
	v_addc_co_u32_e32 v141, vcc, 0, v131, vcc
	global_store_short_d16_hi v[140:141], v124, off
	v_add_co_u32_e32 v140, vcc, 0x10000, v130
	s_nop 1
	v_addc_co_u32_e32 v141, vcc, 0, v131, vcc
	global_store_short v[140:141], v125, off
	v_add_co_u32_e32 v140, vcc, 0x18000, v130
	s_nop 1
	v_addc_co_u32_e32 v141, vcc, 0, v131, vcc
	v_add_co_u32_e32 v124, vcc, 0x20000, v130
	global_store_short_d16_hi v[140:141], v125, off
	s_nop 0
	v_addc_co_u32_e32 v125, vcc, 0, v131, vcc
	global_store_short v[124:125], v126, off
	v_add_co_u32_e32 v124, vcc, 0x28000, v130
	s_nop 1
	v_addc_co_u32_e32 v125, vcc, 0, v131, vcc
	global_store_short_d16_hi v[124:125], v126, off
	v_add_co_u32_e32 v124, vcc, 0x30000, v130
	s_nop 1
	v_addc_co_u32_e32 v125, vcc, 0, v131, vcc
	global_store_short v[124:125], v127, off
	v_add_co_u32_e32 v124, vcc, 0x38000, v130
	s_nop 1
	v_addc_co_u32_e32 v125, vcc, 0, v131, vcc
	global_store_short_d16_hi v[124:125], v127, off

;     __device__ __forceinline__ void operator()(const pg8::f32x4 (&acc)[2][2][4][2], const pg8::Unit& u, int wr, int wc, int fr, int fq) const {
;     ...
;                         if (vt_all || (vt_half && bj == 1)) {
;                             bf16_t* vp = vt + (size_t)(vrow0 + bj * 128) * S + row;
;                             vp[0 * (size_t)S] = (bf16_t)(w.x & 0xffffu); vp[1 * (size_t)S] = (bf16_t)(w.x >> 16); vp[2 * (size_t)S] = (bf16_t)(w.y & 0xffffu); vp[3 * (size_t)S] = (bf16_t)(w.y >> 16);
;                             vp[4 * (size_t)S] = (bf16_t)(w.z & 0xffffu); vp[5 * (size_t)S] = (bf16_t)(w.z >> 16); vp[6 * (size_t)S] = (bf16_t)(w.w & 0xffffu); vp[7 * (size_t)S] = (bf16_t)(w.w >> 16);
.LBB0_363:
	s_and_b64 vcc, exec, s[0:1]
	s_cbranch_vccz .LBB0_365
	v_lshlrev_b64 v[120:121], 15, v[128:129]
	v_lshl_add_u64 v[120:121], s[6:7], 0, v[120:121]
	v_lshl_add_u64 v[120:121], v[220:221], 1, v[120:121]
	v_add_co_u32_e32 v122, vcc, 0x400000, v120
	s_nop 1
	v_addc_co_u32_e32 v123, vcc, 0, v121, vcc
	global_store_short v[122:123], v116, off
	v_add_co_u32_e32 v122, vcc, 0x408000, v120
	s_nop 1
	v_addc_co_u32_e32 v123, vcc, 0, v121, vcc
	global_store_short_d16_hi v[122:123], v116, off
	v_add_co_u32_e32 v122, vcc, 0x410000, v120
	s_nop 1
	v_addc_co_u32_e32 v123, vcc, 0, v121, vcc
	global_store_short v[122:123], v117, off
	v_add_co_u32_e32 v122, vcc, 0x418000, v120
	s_nop 1
	v_addc_co_u32_e32 v123, vcc, 0, v121, vcc
	v_add_co_u32_e32 v116, vcc, 0x420000, v120
	global_store_short_d16_hi v[122:123], v117, off
	s_nop 0
	v_addc_co_u32_e32 v117, vcc, 0, v121, vcc
	global_store_short v[116:117], v118, off
	v_add_co_u32_e32 v116, vcc, 0x428000, v120
	s_nop 1
	v_addc_co_u32_e32 v117, vcc, 0, v121, vcc
	global_store_short_d16_hi v[116:117], v118, off
	v_add_co_u32_e32 v116, vcc, 0x430000, v120
	s_nop 1
	v_addc_co_u32_e32 v117, vcc, 0, v121, vcc
	global_store_short v[116:117], v119, off
	v_add_co_u32_e32 v116, vcc, 0x438000, v120
	s_nop 1
	v_addc_co_u32_e32 v117, vcc, 0, v121, vcc
	global_store_short_d16_hi v[116:117], v119, off

;     __device__ __forceinline__ void operator()(const pg8::f32x4 (&acc)[2][2][4][2], const pg8::Unit& u, int wr, int wc, int fr, int fq) const {
;     ...
;                         if (vt_all || (vt_half && bj == 1)) {
;                             bf16_t* vp = vt + (size_t)(vrow0 + bj * 128) * S + row;
;                             vp[0 * (size_t)S] = (bf16_t)(w.x & 0xffffu); vp[1 * (size_t)S] = (bf16_t)(w.x >> 16); vp[2 * (size_t)S] = (bf16_t)(w.y & 0xffffu); vp[3 * (size_t)S] = (bf16_t)(w.y >> 16);
;                             vp[4 * (size_t)S] = (bf16_t)(w.z & 0xffffu); vp[5 * (size_t)S] = (bf16_t)(w.z >> 16); vp[6 * (size_t)S] = (bf16_t)(w.w & 0xffffu); vp[7 * (size_t)S] = (bf16_t)(w.w >> 16);
.LBB0_374:
	v_lshlrev_b64 v[112:113], 15, v[128:129]
	v_lshl_add_u64 v[112:113], s[6:7], 0, v[112:113]
	v_lshl_add_u64 v[112:113], v[220:221], 1, v[112:113]
	v_add_co_u32_e32 v114, vcc, 0x8000, v112
	global_store_short v[112:113], v108, off offset:32
	s_nop 0
	v_addc_co_u32_e32 v115, vcc, 0, v113, vcc
	global_store_short_d16_hi v[114:115], v108, off offset:32
	v_add_co_u32_e32 v114, vcc, 0x10000, v112
	s_nop 1
	v_addc_co_u32_e32 v115, vcc, 0, v113, vcc
	global_store_short v[114:115], v109, off offset:32
	v_add_co_u32_e32 v114, vcc, 0x18000, v112
	s_nop 1
	v_addc_co_u32_e32 v115, vcc, 0, v113, vcc
	v_add_co_u32_e32 v108, vcc, 0x20000, v112
	global_store_short_d16_hi v[114:115], v109, off offset:32
	s_nop 0
	v_addc_co_u32_e32 v109, vcc, 0, v113, vcc
	global_store_short v[108:109], v110, off offset:32
	v_add_co_u32_e32 v108, vcc, 0x28000, v112
	s_nop 1
	v_addc_co_u32_e32 v109, vcc, 0, v113, vcc
	global_store_short_d16_hi v[108:109], v110, off offset:32
	v_add_co_u32_e32 v108, vcc, 0x30000, v112
	s_nop 1
	v_addc_co_u32_e32 v109, vcc, 0, v113, vcc
	global_store_short v[108:109], v111, off offset:32
	v_add_co_u32_e32 v108, vcc, 0x38000, v112
	s_nop 1
	v_addc_co_u32_e32 v109, vcc, 0, v113, vcc
	global_store_short_d16_hi v[108:109], v111, off offset:32
	v_mov_b32_e32 v119, v118
	s_cmp_lt_i32 s57, 10
	s_cbranch_scc0 .LBB0_372

;     __device__ __forceinline__ void operator()(const pg8::f32x4 (&acc)[2][2][4][2], const pg8::Unit& u, int wr, int wc, int fr, int fq) const {
;     ...
;                         if (vt_all || (vt_half && bj == 1)) {
;                             bf16_t* vp = vt + (size_t)(vrow0 + bj * 128) * S + row;
;                             vp[0 * (size_t)S] = (bf16_t)(w.x & 0xffffu); vp[1 * (size_t)S] = (bf16_t)(w.x >> 16); vp[2 * (size_t)S] = (bf16_t)(w.y & 0xffffu); vp[3 * (size_t)S] = (bf16_t)(w.y >> 16);
;                             vp[4 * (size_t)S] = (bf16_t)(w.z & 0xffffu); vp[5 * (size_t)S] = (bf16_t)(w.z >> 16); vp[6 * (size_t)S] = (bf16_t)(w.w & 0xffffu); vp[7 * (size_t)S] = (bf16_t)(w.w >> 16);
.LBB0_380:
	s_and_b64 vcc, exec, s[0:1]
	s_cbranch_vccz .LBB0_382
	v_lshlrev_b64 v[104:105], 15, v[128:129]
	v_lshl_add_u64 v[104:105], s[6:7], 0, v[104:105]
	v_lshl_add_u64 v[104:105], v[220:221], 1, v[104:105]
	v_add_co_u32_e32 v106, vcc, 0x400000, v104
	s_nop 1
	v_addc_co_u32_e32 v107, vcc, 0, v105, vcc
	global_store_short v[106:107], v100, off offset:32
	v_add_co_u32_e32 v106, vcc, 0x408000, v104
	s_nop 1
	v_addc_co_u32_e32 v107, vcc, 0, v105, vcc
	global_store_short_d16_hi v[106:107], v100, off offset:32
	v_add_co_u32_e32 v106, vcc, 0x410000, v104
	s_nop 1
	v_addc_co_u32_e32 v107, vcc, 0, v105, vcc
	global_store_short v[106:107], v101, off offset:32
	v_add_co_u32_e32 v106, vcc, 0x418000, v104
	s_nop 1
	v_addc_co_u32_e32 v107, vcc, 0, v105, vcc
	v_add_co_u32_e32 v100, vcc, 0x420000, v104
	global_store_short_d16_hi v[106:107], v101, off offset:32
	s_nop 0
	v_addc_co_u32_e32 v101, vcc, 0, v105, vcc
	global_store_short v[100:101], v102, off offset:32
	v_add_co_u32_e32 v100, vcc, 0x428000, v104
	s_nop 1
	v_addc_co_u32_e32 v101, vcc, 0, v105, vcc
	global_store_short_d16_hi v[100:101], v102, off offset:32
	v_add_co_u32_e32 v100, vcc, 0x430000, v104
	s_nop 1
	v_addc_co_u32_e32 v101, vcc, 0, v105, vcc
	global_store_short v[100:101], v103, off offset:32
	v_add_co_u32_e32 v100, vcc, 0x438000, v104
	s_nop 1
	v_addc_co_u32_e32 v101, vcc, 0, v105, vcc
	global_store_short_d16_hi v[100:101], v103, off offset:32

;     __device__ __forceinline__ void operator()(const pg8::f32x4 (&acc)[2][2][4][2], const pg8::Unit& u, int wr, int wc, int fr, int fq) const {
;     ...
;                         if (vt_all || (vt_half && bj == 1)) {
;                             bf16_t* vp = vt + (size_t)(vrow0 + bj * 128) * S + row;
;                             vp[0 * (size_t)S] = (bf16_t)(w.x & 0xffffu); vp[1 * (size_t)S] = (bf16_t)(w.x >> 16); vp[2 * (size_t)S] = (bf16_t)(w.y & 0xffffu); vp[3 * (size_t)S] = (bf16_t)(w.y >> 16);
;                             vp[4 * (size_t)S] = (bf16_t)(w.z & 0xffffu); vp[5 * (size_t)S] = (bf16_t)(w.z >> 16); vp[6 * (size_t)S] = (bf16_t)(w.w & 0xffffu); vp[7 * (size_t)S] = (bf16_t)(w.w >> 16);
.LBB0_391:
	v_lshlrev_b64 v[96:97], 15, v[128:129]
	v_lshl_add_u64 v[96:97], s[6:7], 0, v[96:97]
	v_lshl_add_u64 v[96:97], v[220:221], 1, v[96:97]
	v_add_co_u32_e32 v98, vcc, 0x8000, v96
	global_store_short v[96:97], v92, off offset:64
	s_nop 0
	v_addc_co_u32_e32 v99, vcc, 0, v97, vcc
	global_store_short_d16_hi v[98:99], v92, off offset:64
	v_add_co_u32_e32 v98, vcc, 0x10000, v96
	s_nop 1
	v_addc_co_u32_e32 v99, vcc, 0, v97, vcc
	global_store_short v[98:99], v93, off offset:64
	v_add_co_u32_e32 v98, vcc, 0x18000, v96
	s_nop 1
	v_addc_co_u32_e32 v99, vcc, 0, v97, vcc
	v_add_co_u32_e32 v92, vcc, 0x20000, v96
	global_store_short_d16_hi v[98:99], v93, off offset:64
	s_nop 0
	v_addc_co_u32_e32 v93, vcc, 0, v97, vcc
	global_store_short v[92:93], v94, off offset:64
	v_add_co_u32_e32 v92, vcc, 0x28000, v96
	s_nop 1
	v_addc_co_u32_e32 v93, vcc, 0, v97, vcc
	global_store_short_d16_hi v[92:93], v94, off offset:64
	v_add_co_u32_e32 v92, vcc, 0x30000, v96
	s_nop 1
	v_addc_co_u32_e32 v93, vcc, 0, v97, vcc
	global_store_short v[92:93], v95, off offset:64
	v_add_co_u32_e32 v92, vcc, 0x38000, v96
	s_nop 1
	v_addc_co_u32_e32 v93, vcc, 0, v97, vcc
	global_store_short_d16_hi v[92:93], v95, off offset:64
	v_mov_b32_e32 v103, v102
	s_cmp_lt_i32 s57, 10
	s_cbranch_scc0 .LBB0_389

;     __device__ __forceinline__ void operator()(const pg8::f32x4 (&acc)[2][2][4][2], const pg8::Unit& u, int wr, int wc, int fr, int fq) const {
;     ...
;                         if (vt_all || (vt_half && bj == 1)) {
;                             bf16_t* vp = vt + (size_t)(vrow0 + bj * 128) * S + row;
;                             vp[0 * (size_t)S] = (bf16_t)(w.x & 0xffffu); vp[1 * (size_t)S] = (bf16_t)(w.x >> 16); vp[2 * (size_t)S] = (bf16_t)(w.y & 0xffffu); vp[3 * (size_t)S] = (bf16_t)(w.y >> 16);
;                             vp[4 * (size_t)S] = (bf16_t)(w.z & 0xffffu); vp[5 * (size_t)S] = (bf16_t)(w.z >> 16); vp[6 * (size_t)S] = (bf16_t)(w.w & 0xffffu); vp[7 * (size_t)S] = (bf16_t)(w.w >> 16);
.LBB0_397:
	s_and_b64 vcc, exec, s[0:1]
	s_cbranch_vccz .LBB0_399
	v_lshlrev_b64 v[88:89], 15, v[128:129]
	v_lshl_add_u64 v[88:89], s[6:7], 0, v[88:89]
	v_lshl_add_u64 v[88:89], v[220:221], 1, v[88:89]
	v_add_co_u32_e32 v90, vcc, 0x400000, v88
	s_nop 1
	v_addc_co_u32_e32 v91, vcc, 0, v89, vcc
	global_store_short v[90:91], v84, off offset:64
	v_add_co_u32_e32 v90, vcc, 0x408000, v88
	s_nop 1
	v_addc_co_u32_e32 v91, vcc, 0, v89, vcc
	global_store_short_d16_hi v[90:91], v84, off offset:64
	v_add_co_u32_e32 v90, vcc, 0x410000, v88
	s_nop 1
	v_addc_co_u32_e32 v91, vcc, 0, v89, vcc
	global_store_short v[90:91], v85, off offset:64
	v_add_co_u32_e32 v90, vcc, 0x418000, v88
	s_nop 1
	v_addc_co_u32_e32 v91, vcc, 0, v89, vcc
	v_add_co_u32_e32 v84, vcc, 0x420000, v88
	global_store_short_d16_hi v[90:91], v85, off offset:64
	s_nop 0
	v_addc_co_u32_e32 v85, vcc, 0, v89, vcc
	global_store_short v[84:85], v86, off offset:64
	v_add_co_u32_e32 v84, vcc, 0x428000, v88
	s_nop 1
	v_addc_co_u32_e32 v85, vcc, 0, v89, vcc
	global_store_short_d16_hi v[84:85], v86, off offset:64
	v_add_co_u32_e32 v84, vcc, 0x430000, v88
	s_nop 1
	v_addc_co_u32_e32 v85, vcc, 0, v89, vcc
	global_store_short v[84:85], v87, off offset:64
	v_add_co_u32_e32 v84, vcc, 0x438000, v88
	s_nop 1
	v_addc_co_u32_e32 v85, vcc, 0, v89, vcc
	global_store_short_d16_hi v[84:85], v87, off offset:64

;     __device__ __forceinline__ void operator()(const pg8::f32x4 (&acc)[2][2][4][2], const pg8::Unit& u, int wr, int wc, int fr, int fq) const {
;     ...
;                         if (vt_all || (vt_half && bj == 1)) {
;                             bf16_t* vp = vt + (size_t)(vrow0 + bj * 128) * S + row;
;                             vp[0 * (size_t)S] = (bf16_t)(w.x & 0xffffu); vp[1 * (size_t)S] = (bf16_t)(w.x >> 16); vp[2 * (size_t)S] = (bf16_t)(w.y & 0xffffu); vp[3 * (size_t)S] = (bf16_t)(w.y >> 16);
;                             vp[4 * (size_t)S] = (bf16_t)(w.z & 0xffffu); vp[5 * (size_t)S] = (bf16_t)(w.z >> 16); vp[6 * (size_t)S] = (bf16_t)(w.w & 0xffffu); vp[7 * (size_t)S] = (bf16_t)(w.w >> 16);
.LBB0_408:
	v_lshlrev_b64 v[80:81], 15, v[128:129]
	v_lshl_add_u64 v[80:81], s[6:7], 0, v[80:81]
	v_lshl_add_u64 v[80:81], v[220:221], 1, v[80:81]
	v_add_co_u32_e32 v82, vcc, 0x8000, v80
	global_store_short v[80:81], v76, off offset:96
	s_nop 0
	v_addc_co_u32_e32 v83, vcc, 0, v81, vcc
	global_store_short_d16_hi v[82:83], v76, off offset:96
	v_add_co_u32_e32 v82, vcc, 0x10000, v80
	s_nop 1
	v_addc_co_u32_e32 v83, vcc, 0, v81, vcc
	global_store_short v[82:83], v77, off offset:96
	v_add_co_u32_e32 v82, vcc, 0x18000, v80
	s_nop 1
	v_addc_co_u32_e32 v83, vcc, 0, v81, vcc
	v_add_co_u32_e32 v76, vcc, 0x20000, v80
	global_store_short_d16_hi v[82:83], v77, off offset:96
	s_nop 0
	v_addc_co_u32_e32 v77, vcc, 0, v81, vcc
	global_store_short v[76:77], v78, off offset:96
	v_add_co_u32_e32 v76, vcc, 0x28000, v80
	s_nop 1
	v_addc_co_u32_e32 v77, vcc, 0, v81, vcc
	global_store_short_d16_hi v[76:77], v78, off offset:96
	v_add_co_u32_e32 v76, vcc, 0x30000, v80
	s_nop 1
	v_addc_co_u32_e32 v77, vcc, 0, v81, vcc
	global_store_short v[76:77], v79, off offset:96
	v_add_co_u32_e32 v76, vcc, 0x38000, v80
	s_nop 1
	v_addc_co_u32_e32 v77, vcc, 0, v81, vcc
	global_store_short_d16_hi v[76:77], v79, off offset:96
	v_mov_b32_e32 v87, v86
	s_cmp_lt_i32 s57, 10
	s_cbranch_scc0 .LBB0_406

;     __device__ __forceinline__ void operator()(const pg8::f32x4 (&acc)[2][2][4][2], const pg8::Unit& u, int wr, int wc, int fr, int fq) const {
;     ...
;                         if (vt_all || (vt_half && bj == 1)) {
;                             bf16_t* vp = vt + (size_t)(vrow0 + bj * 128) * S + row;
;                             vp[0 * (size_t)S] = (bf16_t)(w.x & 0xffffu); vp[1 * (size_t)S] = (bf16_t)(w.x >> 16); vp[2 * (size_t)S] = (bf16_t)(w.y & 0xffffu); vp[3 * (size_t)S] = (bf16_t)(w.y >> 16);
;                             vp[4 * (size_t)S] = (bf16_t)(w.z & 0xffffu); vp[5 * (size_t)S] = (bf16_t)(w.z >> 16); vp[6 * (size_t)S] = (bf16_t)(w.w & 0xffffu); vp[7 * (size_t)S] = (bf16_t)(w.w >> 16);
.LBB0_414:
	s_and_b64 vcc, exec, s[0:1]
	s_cbranch_vccz .LBB0_416
	v_lshlrev_b64 v[72:73], 15, v[128:129]
	v_lshl_add_u64 v[72:73], s[6:7], 0, v[72:73]
	v_lshl_add_u64 v[72:73], v[220:221], 1, v[72:73]
	v_add_co_u32_e32 v74, vcc, 0x400000, v72
	s_nop 1
	v_addc_co_u32_e32 v75, vcc, 0, v73, vcc
	global_store_short v[74:75], v68, off offset:96
	v_add_co_u32_e32 v74, vcc, 0x408000, v72
	s_nop 1
	v_addc_co_u32_e32 v75, vcc, 0, v73, vcc
	global_store_short_d16_hi v[74:75], v68, off offset:96
	v_add_co_u32_e32 v74, vcc, 0x410000, v72
	s_nop 1
	v_addc_co_u32_e32 v75, vcc, 0, v73, vcc
	global_store_short v[74:75], v69, off offset:96
	v_add_co_u32_e32 v74, vcc, 0x418000, v72
	s_nop 1
	v_addc_co_u32_e32 v75, vcc, 0, v73, vcc
	v_add_co_u32_e32 v68, vcc, 0x420000, v72
	global_store_short_d16_hi v[74:75], v69, off offset:96
	s_nop 0
	v_addc_co_u32_e32 v69, vcc, 0, v73, vcc
	global_store_short v[68:69], v70, off offset:96
	v_add_co_u32_e32 v68, vcc, 0x428000, v72
	s_nop 1
	v_addc_co_u32_e32 v69, vcc, 0, v73, vcc
	global_store_short_d16_hi v[68:69], v70, off offset:96
	v_add_co_u32_e32 v68, vcc, 0x430000, v72
	s_nop 1
	v_addc_co_u32_e32 v69, vcc, 0, v73, vcc
	global_store_short v[68:69], v71, off offset:96
	v_add_co_u32_e32 v68, vcc, 0x438000, v72
	s_nop 1
	v_addc_co_u32_e32 v69, vcc, 0, v73, vcc
	global_store_short_d16_hi v[68:69], v71, off offset:96

;     __device__ __forceinline__ void operator()(const pg8::f32x4 (&acc)[2][2][4][2], const pg8::Unit& u, int wr, int wc, int fr, int fq) const {
;     ...
;                         if (vt_all || (vt_half && bj == 1)) {
;                             bf16_t* vp = vt + (size_t)(vrow0 + bj * 128) * S + row;
;                             vp[0 * (size_t)S] = (bf16_t)(w.x & 0xffffu); vp[1 * (size_t)S] = (bf16_t)(w.x >> 16); vp[2 * (size_t)S] = (bf16_t)(w.y & 0xffffu); vp[3 * (size_t)S] = (bf16_t)(w.y >> 16);
;                             vp[4 * (size_t)S] = (bf16_t)(w.z & 0xffffu); vp[5 * (size_t)S] = (bf16_t)(w.z >> 16); vp[6 * (size_t)S] = (bf16_t)(w.w & 0xffffu); vp[7 * (size_t)S] = (bf16_t)(w.w >> 16);
.LBB0_425:
	v_lshlrev_b64 v[64:65], 15, v[128:129]
	v_lshl_add_u64 v[64:65], s[6:7], 0, v[64:65]
	v_lshl_add_u64 v[64:65], v[220:221], 1, v[64:65]
	v_add_co_u32_e32 v66, vcc, 0x8000, v64
	global_store_short v[64:65], v60, off offset:256
	s_nop 0
	v_addc_co_u32_e32 v67, vcc, 0, v65, vcc
	global_store_short_d16_hi v[66:67], v60, off offset:256
	v_add_co_u32_e32 v66, vcc, 0x10000, v64
	s_nop 1
	v_addc_co_u32_e32 v67, vcc, 0, v65, vcc
	global_store_short v[66:67], v61, off offset:256
	v_add_co_u32_e32 v66, vcc, 0x18000, v64
	s_nop 1
	v_addc_co_u32_e32 v67, vcc, 0, v65, vcc
	v_add_co_u32_e32 v60, vcc, 0x20000, v64
	global_store_short_d16_hi v[66:67], v61, off offset:256
	s_nop 0
	v_addc_co_u32_e32 v61, vcc, 0, v65, vcc
	global_store_short v[60:61], v62, off offset:256
	v_add_co_u32_e32 v60, vcc, 0x28000, v64
	s_nop 1
	v_addc_co_u32_e32 v61, vcc, 0, v65, vcc
	global_store_short_d16_hi v[60:61], v62, off offset:256
	v_add_co_u32_e32 v60, vcc, 0x30000, v64
	s_nop 1
	v_addc_co_u32_e32 v61, vcc, 0, v65, vcc
	global_store_short v[60:61], v63, off offset:256
	v_add_co_u32_e32 v60, vcc, 0x38000, v64
	s_nop 1
	v_addc_co_u32_e32 v61, vcc, 0, v65, vcc
	global_store_short_d16_hi v[60:61], v63, off offset:256
	v_mov_b32_e32 v71, v70
	s_cmp_lt_i32 s57, 10
	s_cbranch_scc0 .LBB0_423

;     __device__ __forceinline__ void operator()(const pg8::f32x4 (&acc)[2][2][4][2], const pg8::Unit& u, int wr, int wc, int fr, int fq) const {
;     ...
;                         if (vt_all || (vt_half && bj == 1)) {
;                             bf16_t* vp = vt + (size_t)(vrow0 + bj * 128) * S + row;
;                             vp[0 * (size_t)S] = (bf16_t)(w.x & 0xffffu); vp[1 * (size_t)S] = (bf16_t)(w.x >> 16); vp[2 * (size_t)S] = (bf16_t)(w.y & 0xffffu); vp[3 * (size_t)S] = (bf16_t)(w.y >> 16);
;                             vp[4 * (size_t)S] = (bf16_t)(w.z & 0xffffu); vp[5 * (size_t)S] = (bf16_t)(w.z >> 16); vp[6 * (size_t)S] = (bf16_t)(w.w & 0xffffu); vp[7 * (size_t)S] = (bf16_t)(w.w >> 16);
.LBB0_431:
	s_and_b64 vcc, exec, s[0:1]
	s_cbranch_vccz .LBB0_433
	v_lshlrev_b64 v[56:57], 15, v[128:129]
	v_lshl_add_u64 v[56:57], s[6:7], 0, v[56:57]
	v_lshl_add_u64 v[56:57], v[220:221], 1, v[56:57]
	v_add_co_u32_e32 v58, vcc, 0x400000, v56
	s_nop 1
	v_addc_co_u32_e32 v59, vcc, 0, v57, vcc
	global_store_short v[58:59], v52, off offset:256
	v_add_co_u32_e32 v58, vcc, 0x408000, v56
	s_nop 1
	v_addc_co_u32_e32 v59, vcc, 0, v57, vcc
	global_store_short_d16_hi v[58:59], v52, off offset:256
	v_add_co_u32_e32 v58, vcc, 0x410000, v56
	s_nop 1
	v_addc_co_u32_e32 v59, vcc, 0, v57, vcc
	global_store_short v[58:59], v53, off offset:256
	v_add_co_u32_e32 v58, vcc, 0x418000, v56
	s_nop 1
	v_addc_co_u32_e32 v59, vcc, 0, v57, vcc
	v_add_co_u32_e32 v52, vcc, 0x420000, v56
	global_store_short_d16_hi v[58:59], v53, off offset:256
	s_nop 0
	v_addc_co_u32_e32 v53, vcc, 0, v57, vcc
	global_store_short v[52:53], v54, off offset:256
	v_add_co_u32_e32 v52, vcc, 0x428000, v56
	s_nop 1
	v_addc_co_u32_e32 v53, vcc, 0, v57, vcc
	global_store_short_d16_hi v[52:53], v54, off offset:256
	v_add_co_u32_e32 v52, vcc, 0x430000, v56
	s_nop 1
	v_addc_co_u32_e32 v53, vcc, 0, v57, vcc
	global_store_short v[52:53], v55, off offset:256
	v_add_co_u32_e32 v52, vcc, 0x438000, v56
	s_nop 1
	v_addc_co_u32_e32 v53, vcc, 0, v57, vcc
	global_store_short_d16_hi v[52:53], v55, off offset:256

;     __device__ __forceinline__ void operator()(const pg8::f32x4 (&acc)[2][2][4][2], const pg8::Unit& u, int wr, int wc, int fr, int fq) const {
;     ...
;                         if (vt_all || (vt_half && bj == 1)) {
;                             bf16_t* vp = vt + (size_t)(vrow0 + bj * 128) * S + row;
;                             vp[0 * (size_t)S] = (bf16_t)(w.x & 0xffffu); vp[1 * (size_t)S] = (bf16_t)(w.x >> 16); vp[2 * (size_t)S] = (bf16_t)(w.y & 0xffffu); vp[3 * (size_t)S] = (bf16_t)(w.y >> 16);
;                             vp[4 * (size_t)S] = (bf16_t)(w.z & 0xffffu); vp[5 * (size_t)S] = (bf16_t)(w.z >> 16); vp[6 * (size_t)S] = (bf16_t)(w.w & 0xffffu); vp[7 * (size_t)S] = (bf16_t)(w.w >> 16);
.LBB0_442:
	v_lshlrev_b64 v[48:49], 15, v[128:129]
	v_lshl_add_u64 v[48:49], s[6:7], 0, v[48:49]
	v_lshl_add_u64 v[48:49], v[220:221], 1, v[48:49]
	v_add_co_u32_e32 v50, vcc, 0x8000, v48
	global_store_short v[48:49], v44, off offset:288
	s_nop 0
	v_addc_co_u32_e32 v51, vcc, 0, v49, vcc
	global_store_short_d16_hi v[50:51], v44, off offset:288
	v_add_co_u32_e32 v50, vcc, 0x10000, v48
	s_nop 1
	v_addc_co_u32_e32 v51, vcc, 0, v49, vcc
	global_store_short v[50:51], v45, off offset:288
	v_add_co_u32_e32 v50, vcc, 0x18000, v48
	s_nop 1
	v_addc_co_u32_e32 v51, vcc, 0, v49, vcc
	v_add_co_u32_e32 v44, vcc, 0x20000, v48
	global_store_short_d16_hi v[50:51], v45, off offset:288
	s_nop 0
	v_addc_co_u32_e32 v45, vcc, 0, v49, vcc
	global_store_short v[44:45], v46, off offset:288
	v_add_co_u32_e32 v44, vcc, 0x28000, v48
	s_nop 1
	v_addc_co_u32_e32 v45, vcc, 0, v49, vcc
	global_store_short_d16_hi v[44:45], v46, off offset:288
	v_add_co_u32_e32 v44, vcc, 0x30000, v48
	s_nop 1
	v_addc_co_u32_e32 v45, vcc, 0, v49, vcc
	global_store_short v[44:45], v47, off offset:288
	v_add_co_u32_e32 v44, vcc, 0x38000, v48
	s_nop 1
	v_addc_co_u32_e32 v45, vcc, 0, v49, vcc
	global_store_short_d16_hi v[44:45], v47, off offset:288
	v_mov_b32_e32 v55, v54
	s_cmp_lt_i32 s57, 10
	s_cbranch_scc0 .LBB0_440

;     __device__ __forceinline__ void operator()(const pg8::f32x4 (&acc)[2][2][4][2], const pg8::Unit& u, int wr, int wc, int fr, int fq) const {
;     ...
;                         if (vt_all || (vt_half && bj == 1)) {
;                             bf16_t* vp = vt + (size_t)(vrow0 + bj * 128) * S + row;
;                             vp[0 * (size_t)S] = (bf16_t)(w.x & 0xffffu); vp[1 * (size_t)S] = (bf16_t)(w.x >> 16); vp[2 * (size_t)S] = (bf16_t)(w.y & 0xffffu); vp[3 * (size_t)S] = (bf16_t)(w.y >> 16);
;                             vp[4 * (size_t)S] = (bf16_t)(w.z & 0xffffu); vp[5 * (size_t)S] = (bf16_t)(w.z >> 16); vp[6 * (size_t)S] = (bf16_t)(w.w & 0xffffu); vp[7 * (size_t)S] = (bf16_t)(w.w >> 16);
.LBB0_448:
	s_and_b64 vcc, exec, s[0:1]
	s_cbranch_vccz .LBB0_450
	v_lshlrev_b64 v[40:41], 15, v[128:129]
	v_lshl_add_u64 v[40:41], s[6:7], 0, v[40:41]
	v_lshl_add_u64 v[40:41], v[220:221], 1, v[40:41]
	v_add_co_u32_e32 v42, vcc, 0x400000, v40
	s_nop 1
	v_addc_co_u32_e32 v43, vcc, 0, v41, vcc
	global_store_short v[42:43], v36, off offset:288
	v_add_co_u32_e32 v42, vcc, 0x408000, v40
	s_nop 1
	v_addc_co_u32_e32 v43, vcc, 0, v41, vcc
	global_store_short_d16_hi v[42:43], v36, off offset:288
	v_add_co_u32_e32 v42, vcc, 0x410000, v40
	s_nop 1
	v_addc_co_u32_e32 v43, vcc, 0, v41, vcc
	global_store_short v[42:43], v37, off offset:288
	v_add_co_u32_e32 v42, vcc, 0x418000, v40
	s_nop 1
	v_addc_co_u32_e32 v43, vcc, 0, v41, vcc
	v_add_co_u32_e32 v36, vcc, 0x420000, v40
	global_store_short_d16_hi v[42:43], v37, off offset:288
	s_nop 0
	v_addc_co_u32_e32 v37, vcc, 0, v41, vcc
	global_store_short v[36:37], v38, off offset:288
	v_add_co_u32_e32 v36, vcc, 0x428000, v40
	s_nop 1
	v_addc_co_u32_e32 v37, vcc, 0, v41, vcc
	global_store_short_d16_hi v[36:37], v38, off offset:288
	v_add_co_u32_e32 v36, vcc, 0x430000, v40
	s_nop 1
	v_addc_co_u32_e32 v37, vcc, 0, v41, vcc
	global_store_short v[36:37], v39, off offset:288
	v_add_co_u32_e32 v36, vcc, 0x438000, v40
	s_nop 1
	v_addc_co_u32_e32 v37, vcc, 0, v41, vcc
	global_store_short_d16_hi v[36:37], v39, off offset:288

;     __device__ __forceinline__ void operator()(const pg8::f32x4 (&acc)[2][2][4][2], const pg8::Unit& u, int wr, int wc, int fr, int fq) const {
;     ...
;                         if (vt_all || (vt_half && bj == 1)) {
;                             bf16_t* vp = vt + (size_t)(vrow0 + bj * 128) * S + row;
;                             vp[0 * (size_t)S] = (bf16_t)(w.x & 0xffffu); vp[1 * (size_t)S] = (bf16_t)(w.x >> 16); vp[2 * (size_t)S] = (bf16_t)(w.y & 0xffffu); vp[3 * (size_t)S] = (bf16_t)(w.y >> 16);
;                             vp[4 * (size_t)S] = (bf16_t)(w.z & 0xffffu); vp[5 * (size_t)S] = (bf16_t)(w.z >> 16); vp[6 * (size_t)S] = (bf16_t)(w.w & 0xffffu); vp[7 * (size_t)S] = (bf16_t)(w.w >> 16);
.LBB0_459:
	v_lshlrev_b64 v[28:29], 15, v[128:129]
	v_lshl_add_u64 v[28:29], s[6:7], 0, v[28:29]
	v_lshl_add_u64 v[28:29], v[220:221], 1, v[28:29]
	v_add_co_u32_e32 v30, vcc, 0x8000, v28
	global_store_short v[28:29], v24, off offset:320
	s_nop 0
	v_addc_co_u32_e32 v31, vcc, 0, v29, vcc
	global_store_short_d16_hi v[30:31], v24, off offset:320
	v_add_co_u32_e32 v30, vcc, 0x10000, v28
	s_nop 1
	v_addc_co_u32_e32 v31, vcc, 0, v29, vcc
	global_store_short v[30:31], v25, off offset:320
	v_add_co_u32_e32 v30, vcc, 0x18000, v28
	s_nop 1
	v_addc_co_u32_e32 v31, vcc, 0, v29, vcc
	v_add_co_u32_e32 v24, vcc, 0x20000, v28
	global_store_short_d16_hi v[30:31], v25, off offset:320
	s_nop 0
	v_addc_co_u32_e32 v25, vcc, 0, v29, vcc
	global_store_short v[24:25], v26, off offset:320
	v_add_co_u32_e32 v24, vcc, 0x28000, v28
	s_nop 1
	v_addc_co_u32_e32 v25, vcc, 0, v29, vcc
	global_store_short_d16_hi v[24:25], v26, off offset:320
	v_add_co_u32_e32 v24, vcc, 0x30000, v28
	s_nop 1
	v_addc_co_u32_e32 v25, vcc, 0, v29, vcc
	global_store_short v[24:25], v27, off offset:320
	v_add_co_u32_e32 v24, vcc, 0x38000, v28
	s_nop 1
	v_addc_co_u32_e32 v25, vcc, 0, v29, vcc
	global_store_short_d16_hi v[24:25], v27, off offset:320
	v_mov_b32_e32 v39, v38
	s_cmp_lt_i32 s57, 10
	s_cbranch_scc0 .LBB0_457

;     __device__ __forceinline__ void operator()(const pg8::f32x4 (&acc)[2][2][4][2], const pg8::Unit& u, int wr, int wc, int fr, int fq) const {
;     ...
;                         if (vt_all || (vt_half && bj == 1)) {
;                             bf16_t* vp = vt + (size_t)(vrow0 + bj * 128) * S + row;
;                             vp[0 * (size_t)S] = (bf16_t)(w.x & 0xffffu); vp[1 * (size_t)S] = (bf16_t)(w.x >> 16); vp[2 * (size_t)S] = (bf16_t)(w.y & 0xffffu); vp[3 * (size_t)S] = (bf16_t)(w.y >> 16);
;                             vp[4 * (size_t)S] = (bf16_t)(w.z & 0xffffu); vp[5 * (size_t)S] = (bf16_t)(w.z >> 16); vp[6 * (size_t)S] = (bf16_t)(w.w & 0xffffu); vp[7 * (size_t)S] = (bf16_t)(w.w >> 16);
.LBB0_465:
	s_and_b64 vcc, exec, s[0:1]
	s_cbranch_vccz .LBB0_467
	v_lshlrev_b64 v[20:21], 15, v[128:129]
	v_lshl_add_u64 v[20:21], s[6:7], 0, v[20:21]
	v_lshl_add_u64 v[20:21], v[220:221], 1, v[20:21]
	v_add_co_u32_e32 v22, vcc, 0x400000, v20
	s_nop 1
	v_addc_co_u32_e32 v23, vcc, 0, v21, vcc
	global_store_short v[22:23], v16, off offset:320
	v_add_co_u32_e32 v22, vcc, 0x408000, v20
	s_nop 1
	v_addc_co_u32_e32 v23, vcc, 0, v21, vcc
	global_store_short_d16_hi v[22:23], v16, off offset:320
	v_add_co_u32_e32 v22, vcc, 0x410000, v20
	s_nop 1
	v_addc_co_u32_e32 v23, vcc, 0, v21, vcc
	global_store_short v[22:23], v17, off offset:320
	v_add_co_u32_e32 v22, vcc, 0x418000, v20
	s_nop 1
	v_addc_co_u32_e32 v23, vcc, 0, v21, vcc
	v_add_co_u32_e32 v16, vcc, 0x420000, v20
	global_store_short_d16_hi v[22:23], v17, off offset:320
	s_nop 0
	v_addc_co_u32_e32 v17, vcc, 0, v21, vcc
	global_store_short v[16:17], v18, off offset:320
	v_add_co_u32_e32 v16, vcc, 0x428000, v20
	s_nop 1
	v_addc_co_u32_e32 v17, vcc, 0, v21, vcc
	global_store_short_d16_hi v[16:17], v18, off offset:320
	v_add_co_u32_e32 v16, vcc, 0x430000, v20
	s_nop 1
	v_addc_co_u32_e32 v17, vcc, 0, v21, vcc
	global_store_short v[16:17], v19, off offset:320
	v_add_co_u32_e32 v16, vcc, 0x438000, v20
	s_nop 1
	v_addc_co_u32_e32 v17, vcc, 0, v21, vcc
	global_store_short_d16_hi v[16:17], v19, off offset:320

;     __device__ __forceinline__ void operator()(const pg8::f32x4 (&acc)[2][2][4][2], const pg8::Unit& u, int wr, int wc, int fr, int fq) const {
;     ...
;                         if (vt_all || (vt_half && bj == 1)) {
;                             bf16_t* vp = vt + (size_t)(vrow0 + bj * 128) * S + row;
;                             vp[0 * (size_t)S] = (bf16_t)(w.x & 0xffffu); vp[1 * (size_t)S] = (bf16_t)(w.x >> 16); vp[2 * (size_t)S] = (bf16_t)(w.y & 0xffffu); vp[3 * (size_t)S] = (bf16_t)(w.y >> 16);
;                             vp[4 * (size_t)S] = (bf16_t)(w.z & 0xffffu); vp[5 * (size_t)S] = (bf16_t)(w.z >> 16); vp[6 * (size_t)S] = (bf16_t)(w.w & 0xffffu); vp[7 * (size_t)S] = (bf16_t)(w.w >> 16);
.LBB0_476:
	v_lshlrev_b64 v[12:13], 15, v[128:129]
	v_lshl_add_u64 v[12:13], s[6:7], 0, v[12:13]
	v_lshl_add_u64 v[12:13], v[220:221], 1, v[12:13]
	v_add_co_u32_e32 v14, vcc, 0x8000, v12
	global_store_short v[12:13], v8, off offset:352
	s_nop 0
	v_addc_co_u32_e32 v15, vcc, 0, v13, vcc
	global_store_short_d16_hi v[14:15], v8, off offset:352
	v_add_co_u32_e32 v14, vcc, 0x10000, v12
	s_nop 1
	v_addc_co_u32_e32 v15, vcc, 0, v13, vcc
	global_store_short v[14:15], v9, off offset:352
	v_add_co_u32_e32 v14, vcc, 0x18000, v12
	s_nop 1
	v_addc_co_u32_e32 v15, vcc, 0, v13, vcc
	v_add_co_u32_e32 v8, vcc, 0x20000, v12
	global_store_short_d16_hi v[14:15], v9, off offset:352
	s_nop 0
	v_addc_co_u32_e32 v9, vcc, 0, v13, vcc
	global_store_short v[8:9], v10, off offset:352
	v_add_co_u32_e32 v8, vcc, 0x28000, v12
	s_nop 1
	v_addc_co_u32_e32 v9, vcc, 0, v13, vcc
	global_store_short_d16_hi v[8:9], v10, off offset:352
	v_add_co_u32_e32 v8, vcc, 0x30000, v12
	s_nop 1
	v_addc_co_u32_e32 v9, vcc, 0, v13, vcc
	global_store_short v[8:9], v11, off offset:352
	v_add_co_u32_e32 v8, vcc, 0x38000, v12
	s_nop 1
	v_addc_co_u32_e32 v9, vcc, 0, v13, vcc
	global_store_short_d16_hi v[8:9], v11, off offset:352
	v_mov_b32_e32 v19, v18
	s_cmp_lt_i32 s57, 10
	s_cbranch_scc0 .LBB0_474

;     __device__ __forceinline__ void operator()(const pg8::f32x4 (&acc)[2][2][4][2], const pg8::Unit& u, int wr, int wc, int fr, int fq) const {
;     ...
;                         if (vt_all || (vt_half && bj == 1)) {
;                             bf16_t* vp = vt + (size_t)(vrow0 + bj * 128) * S + row;
;                             vp[0 * (size_t)S] = (bf16_t)(w.x & 0xffffu); vp[1 * (size_t)S] = (bf16_t)(w.x >> 16); vp[2 * (size_t)S] = (bf16_t)(w.y & 0xffffu); vp[3 * (size_t)S] = (bf16_t)(w.y >> 16);
;                             vp[4 * (size_t)S] = (bf16_t)(w.z & 0xffffu); vp[5 * (size_t)S] = (bf16_t)(w.z >> 16); vp[6 * (size_t)S] = (bf16_t)(w.w & 0xffffu); vp[7 * (size_t)S] = (bf16_t)(w.w >> 16);
.LBB0_483:
	s_and_b64 vcc, exec, s[0:1]
	s_cbranch_vccz .LBB0_485
	v_lshlrev_b64 v[4:5], 15, v[128:129]
	v_lshl_add_u64 v[4:5], s[6:7], 0, v[4:5]
	v_lshl_add_u64 v[4:5], v[220:221], 1, v[4:5]
	v_add_co_u32_e32 v6, vcc, 0x400000, v4
	s_nop 1
	v_addc_co_u32_e32 v7, vcc, 0, v5, vcc
	global_store_short v[6:7], v0, off offset:352
	v_add_co_u32_e32 v6, vcc, 0x408000, v4
	s_nop 1
	v_addc_co_u32_e32 v7, vcc, 0, v5, vcc
	global_store_short_d16_hi v[6:7], v0, off offset:352
	v_add_co_u32_e32 v6, vcc, 0x410000, v4
	s_nop 1
	v_addc_co_u32_e32 v7, vcc, 0, v5, vcc
	global_store_short v[6:7], v1, off offset:352
	v_add_co_u32_e32 v6, vcc, 0x418000, v4
	s_nop 1
	v_addc_co_u32_e32 v7, vcc, 0, v5, vcc
	v_add_co_u32_e32 v0, vcc, 0x420000, v4
	global_store_short_d16_hi v[6:7], v1, off offset:352
	s_nop 0
	v_addc_co_u32_e32 v1, vcc, 0, v5, vcc
	global_store_short v[0:1], v2, off offset:352
	v_add_co_u32_e32 v0, vcc, 0x428000, v4
	s_nop 1
	v_addc_co_u32_e32 v1, vcc, 0, v5, vcc
	global_store_short_d16_hi v[0:1], v2, off offset:352
	v_add_co_u32_e32 v0, vcc, 0x430000, v4
	s_nop 1
	v_addc_co_u32_e32 v1, vcc, 0, v5, vcc
	global_store_short v[0:1], v3, off offset:352
	v_add_co_u32_e32 v0, vcc, 0x438000, v4
	s_nop 1
	v_addc_co_u32_e32 v1, vcc, 0, v5, vcc
	global_store_short_d16_hi v[0:1], v3, off offset:352

; template <int MODE, bool FROZEN = false>
; __device__ __forceinline__ bool attn_unit(LAS unsigned char* lds, const Params& p, int l, int ua, int ub) {
;     ...
;         const int g = ua, qb = ub, hq = g * 4 + (wid >> 1); qtok0 = qb * 64 + (wid & 1) * 32; lut_sel = wid >> 1;
;         qcol = 3072 + hq * 64; kcol = 3584 + g * 64; vcol = 1024 + g * 64; ocol = hq * 64;
;         const int tlo = max(qb - 2, 0), thi = min(qb + 2, S / 64 - 1); kt0 = tlo * 64; NT = thi - tlo + 1; wt_hi = NT;
;         for (int i = tid; i < 4 * 449; i += 512) { const int hh = i / 449, rel = i % 449 - 224; lut[i] = (rel >= -128 && rel <= 128) ? p.rel_bias[t5_bucket(rel) * 12 + 4 + g * 4 + hh] * LOG2E : NEGBIG; }
;         m_run = p.gqa_sink[l * 8 + hq] * LOG2E; l_run = (hi == 0) ? 1.0f : 0.0f;
;     }
;     bf16x8 qf[4];
;     { const bf16_t* qp = proj + (size_t)(qtok0 + r32) * NPROJ + qcol + 8 * hi;
; #pragma unroll
;       for (int d0 = 0; d0 < 4; ++d0) qf[d0] = *(const bf16x8*)(qp + 16 * d0); }
;     f32x16 o[NB];
; #pragma unroll
;     for (int nb = 0; nb < NB; ++nb)
; #pragma unroll
;         for (int r = 0; r < 16; ++r) o[nb][r] = 0.f;
;     u32x4 kr[NKC], vr[NVC];
;     unsigned ksrc[NKC], vsrc[NVC]; int kdst[NKC], vdst[NVC];
;     const bf16_t* kvbase = proj + (size_t)kt0 * NPROJ;
; #pragma unroll
;     for (int i = 0; i < NKC; ++i) { const int cid = tid + 512 * i, row = cid / KCH, ch = cid % KCH; ksrc[i] = (unsigned)(row * NPROJ + kcol + ch * 8); kdst[i] = OFF_K + row * KPB + ch * 16; }
; #pragma unroll
;     for (int i = 0; i < NVC; ++i) { const int cid = tid + 512 * i, row = cid >> 3, ch = cid & 7; vsrc[i] = (unsigned)((vcol + row) * S + ch * 8); vdst[i] = OFF_V + row * VTP + (ch >> 1) * 32 + (ch & 1) * 8; }
;     const bf16_t* vtbase = vtg + kt0;
;     {
;         u32x4 k1[NKC];
; #pragma unroll
;         for (int i = 0; i < NKC; ++i) { kr[i] = *(const u32x4*)(kvbase + ksrc[i]); k1[i] = *(const u32x4*)(kvbase + (size_t)64 * NPROJ + ksrc[i]); }
; #pragma unroll
;         for (int i = 0; i < NVC; ++i) vr[i] = *(const u32x4*)(vtbase + vsrc[i]);
; #pragma unroll
;         for (int i = 0; i < NKC; ++i) { *(LAS u32x4*)(lds + kdst[i]) = kr[i]; *(LAS u32x4*)(lds + kdst[i] + KBUF) = k1[i]; }
; #pragma unroll
;         for (int i = 0; i < NVC; ++i) { *(LAS u32x2*)(lds + vdst[i]) = (u32x2){vr[i].x, vr[i].y}; *(LAS u32x2*)(lds + vdst[i] + 16) = (u32x2){vr[i].z, vr[i].w}; }
; #pragma unroll
.LBB0_503:
	s_or_b64 exec, exec, s[0:1]
	s_ashr_i32 s10, s20, 1
	s_lshr_b32 s4, s21, 1
	s_lshl_b32 s1, s10, 6
	s_and_b32 s4, s4, 32
	s_max_i32 s11, s10, 2
	s_ashr_i32 s12, s21, 7
	s_or_b32 s5, s4, s1
	s_lshl_b32 s1, s11, 6
	s_add_i32 s0, s12, s8
	s_add_i32 s8, s1, 0xffffff80
	v_readlane_b32 s1, v255, 13
	s_lshl_b32 s4, s0, 6
	s_add_i32 s0, s0, s1
	s_min_i32 s13, s10, 0xfd
	s_ashr_i32 s1, s0, 31
	v_readlane_b32 s40, v254, 57
	s_lshl_b32 s14, s22, 6
	s_sub_i32 s13, s13, s11
	s_lshl_b64 s[0:1], s[0:1], 2
	v_readlane_b32 s52, v255, 5
	v_readlane_b32 s53, v255, 6
	s_add_u32 s0, s52, s0
	v_and_b32_e32 v92, 31, v2
	s_addc_u32 s1, s53, s1
	global_load_dword v36, v197, s[0:1]
	v_or_b32_e32 v32, s5, v92
	v_mov_b64_e32 v[0:1], s[34:35]
	s_movk_i32 s0, 0x1e00
	v_bfe_u32 v35, v2, 5, 1
	v_mad_i64_i32 v[0:1], s[0:1], v32, s0, v[0:1]
	s_ashr_i32 s5, s4, 31
	v_lshl_add_u64 v[0:1], s[4:5], 1, v[0:1]
	v_lshlrev_b32_e32 v196, 4, v35
	v_lshl_add_u64 v[0:1], v[0:1], 0, v[196:197]
	s_mov_b64 s[0:1], 0x1800
	v_lshl_add_u64 v[4:5], v[0:1], 0, s[0:1]
	s_movk_i32 s0, 0x1000
	v_add_co_u32_e64 v0, s[0:1], s0, v0
	s_movk_i32 s15, 0xf00
	s_nop 0
	v_addc_co_u32_e64 v1, s[0:1], 0, v1, s[0:1]
	global_load_dwordx4 v[68:71], v[0:1], off offset:2048
	global_load_dwordx4 v[72:75], v[4:5], off offset:32
	global_load_dwordx4 v[76:79], v[4:5], off offset:64
	global_load_dwordx4 v[80:83], v[4:5], off offset:96
	v_ashrrev_i32_e32 v0, 31, v2
	v_lshrrev_b32_e32 v0, 29, v0
	v_add_u32_e32 v0, v2, v0
	v_ashrrev_i32_e32 v1, 3, v0
	v_and_b32_e32 v0, -8, v0
	v_sub_u32_e32 v3, v2, v0
	v_mul_lo_u32 v0, v1, s15
	s_movk_i32 s16, 0x90
	v_or_b32_e32 v0, s14, v0
	v_lshlrev_b32_e32 v4, 3, v3
	s_movk_i32 s15, 0xe00
	v_mul_lo_u32 v12, v1, s16
	v_ashrrev_i32_e32 v1, 3, v2
	s_mul_i32 s0, s8, 0x1e00
	v_add3_u32 v0, v0, v4, s15
	v_add_u32_e32 v4, s14, v1
	v_mul_lo_u32 v14, v1, s16
	v_lshlrev_b32_e32 v1, 4, v2
	s_mul_hi_u32 s1, s8, 0x1e00
	s_add_u32 s0, s34, s0
	v_and_b32_e32 v15, 0x60, v1
	v_lshlrev_b32_e32 v1, 3, v2
	s_addc_u32 s1, s35, s1
	v_lshlrev_b32_e32 v13, 4, v3
	v_and_b32_e32 v3, 7, v2
	v_lshlrev_b32_e32 v16, 4, v2
	v_and_b32_e32 v16, 16, v16
	v_mov_b32_e32 v1, v197
	v_lshlrev_b32_e32 v3, 3, v3
	v_lshl_add_u64 v[108:109], v[0:1], 1, s[0:1]
	s_mov_b32 s0, 0x78000
	v_lshl_or_b32 v3, v4, 14, v3
	s_lshl_b64 s[14:15], s[8:9], 1
	v_add_co_u32_e64 v4, s[0:1], s0, v108
	v_add_u32_e32 v8, 0x1000000, v3
	s_add_u32 s14, s6, s14
	global_load_dwordx4 v[0:3], v[108:109], off
	v_addc_co_u32_e64 v5, s[0:1], 0, v109, s[0:1]
	s_addc_u32 s15, s7, s15
	global_load_dwordx4 v[4:7], v[4:5], off
	v_mov_b32_e32 v9, v197
	v_lshl_add_u64 v[110:111], v[8:9], 1, s[14:15]
	global_load_dwordx4 v[8:11], v[110:111], off
	v_add3_u32 v33, 0, v12, v13
	s_mov_b32 s0, 0xf0000
	v_add_u32_e32 v37, 0, v196
	v_mad_u32_u24 v145, v92, s16, v37
	v_cmp_eq_u32_e32 vcc, 0, v35
	v_readlane_b32 s41, v254, 58
	v_readlane_b32 s42, v254, 59
	v_readlane_b32 s43, v254, 60
	v_readlane_b32 s44, v254, 61
	v_readlane_b32 s45, v254, 62
	v_readlane_b32 s46, v254, 63
	v_readlane_b32 s47, v255, 0
	v_readlane_b32 s48, v255, 1
	v_readlane_b32 s49, v255, 2
	v_readlane_b32 s50, v255, 3
	v_readlane_b32 s51, v255, 4
	s_waitcnt vmcnt(7)
	v_mul_f32_e32 v93, 0x3fb8aa3b, v36
	v_readlane_b32 s54, v255, 7
	v_readlane_b32 s55, v255, 8
	s_waitcnt vmcnt(2)
	ds_write_b128 v33, v[0:3]
	s_waitcnt vmcnt(1)
	ds_write_b128 v33, v[4:7] offset:9216
	v_add_u32_e32 v0, 0, v14
	v_add3_u32 v144, v0, v16, v15
	v_add_u32_e32 v0, 0x4800, v144
	s_waitcnt vmcnt(0)
	ds_write_b128 v0, v[8:11]
	v_add_co_u32_e64 v0, s[0:1], s0, v108
	s_nop 1
	v_addc_co_u32_e64 v1, s[0:1], 0, v109, s[0:1]
	global_load_dwordx4 v[88:91], v[0:1], off
	global_load_dwordx4 v[84:87], v[110:111], off offset:128
	s_waitcnt lgkmcnt(0)
	s_barrier
; #define ATT_MAX3(dst) do { float tm_ = max3f(sB0[0], sB1[0], sB0[1]), tn_ = max3f(sB1[1], sB0[2], sB1[2]); \
;         _Pragma("unroll") for (int r = 3; r < 15; r += 2) { tm_ = max3f(tm_, sB0[r], sB1[r]); tn_ = max3f(tn_, sB0[r + 1], sB1[r + 1]); } \
;         tm_ = max3f(tm_, sB0[15], sB1[15]); dst = max3f(tm_, tn_, tn_); } while (0)
; template <int MODE, bool FROZEN = false>
; __device__ __forceinline__ bool attn_unit(LAS unsigned char* lds, const Params& p, int l, int ua, int ub) {
;     ...
;     float cb_pos = 0.f, cb_neg = 0.f;
;     if constexpr (MODE == 1) { cb_pos = lut[448]; cb_neg = lut[0]; }
;     ATT_QK(0);
;     if constexpr (FROZEN) m_run = cb_neg;
;     { float tm0 = 0.f; if constexpr (!FROZEN) ATT_MAX3(tm0); ATT_BIAS(0, tm0); ATT_UPD(tm0); }
;     __syncthreads();
	ds_read_b128 v[0:3], v145 offset:4608
	ds_read_b128 v[4:7], v145
	ds_read_b128 v[38:41], v145 offset:32
	s_waitcnt lgkmcnt(1)
	v_mfma_f32_32x32x16_bf16 v[16:31], v[4:7], v[68:71], 0
	ds_read_b128 v[42:45], v145 offset:4640
	s_mul_i32 s0, s12, 0x704
	v_mfma_f32_32x32x16_bf16 v[0:15], v[0:3], v[68:71], 0
	s_waitcnt lgkmcnt(1)
	v_mfma_f32_32x32x16_bf16 v[16:31], v[38:41], v[72:75], v[16:31]
	s_waitcnt lgkmcnt(0)
	v_mfma_f32_32x32x16_bf16 v[0:15], v[42:45], v[72:75], v[0:15]
	ds_read_b128 v[38:41], v145 offset:64
	ds_read_b128 v[42:45], v145 offset:4672
	s_waitcnt lgkmcnt(1)
	v_mfma_f32_32x32x16_bf16 v[16:31], v[38:41], v[76:79], v[16:31]
	s_waitcnt lgkmcnt(0)
	v_mfma_f32_32x32x16_bf16 v[0:15], v[42:45], v[76:79], v[0:15]
	ds_read_b128 v[38:41], v145 offset:96
	ds_read_b128 v[42:45], v145 offset:4704
	s_waitcnt lgkmcnt(1)
	v_mfma_f32_32x32x16_bf16 v[16:31], v[38:41], v[80:83], v[16:31]
	v_sub_u32_e32 v38, s8, v32
	v_lshlrev_b32_e32 v38, 2, v38
	v_add3_u32 v37, v37, v38, s0
	v_add_u32_e32 v38, 0x9380, v37
	ds_read2_b32 v[38:39], v38 offset1:1
	s_waitcnt lgkmcnt(0)
	v_pk_add_f32 v[38:39], v[38:39], 0 op_sel_hi:[1,0]
	s_nop 4
	v_pk_add_f32 v[16:17], v[16:17], v[38:39]
	v_add_u32_e32 v38, 0x9388, v37
	ds_read2_b32 v[38:39], v38 offset1:1
	v_mfma_f32_32x32x16_bf16 v[0:15], v[42:45], v[80:83], v[0:15]
	s_waitcnt lgkmcnt(0)
	v_add_f32_e64 v38, v38, 0
	v_add_f32_e64 v39, v39, 0
	v_add_f32_e64 v18, v18, v38
	v_add_f32_e64 v19, v19, v39
	v_add_u32_e32 v38, 0x93a0, v37
	ds_read2_b32 v[38:39], v38 offset1:1
	s_waitcnt lgkmcnt(0)
	v_pk_add_f32 v[38:39], v[38:39], 0 op_sel_hi:[1,0]
	s_nop 0
	v_pk_add_f32 v[20:21], v[20:21], v[38:39]
	v_add_u32_e32 v38, 0x93a8, v37
	ds_read2_b32 v[38:39], v38 offset1:1
	s_waitcnt lgkmcnt(0)
	v_pk_add_f32 v[38:39], v[38:39], 0 op_sel_hi:[1,0]
	s_nop 0
	v_pk_add_f32 v[22:23], v[22:23], v[38:39]
	v_add_u32_e32 v38, 0x93c0, v37
	ds_read2_b32 v[38:39], v38 offset1:1
	s_waitcnt lgkmcnt(0)
	v_pk_add_f32 v[38:39], v[38:39], 0 op_sel_hi:[1,0]
	s_nop 0
	v_pk_add_f32 v[24:25], v[24:25], v[38:39]
	v_add_u32_e32 v38, 0x93c8, v37
	ds_read2_b32 v[38:39], v38 offset1:1
	s_waitcnt lgkmcnt(0)
	v_pk_add_f32 v[38:39], v[38:39], 0 op_sel_hi:[1,0]
	s_nop 0
	v_pk_add_f32 v[26:27], v[26:27], v[38:39]
	v_add_u32_e32 v38, 0x93e0, v37
	ds_read2_b32 v[38:39], v38 offset1:1
	s_waitcnt lgkmcnt(0)
	v_pk_add_f32 v[38:39], v[38:39], 0 op_sel_hi:[1,0]
	s_nop 0
	v_pk_add_f32 v[28:29], v[28:29], v[38:39]
	v_add_u32_e32 v38, 0x93e8, v37
	ds_read2_b32 v[38:39], v38 offset1:1
	s_waitcnt lgkmcnt(0)
	v_pk_add_f32 v[38:39], v[38:39], 0 op_sel_hi:[1,0]
	s_nop 0
	v_pk_add_f32 v[30:31], v[30:31], v[38:39]
	v_add_u32_e32 v38, 0x9400, v37
	ds_read2_b32 v[38:39], v38 offset1:1
	s_waitcnt lgkmcnt(0)
	v_pk_add_f32 v[38:39], v[38:39], 0 op_sel_hi:[1,0]
	s_nop 0
	v_pk_add_f32 v[0:1], v[0:1], v[38:39]
	v_add_u32_e32 v38, 0x9408, v37
	ds_read2_b32 v[38:39], v38 offset1:1
	s_waitcnt lgkmcnt(0)
	v_pk_add_f32 v[38:39], v[38:39], 0 op_sel_hi:[1,0]
	s_nop 0
	v_pk_add_f32 v[2:3], v[2:3], v[38:39]
	v_add_u32_e32 v38, 0x9420, v37
	ds_read2_b32 v[38:39], v38 offset1:1
	s_waitcnt lgkmcnt(0)
	v_pk_add_f32 v[38:39], v[38:39], 0 op_sel_hi:[1,0]
	s_nop 0
	v_pk_add_f32 v[4:5], v[4:5], v[38:39]
	v_add_u32_e32 v38, 0x9428, v37
	ds_read2_b32 v[38:39], v38 offset1:1
	s_waitcnt lgkmcnt(0)
	v_pk_add_f32 v[38:39], v[38:39], 0 op_sel_hi:[1,0]
	s_nop 0
	v_pk_add_f32 v[6:7], v[6:7], v[38:39]
	v_add_u32_e32 v38, 0x9440, v37
	ds_read2_b32 v[38:39], v38 offset1:1
	s_waitcnt lgkmcnt(0)
	v_pk_add_f32 v[38:39], v[38:39], 0 op_sel_hi:[1,0]
	s_nop 0
	v_pk_add_f32 v[8:9], v[8:9], v[38:39]
	v_add_u32_e32 v38, 0x9448, v37
	ds_read2_b32 v[38:39], v38 offset1:1
	s_waitcnt lgkmcnt(0)
	v_pk_add_f32 v[38:39], v[38:39], 0 op_sel_hi:[1,0]
	s_nop 0
	v_pk_add_f32 v[10:11], v[10:11], v[38:39]
	v_add_u32_e32 v38, 0x9460, v37
	ds_read2_b32 v[38:39], v38 offset1:1
	v_add_u32_e32 v37, 0x9468, v37
	s_waitcnt lgkmcnt(0)
	v_pk_add_f32 v[38:39], v[38:39], 0 op_sel_hi:[1,0]
	s_nop 0
	v_pk_add_f32 v[12:13], v[12:13], v[38:39]
	ds_read2_b32 v[38:39], v37 offset1:1
	s_waitcnt lgkmcnt(0)
	v_pk_add_f32 v[38:39], v[38:39], 0 op_sel_hi:[1,0]
	s_nop 0
	v_pk_add_f32 v[14:15], v[14:15], v[38:39]
	v_max_f32_e32 v37, v16, v0
	v_max3_f32 v38, v1, v18, v2
	v_max3_f32 v37, v37, v17, v19
	v_max3_f32 v38, v38, v20, v4
	v_max3_f32 v37, v37, v3, v21
	v_max3_f32 v38, v38, v22, v6
	v_max3_f32 v37, v37, v5, v23
	v_max3_f32 v38, v38, v24, v8
	v_max3_f32 v37, v37, v7, v25
	v_max3_f32 v38, v38, v26, v10
	v_max3_f32 v37, v37, v9, v27
	v_max3_f32 v38, v38, v28, v12
	v_max3_f32 v37, v37, v11, v29
	v_max3_f32 v38, v38, v30, v14
	v_max3_f32 v37, v37, v13, v31
	v_max3_f32 v37, v37, v15, v38
	v_mov_b32_e32 v38, v37
	s_nop 1
	v_permlane32_swap_b32_e32 v37, v38
	v_max_f32_e32 v38, v38, v38
	v_max_f32_e32 v37, v37, v37
	v_max_f32_e32 v37, v37, v38
	v_add_f32_e32 v38, 0, v37
	v_max_f32_e32 v94, v93, v38
	s_mov_b32 s8, 0x3fb8aa3b
	v_fma_f32 v36, v36, s8, -v94
	v_exp_f32_e32 v95, v36
	v_cndmask_b32_e64 v96, 0, 1.0, vcc
	v_cmp_gt_f32_e32 vcc, v37, v93
	s_cmp_eq_u64 vcc, 0
	v_mul_f32_e32 v36, 0, v95
	s_cselect_b64 vcc, -1, 0
	v_cndmask_b32_e64 v52, v36, 0, vcc
	v_cndmask_b32_e64 v95, v95, 1.0, vcc
	v_mov_b32_e32 v53, v52
	v_mov_b32_e32 v54, v52
	v_mov_b32_e32 v55, v52
	v_mov_b32_e32 v56, v52
	v_mov_b32_e32 v57, v52
	v_mov_b32_e32 v58, v52
	v_mov_b32_e32 v59, v52
	v_mov_b32_e32 v60, v52
	v_mov_b32_e32 v61, v52
	v_mov_b32_e32 v62, v52
	v_mov_b32_e32 v63, v52
	v_mov_b32_e32 v64, v52
	v_mov_b32_e32 v65, v52
	v_mov_b32_e32 v66, v52
	v_mov_b32_e32 v67, v52
	v_mov_b32_e32 v36, v52
	v_mov_b32_e32 v37, v52
	v_mov_b32_e32 v38, v52
	v_mov_b32_e32 v39, v52
	v_mov_b32_e32 v40, v52
	v_mov_b32_e32 v41, v52
	v_mov_b32_e32 v42, v52
	v_mov_b32_e32 v43, v52
	v_mov_b32_e32 v44, v52
	v_mov_b32_e32 v45, v52
	v_mov_b32_e32 v46, v52
	v_mov_b32_e32 v47, v52
	v_mov_b32_e32 v48, v52
	v_mov_b32_e32 v49, v52
	v_mov_b32_e32 v50, v52
	v_mov_b32_e32 v51, v52
	v_mul_f32_e32 v146, v96, v95
	s_cmp_gt_i32 s13, -5
	s_barrier
	s_cbranch_scc0 .LBB0_489
	s_lshl_b32 s1, s11, 8
	s_add_i32 s0, s0, s1
	v_mul_u32_u24_e32 v95, 0x90, v92
	v_cndmask_b32_e32 v149, v94, v93, vcc
	v_add_u32_e32 v93, s0, v196
	v_lshlrev_b32_e32 v92, 2, v92
	s_lshl_b32 s0, s21, 1
	v_sub_u32_e32 v92, v93, v92
	s_and_b32 s0, s0, 0x80
	v_subrev_u32_e32 v92, s0, v92
	s_lshl_b32 s0, s10, 8
	v_subrev_u32_e32 v92, s0, v92
	v_readlane_b32 s0, v254, 49
	v_add3_u32 v147, 0, v95, v196
	s_add_i32 s12, s13, 4
	s_add_i32 s13, s13, 5
	v_add_u32_e32 v148, s0, v92
	s_mov_b32 s15, 0
	s_add_i32 s8, s15, 2
	s_cmp_gt_i32 s8, s12
	s_cbranch_scc1 .LBB0_506

; #define LAS __attribute__((address_space(3)))
; template <int MODE, bool FROZEN = false>
; __device__ __forceinline__ bool attn_unit(LAS unsigned char* lds, const Params& p, int l, int ua, int ub) {
;     ...
;         if (t + 1 < NT) {
; #pragma unroll
;             for (int i = 0; i < NVC; ++i) { *(LAS u32x2*)(lds + vdst[i] + ((t + 1) & 1) * VBUF) = (u32x2){vr[i].x, vr[i].y}; *(LAS u32x2*)(lds + vdst[i] + ((t + 1) & 1) * VBUF + 16) = (u32x2){vr[i].z, vr[i].w}; }
;         }
.LBB0_508:
	s_andn2_b64 vcc, exec, s[10:11]
	s_cbranch_vccnz .LBB0_510
	s_bitcmp1_b32 s14, 0
	s_cselect_b32 s16, 0x2400, 0
	s_waitcnt vmcnt(1)
	v_add_u32_e32 v88, s16, v144
	v_add_u32_e32 v88, 0x4800, v88
	s_waitcnt vmcnt(0)
	ds_write_b128 v88, v[84:87]
